# A/B: per-phase s_setprio 1/0 flips deleted from all eight GEMM K-loops (128 instructions), on top of v9
# speedup vs baseline: 1.0138x; 1.0138x over previous
; #define PG8_STAGE(bufoff, gbase, voff) do { _Pragma("unroll") for (int _i = 0; _i < 2; ++_i) \
;     __builtin_amdgcn_global_load_lds((const unsigned*)((const char*)(gbase) + (voff)[_i]), (LAS unsigned*)(lds + (bufoff) + ldsw + _i * 8192), 16, 0, 0); } while (0)
; #define PG8_LDA(dst, b, h) do { _Pragma("unroll") for (int m = 0; m < 4; ++m) _Pragma("unroll") for (int k = 0; k < 2; ++k) dst[m][k] = *(const LAS bf16x8*)(lds + PG8_SA(b, h) + aoff + m * 2048 + k * 1024); } while (0)
; #define PG8_LDB(dst, b, h) do { _Pragma("unroll") for (int n = 0; n < 2; ++n) _Pragma("unroll") for (int k = 0; k < 2; ++k) dst[n][k] = *(const LAS bf16x8*)(lds + PG8_SB(b, h) + boff + n * 2048 + k * 1024); } while (0)
; #define PG8_MMA(ai, bj, At, Bt) do { __builtin_amdgcn_s_setprio(1); _Pragma("unroll") for (int m = 0; m < 4; ++m) _Pragma("unroll") for (int n = 0; n < 2; ++n) _Pragma("unroll") for (int k = 0; k < 2; ++k) \
;     acc[ai][bj][m][n] = __builtin_amdgcn_mfma_f32_16x16x32_bf16(Bt[n][k], At[m][k], acc[ai][bj][m][n], 0, 0, 0); __builtin_amdgcn_s_setprio(0); } while (0)
; #define PG8_WAIT_V(n) asm volatile("s_waitcnt vmcnt(" #n ")" ::: "memory")
; #define PG8_WAIT_L(n) asm volatile("s_waitcnt lgkmcnt(" #n ")" ::: "memory")
; #define PG8_BAR __builtin_amdgcn_s_barrier()
; #define PG8_SCHED __builtin_amdgcn_sched_barrier(0)
; template <class Epi>
; DI void gemm_phase(LAS unsigned char* lds, const Gemm g, const StaticOrder& S, const Epi& E) {
;     ...
;       PG8_LDB(B0, 0, 0); PG8_SCHED; PG8_LDA(At, 0, 0); PG8_STAGE(PG8_SA(1, 1), a1 + hstepA, voffA);
;       PG8_WAIT_L(8); PG8_BAR; PG8_WAIT_L(0); PG8_MMA(0, 0, At, B0); PG8_BAR; PG8_SCHED;
;       PG8_LDB(B1, 0, 1); PG8_STAGE(PG8_SB(0, 0), b2, voffB);
;       PG8_BAR; PG8_WAIT_L(0); PG8_MMA(0, 1, At, B1); PG8_BAR;
;       PG8_LDA(At, 0, 1); PG8_STAGE(PG8_SA(0, 0), a2, voffA);
;       PG8_BAR; PG8_WAIT_L(0); PG8_MMA(1, 0, At, B0); PG8_BAR; PG8_SCHED;
;       PG8_STAGE(PG8_SB(0, 1), b2 + hstepB, voffB);
;       PG8_WAIT_V(6); PG8_BAR; PG8_MMA(1, 1, At, B1); PG8_BAR;
.LBB0_184:
	ds_read_b128 v[150:153], v166
	ds_read_b128 v[154:157], v166 offset:1024
	ds_read_b128 v[158:161], v166 offset:2048
	ds_read_b128 v[170:173], v166 offset:3072
	s_add_u32 s30, s6, 0xfff80080
	s_addc_u32 s31, s7, -1
	s_cmp_eq_u32 s39, 28
	s_cselect_b32 s35, s5, s31
	s_cselect_b32 s34, s8, s30
	s_cselect_b32 s31, s23, s38
	s_cselect_b32 s30, s25, s37
	v_lshl_add_u64 v[162:163], s[6:7], 0, v[142:143]
	s_add_i32 m0, s45, 0xc000
	ds_read_b128 v[174:177], v167
	ds_read_b128 v[178:181], v167 offset:1024
	ds_read_b128 v[182:185], v167 offset:2048
	ds_read_b128 v[186:189], v167 offset:3072
	ds_read_b128 v[190:193], v167 offset:4096
	ds_read_b128 v[194:197], v167 offset:5120
	ds_read_b128 v[198:201], v167 offset:6144
	ds_read_b128 v[202:205], v167 offset:7168
	global_load_lds_dwordx4 v[162:163], off
	v_lshl_add_u64 v[162:163], s[6:7], 0, v[144:145]
	s_add_i32 m0, s45, 0xe000
	s_nop 0
	global_load_lds_dwordx4 v[162:163], off
	s_waitcnt lgkmcnt(8)
	s_barrier
	s_waitcnt lgkmcnt(0)
	s_waitcnt lgkmcnt(0)
	v_mfma_f32_16x16x32_bf16 v[126:129], v[150:153], v[174:177], v[126:129]
	v_mfma_f32_16x16x32_bf16 v[122:125], v[158:161], v[174:177], v[122:125]
	v_mfma_f32_16x16x32_bf16 v[110:113], v[150:153], v[182:185], v[110:113]
	v_mfma_f32_16x16x32_bf16 v[106:109], v[158:161], v[182:185], v[106:109]
	v_mfma_f32_16x16x32_bf16 v[94:97], v[150:153], v[190:193], v[94:97]
	v_mfma_f32_16x16x32_bf16 v[90:93], v[158:161], v[190:193], v[90:93]
	v_mfma_f32_16x16x32_bf16 v[78:81], v[150:153], v[198:201], v[78:81]
	v_mfma_f32_16x16x32_bf16 v[74:77], v[158:161], v[198:201], v[74:77]
	v_mfma_f32_16x16x32_bf16 v[126:129], v[154:157], v[178:181], v[126:129]
	v_mfma_f32_16x16x32_bf16 v[122:125], v[170:173], v[178:181], v[122:125]
	v_mfma_f32_16x16x32_bf16 v[110:113], v[154:157], v[186:189], v[110:113]
	v_mfma_f32_16x16x32_bf16 v[106:109], v[170:173], v[186:189], v[106:109]
	v_mfma_f32_16x16x32_bf16 v[94:97], v[154:157], v[194:197], v[94:97]
	v_mfma_f32_16x16x32_bf16 v[90:93], v[170:173], v[194:197], v[90:93]
	v_mfma_f32_16x16x32_bf16 v[78:81], v[154:157], v[202:205], v[78:81]
	v_mfma_f32_16x16x32_bf16 v[74:77], v[170:173], v[202:205], v[74:77]
	s_barrier
	s_add_i32 s40, s55, s44
	v_lshl_add_u64 v[162:163], s[30:31], 0, v[132:133]
	s_mov_b32 m0, s40
	ds_read_b128 v[206:209], v168
	ds_read_b128 v[210:213], v168 offset:1024
	ds_read_b128 v[214:217], v168 offset:2048
	ds_read_b128 v[218:221], v168 offset:3072
	global_load_lds_dwordx4 v[162:163], off
	v_lshl_add_u64 v[222:223], s[30:31], 0, v[136:137]
	s_add_i32 m0, s40, 0x2000
	s_nop 0
	global_load_lds_dwordx4 v[222:223], off
	s_barrier
	s_waitcnt lgkmcnt(0)
	s_waitcnt lgkmcnt(0)
	v_mfma_f32_16x16x32_bf16 v[118:121], v[206:209], v[174:177], v[118:121]
	v_mfma_f32_16x16x32_bf16 v[114:117], v[214:217], v[174:177], v[114:117]
	v_mfma_f32_16x16x32_bf16 v[102:105], v[206:209], v[182:185], v[102:105]
	v_mfma_f32_16x16x32_bf16 v[98:101], v[214:217], v[182:185], v[98:101]
	v_mfma_f32_16x16x32_bf16 v[86:89], v[206:209], v[190:193], v[86:89]
	v_mfma_f32_16x16x32_bf16 v[82:85], v[214:217], v[190:193], v[82:85]
	v_mfma_f32_16x16x32_bf16 v[70:73], v[206:209], v[198:201], v[70:73]
	v_mfma_f32_16x16x32_bf16 v[66:69], v[214:217], v[198:201], v[66:69]
	v_mfma_f32_16x16x32_bf16 v[118:121], v[210:213], v[178:181], v[118:121]
	v_mfma_f32_16x16x32_bf16 v[114:117], v[218:221], v[178:181], v[114:117]
	v_mfma_f32_16x16x32_bf16 v[102:105], v[210:213], v[186:189], v[102:105]
	v_mfma_f32_16x16x32_bf16 v[98:101], v[218:221], v[186:189], v[98:101]
	v_mfma_f32_16x16x32_bf16 v[86:89], v[210:213], v[194:197], v[86:89]
	v_mfma_f32_16x16x32_bf16 v[82:85], v[218:221], v[194:197], v[82:85]
	v_mfma_f32_16x16x32_bf16 v[70:73], v[210:213], v[202:205], v[70:73]
	v_mfma_f32_16x16x32_bf16 v[66:69], v[218:221], v[202:205], v[66:69]
	s_mov_b32 m0, s45
	v_lshl_add_u64 v[224:225], s[34:35], 0, v[130:131]
	s_barrier
	ds_read_b128 v[174:177], v167 offset:16384
	ds_read_b128 v[178:181], v167 offset:17408
	ds_read_b128 v[182:185], v167 offset:18432
	ds_read_b128 v[186:189], v167 offset:19456
	ds_read_b128 v[190:193], v167 offset:20480
	ds_read_b128 v[194:197], v167 offset:21504
	ds_read_b128 v[198:201], v167 offset:22528
	ds_read_b128 v[202:205], v167 offset:23552
	global_load_lds_dwordx4 v[224:225], off
	v_lshl_add_u64 v[226:227], s[34:35], 0, v[134:135]
	s_mov_b32 m0, s46
	s_nop 0
	global_load_lds_dwordx4 v[226:227], off
	s_barrier
	s_waitcnt lgkmcnt(0)
	s_waitcnt lgkmcnt(0)
	v_mfma_f32_16x16x32_bf16 v[62:65], v[150:153], v[174:177], v[62:65]
	v_mfma_f32_16x16x32_bf16 v[58:61], v[158:161], v[174:177], v[58:61]
	v_mfma_f32_16x16x32_bf16 v[46:49], v[150:153], v[182:185], v[46:49]
	v_mfma_f32_16x16x32_bf16 v[42:45], v[158:161], v[182:185], v[42:45]
	v_mfma_f32_16x16x32_bf16 v[30:33], v[150:153], v[190:193], v[30:33]
	v_mfma_f32_16x16x32_bf16 v[26:29], v[158:161], v[190:193], v[26:29]
	v_mfma_f32_16x16x32_bf16 v[14:17], v[150:153], v[198:201], v[14:17]
	v_mfma_f32_16x16x32_bf16 v[10:13], v[158:161], v[198:201], v[10:13]
	v_mfma_f32_16x16x32_bf16 v[62:65], v[154:157], v[178:181], v[62:65]
	v_mfma_f32_16x16x32_bf16 v[58:61], v[170:173], v[178:181], v[58:61]
	v_mfma_f32_16x16x32_bf16 v[46:49], v[154:157], v[186:189], v[46:49]
	v_mfma_f32_16x16x32_bf16 v[42:45], v[170:173], v[186:189], v[42:45]
	v_mfma_f32_16x16x32_bf16 v[30:33], v[154:157], v[194:197], v[30:33]
	v_mfma_f32_16x16x32_bf16 v[26:29], v[170:173], v[194:197], v[26:29]
	v_mfma_f32_16x16x32_bf16 v[14:17], v[154:157], v[202:205], v[14:17]
	v_mfma_f32_16x16x32_bf16 v[10:13], v[170:173], v[202:205], v[10:13]
	s_barrier
; #define PG8_STAGE(bufoff, gbase, voff) do { _Pragma("unroll") for (int _i = 0; _i < 2; ++_i) \
;     __builtin_amdgcn_global_load_lds((const unsigned*)((const char*)(gbase) + (voff)[_i]), (LAS unsigned*)(lds + (bufoff) + ldsw + _i * 8192), 16, 0, 0); } while (0)
; #define PG8_LDA(dst, b, h) do { _Pragma("unroll") for (int m = 0; m < 4; ++m) _Pragma("unroll") for (int k = 0; k < 2; ++k) dst[m][k] = *(const LAS bf16x8*)(lds + PG8_SA(b, h) + aoff + m * 2048 + k * 1024); } while (0)
; #define PG8_LDB(dst, b, h) do { _Pragma("unroll") for (int n = 0; n < 2; ++n) _Pragma("unroll") for (int k = 0; k < 2; ++k) dst[n][k] = *(const LAS bf16x8*)(lds + PG8_SB(b, h) + boff + n * 2048 + k * 1024); } while (0)
; #define PG8_MMA(ai, bj, At, Bt) do { __builtin_amdgcn_s_setprio(1); _Pragma("unroll") for (int m = 0; m < 4; ++m) _Pragma("unroll") for (int n = 0; n < 2; ++n) _Pragma("unroll") for (int k = 0; k < 2; ++k) \
;     acc[ai][bj][m][n] = __builtin_amdgcn_mfma_f32_16x16x32_bf16(Bt[n][k], At[m][k], acc[ai][bj][m][n], 0, 0, 0); __builtin_amdgcn_s_setprio(0); } while (0)
; #define PG8_WAIT_V(n) asm volatile("s_waitcnt vmcnt(" #n ")" ::: "memory")
; #define PG8_WAIT_L(n) asm volatile("s_waitcnt lgkmcnt(" #n ")" ::: "memory")
; #define PG8_BAR __builtin_amdgcn_s_barrier()
; #define PG8_SCHED __builtin_amdgcn_sched_barrier(0)
; template <class Epi>
; DI void gemm_phase(LAS unsigned char* lds, const Gemm g, const StaticOrder& S, const Epi& E) {
;     ...
;       PG8_STAGE(PG8_SB(0, 1), b2 + hstepB, voffB);
;       PG8_WAIT_V(6); PG8_BAR; PG8_MMA(1, 1, At, B1); PG8_BAR;
;       PG8_LDB(B0, 1, 0); PG8_SCHED; PG8_LDA(At, 1, 0); PG8_STAGE(PG8_SA(0, 1), a2 + hstepA, voffA);
;       PG8_WAIT_L(8); PG8_BAR; PG8_WAIT_L(0); PG8_MMA(0, 0, At, B0); PG8_BAR; PG8_SCHED;
;       PG8_LDB(B1, 1, 1); PG8_STAGE(PG8_SB(1, 0), b3, voffB);
;       PG8_BAR; PG8_WAIT_L(0); PG8_MMA(0, 1, At, B1); PG8_BAR;
;       PG8_LDA(At, 1, 1); PG8_STAGE(PG8_SA(1, 0), a3, voffA);
;       PG8_BAR; PG8_WAIT_L(0); PG8_MMA(1, 0, At, B0); PG8_BAR; PG8_SCHED;
	s_add_u32 s40, s30, 0x80000
	s_addc_u32 s41, s31, 0
	s_add_i32 s59, s56, s44
	v_lshl_add_u64 v[150:151], s[40:41], 0, v[132:133]
	s_mov_b32 m0, s59
	s_nop 0
	global_load_lds_dwordx4 v[150:151], off
	v_lshl_add_u64 v[150:151], s[40:41], 0, v[136:137]
	s_add_i32 m0, s59, 0x2000
	s_nop 0
	global_load_lds_dwordx4 v[150:151], off
	s_waitcnt vmcnt(6)
	s_barrier
	v_mfma_f32_16x16x32_bf16 v[54:57], v[206:209], v[174:177], v[54:57]
	v_mfma_f32_16x16x32_bf16 v[50:53], v[214:217], v[174:177], v[50:53]
	v_mfma_f32_16x16x32_bf16 v[38:41], v[206:209], v[182:185], v[38:41]
	v_mfma_f32_16x16x32_bf16 v[34:37], v[214:217], v[182:185], v[34:37]
	v_mfma_f32_16x16x32_bf16 v[22:25], v[206:209], v[190:193], v[22:25]
	v_mfma_f32_16x16x32_bf16 v[18:21], v[214:217], v[190:193], v[18:21]
	v_mfma_f32_16x16x32_bf16 v[6:9], v[206:209], v[198:201], v[6:9]
	v_mfma_f32_16x16x32_bf16 v[2:5], v[214:217], v[198:201], v[2:5]
	v_mfma_f32_16x16x32_bf16 v[54:57], v[210:213], v[178:181], v[54:57]
	v_mfma_f32_16x16x32_bf16 v[50:53], v[218:221], v[178:181], v[50:53]
	v_mfma_f32_16x16x32_bf16 v[38:41], v[210:213], v[186:189], v[38:41]
	v_mfma_f32_16x16x32_bf16 v[34:37], v[218:221], v[186:189], v[34:37]
	v_mfma_f32_16x16x32_bf16 v[22:25], v[210:213], v[194:197], v[22:25]
	v_mfma_f32_16x16x32_bf16 v[18:21], v[218:221], v[194:197], v[18:21]
	v_mfma_f32_16x16x32_bf16 v[6:9], v[210:213], v[202:205], v[6:9]
	v_mfma_f32_16x16x32_bf16 v[2:5], v[218:221], v[202:205], v[2:5]
	s_add_i32 s40, 0, 0x18000
	v_add_u32_e32 v138, s40, v165
	s_barrier
	ds_read_b128 v[150:153], v138
	ds_read_b128 v[154:157], v138 offset:1024
	ds_read_b128 v[158:161], v138 offset:2048
	ds_read_b128 v[170:173], v138 offset:3072
	s_add_u32 s34, s34, 0x80000
	s_addc_u32 s35, s35, 0
	s_mov_b32 m0, s47
	v_lshl_add_u64 v[206:207], s[34:35], 0, v[130:131]
	ds_read_b128 v[174:177], v167 offset:32768
	ds_read_b128 v[178:181], v167 offset:33792
	ds_read_b128 v[182:185], v167 offset:34816
	ds_read_b128 v[186:189], v167 offset:35840
	ds_read_b128 v[190:193], v167 offset:36864
	ds_read_b128 v[194:197], v167 offset:37888
	ds_read_b128 v[198:201], v167 offset:38912
	ds_read_b128 v[202:205], v167 offset:39936
	global_load_lds_dwordx4 v[206:207], off
	v_lshl_add_u64 v[206:207], s[34:35], 0, v[134:135]
	s_mov_b32 m0, s48
	s_nop 0
	global_load_lds_dwordx4 v[206:207], off
	s_waitcnt lgkmcnt(8)
	s_barrier
	s_waitcnt lgkmcnt(0)
	s_waitcnt lgkmcnt(0)
	v_mfma_f32_16x16x32_bf16 v[126:129], v[150:153], v[174:177], v[126:129]
	v_mfma_f32_16x16x32_bf16 v[122:125], v[158:161], v[174:177], v[122:125]
	v_mfma_f32_16x16x32_bf16 v[110:113], v[150:153], v[182:185], v[110:113]
	v_mfma_f32_16x16x32_bf16 v[106:109], v[158:161], v[182:185], v[106:109]
	v_mfma_f32_16x16x32_bf16 v[94:97], v[150:153], v[190:193], v[94:97]
	v_mfma_f32_16x16x32_bf16 v[90:93], v[158:161], v[190:193], v[90:93]
	v_mfma_f32_16x16x32_bf16 v[78:81], v[150:153], v[198:201], v[78:81]
	v_mfma_f32_16x16x32_bf16 v[74:77], v[158:161], v[198:201], v[74:77]
	v_mfma_f32_16x16x32_bf16 v[126:129], v[154:157], v[178:181], v[126:129]
	v_mfma_f32_16x16x32_bf16 v[122:125], v[170:173], v[178:181], v[122:125]
	v_mfma_f32_16x16x32_bf16 v[110:113], v[154:157], v[186:189], v[110:113]
	v_mfma_f32_16x16x32_bf16 v[106:109], v[170:173], v[186:189], v[106:109]
	v_mfma_f32_16x16x32_bf16 v[94:97], v[154:157], v[194:197], v[94:97]
	v_mfma_f32_16x16x32_bf16 v[90:93], v[170:173], v[194:197], v[90:93]
	v_mfma_f32_16x16x32_bf16 v[78:81], v[154:157], v[202:205], v[78:81]
	v_mfma_f32_16x16x32_bf16 v[74:77], v[170:173], v[202:205], v[74:77]
	s_barrier
	s_add_i32 s34, 0, 0x1c000
	s_add_i32 s35, s40, s44
	v_add_u32_e32 v138, s34, v165
	v_lshl_add_u64 v[162:163], v[162:163], 0, s[10:11]
	s_mov_b32 m0, s35
	ds_read_b128 v[206:209], v138
	ds_read_b128 v[210:213], v138 offset:1024
	ds_read_b128 v[214:217], v138 offset:2048
	ds_read_b128 v[218:221], v138 offset:3072
	global_load_lds_dwordx4 v[162:163], off
	v_lshl_add_u64 v[162:163], v[222:223], 0, s[10:11]
	s_add_i32 m0, s35, 0x2000
	s_nop 0
	global_load_lds_dwordx4 v[162:163], off
	s_barrier
; #define PG8_WAIT_V(n) asm volatile("s_waitcnt vmcnt(" #n ")" ::: "memory")
; #define PG8_WAIT_L(n) asm volatile("s_waitcnt lgkmcnt(" #n ")" ::: "memory")
; template <class Epi>
; DI void gemm_phase(LAS unsigned char* lds, const Gemm g, const StaticOrder& S, const Epi& E) {
;     ...
;       PG8_BAR; PG8_WAIT_L(0); PG8_MMA(0, 1, At, B1); PG8_BAR;
;       PG8_LDA(At, 1, 1); PG8_STAGE(PG8_SA(1, 0), a3, voffA);
;       PG8_BAR; PG8_WAIT_L(0); PG8_MMA(1, 0, At, B0); PG8_BAR; PG8_SCHED;
;       PG8_STAGE(PG8_SB(1, 1), b3 + hstepB, voffB);
;       PG8_WAIT_V(6); PG8_BAR; PG8_MMA(1, 1, At, B1); PG8_BAR;
;     }
;     E(acc, cur, wr, wc, fr, fq);
;   DI void operator()(const f32x4 (&acc)[2][2][4][2], const pg8::Unit& u, int wr, int wc, int fr, int fq) const {
;     ...
;         const int row = u.pm * 256 + ai * 128 + wr * 64 + m * 16 + fr;
;         const int grow = rowbase + row;
;         float rs = 1.f;
;         if (MODE == EP_IN) rs = ((const float*)(ws + OFF_RS0))[grow];
;         if (MODE == EP_UP) rs = ((const float*)(ws + OFF_RS2))[grow];
;         if (MODE == EP_Q || MODE == EP_KV) {
;           const f32x4* sp = (const f32x4*)(ws + OFF_SSQA) + (size_t)grow * 4 + (MODE == EP_KV ? 2 : 0);
;           const f32x4 s0 = sp[0], s1 = sp[1];
;           const float ss = (s0[0] + s0[1]) + (s0[2] + s0[3]) + (s1[0] + s1[1]) + (s1[2] + s1[3]);
;           rs = __builtin_amdgcn_rsqf(ss * (1.0f / 512) + EPS);
;           if (MODE == EP_Q) rs *= QSCALE;
;         }
;         float ssq = 0.f;
; #pragma unroll
;         for (int bj = 0; bj < 2; ++bj) {
;           f32x4 v0 = acc[ai][bj][m][0] * rs, v1 = acc[ai][bj][m][1] * rs;
;           if (MODE == EP_IN || MODE == EP_MIX || MODE == EP_DOWN) {
; #pragma unroll
;             for (int j = 0; j < 4; ++j) ssq += v0[j] * v0[j] + v1[j] * v1[j];
;           }
;           if (MODE == EP_UP) {
; #pragma unroll
;             for (int j = 0; j < 4; ++j) { float a = fmaxf(v0[j], 0.f), b = fmaxf(v1[j], 0.f); v0[j] = a * a; v1[j] = b * b; }
;           }
;           bf16_t* dst;
;           const int ct = bj * 128 + cl;
;           if (MODE == EP_IN) {
;             if (pn < 4) dst = (bf16_t*)(ws + OFF_PROJA) + (size_t)grow * 1024 + pn * 256 + ct;
;             else if (pn < 16) dst = (bf16_t*)(ws + OFF_PROJG) + (size_t)grow * 3072 + (pn - 4) * 256 + ct;
;             else dst = (bf16_t*)(ws + OFF_PROJS) + (size_t)grow * 256 + ct;
	s_waitcnt lgkmcnt(0)
	s_waitcnt lgkmcnt(0)
	v_mfma_f32_16x16x32_bf16 v[118:121], v[206:209], v[174:177], v[118:121]
	v_mfma_f32_16x16x32_bf16 v[114:117], v[214:217], v[174:177], v[114:117]
	v_mfma_f32_16x16x32_bf16 v[102:105], v[206:209], v[182:185], v[102:105]
	v_mfma_f32_16x16x32_bf16 v[98:101], v[214:217], v[182:185], v[98:101]
	v_mfma_f32_16x16x32_bf16 v[86:89], v[206:209], v[190:193], v[86:89]
	v_mfma_f32_16x16x32_bf16 v[82:85], v[214:217], v[190:193], v[82:85]
	v_mfma_f32_16x16x32_bf16 v[70:73], v[206:209], v[198:201], v[70:73]
	v_mfma_f32_16x16x32_bf16 v[66:69], v[214:217], v[198:201], v[66:69]
	v_mfma_f32_16x16x32_bf16 v[118:121], v[210:213], v[178:181], v[118:121]
	v_mfma_f32_16x16x32_bf16 v[114:117], v[218:221], v[178:181], v[114:117]
	v_mfma_f32_16x16x32_bf16 v[102:105], v[210:213], v[186:189], v[102:105]
	v_mfma_f32_16x16x32_bf16 v[98:101], v[218:221], v[186:189], v[98:101]
	v_mfma_f32_16x16x32_bf16 v[86:89], v[210:213], v[194:197], v[86:89]
	v_mfma_f32_16x16x32_bf16 v[82:85], v[218:221], v[194:197], v[82:85]
	v_mfma_f32_16x16x32_bf16 v[70:73], v[210:213], v[202:205], v[70:73]
	v_mfma_f32_16x16x32_bf16 v[66:69], v[218:221], v[202:205], v[66:69]
	s_mov_b32 m0, s50
	v_lshl_add_u64 v[162:163], v[224:225], 0, s[10:11]
	s_barrier
	ds_read_b128 v[174:177], v167 offset:49152
	ds_read_b128 v[178:181], v167 offset:50176
	ds_read_b128 v[182:185], v167 offset:51200
	ds_read_b128 v[186:189], v167 offset:52224
	ds_read_b128 v[190:193], v167 offset:53248
	ds_read_b128 v[194:197], v167 offset:54272
	ds_read_b128 v[198:201], v167 offset:55296
	ds_read_b128 v[202:205], v167 offset:56320
	global_load_lds_dwordx4 v[162:163], off
	v_lshl_add_u64 v[162:163], v[226:227], 0, s[10:11]
	s_mov_b32 m0, s51
	s_nop 0
	global_load_lds_dwordx4 v[162:163], off
	s_barrier
	s_waitcnt lgkmcnt(0)
	s_waitcnt lgkmcnt(0)
	v_mfma_f32_16x16x32_bf16 v[62:65], v[150:153], v[174:177], v[62:65]
	v_mfma_f32_16x16x32_bf16 v[58:61], v[158:161], v[174:177], v[58:61]
	v_mfma_f32_16x16x32_bf16 v[46:49], v[150:153], v[182:185], v[46:49]
	v_mfma_f32_16x16x32_bf16 v[42:45], v[158:161], v[182:185], v[42:45]
	v_mfma_f32_16x16x32_bf16 v[30:33], v[150:153], v[190:193], v[30:33]
	v_mfma_f32_16x16x32_bf16 v[26:29], v[158:161], v[190:193], v[26:29]
	v_mfma_f32_16x16x32_bf16 v[14:17], v[150:153], v[198:201], v[14:17]
	v_mfma_f32_16x16x32_bf16 v[10:13], v[158:161], v[198:201], v[10:13]
	v_mfma_f32_16x16x32_bf16 v[62:65], v[154:157], v[178:181], v[62:65]
	v_mfma_f32_16x16x32_bf16 v[58:61], v[170:173], v[178:181], v[58:61]
	v_mfma_f32_16x16x32_bf16 v[46:49], v[154:157], v[186:189], v[46:49]
	v_mfma_f32_16x16x32_bf16 v[42:45], v[170:173], v[186:189], v[42:45]
	v_mfma_f32_16x16x32_bf16 v[30:33], v[154:157], v[194:197], v[30:33]
	v_mfma_f32_16x16x32_bf16 v[26:29], v[170:173], v[194:197], v[26:29]
	v_mfma_f32_16x16x32_bf16 v[14:17], v[154:157], v[202:205], v[14:17]
	v_mfma_f32_16x16x32_bf16 v[10:13], v[170:173], v[202:205], v[10:13]
	s_barrier
	s_add_u32 s30, s30, 0x80080
	s_addc_u32 s31, s31, 0
	s_add_i32 s34, s34, s44
	v_lshl_add_u64 v[150:151], s[30:31], 0, v[132:133]
	s_mov_b32 m0, s34
	s_nop 0
	global_load_lds_dwordx4 v[150:151], off
	v_lshl_add_u64 v[150:151], s[30:31], 0, v[136:137]
	s_add_i32 m0, s34, 0x2000
	s_nop 0
	global_load_lds_dwordx4 v[150:151], off
	s_waitcnt vmcnt(6)
	s_barrier
	v_mfma_f32_16x16x32_bf16 v[54:57], v[206:209], v[174:177], v[54:57]
	v_mfma_f32_16x16x32_bf16 v[50:53], v[214:217], v[174:177], v[50:53]
	v_mfma_f32_16x16x32_bf16 v[38:41], v[206:209], v[182:185], v[38:41]
	v_mfma_f32_16x16x32_bf16 v[34:37], v[214:217], v[182:185], v[34:37]
	v_mfma_f32_16x16x32_bf16 v[22:25], v[206:209], v[190:193], v[22:25]
	v_mfma_f32_16x16x32_bf16 v[18:21], v[214:217], v[190:193], v[18:21]
	v_mfma_f32_16x16x32_bf16 v[6:9], v[206:209], v[198:201], v[6:9]
	v_mfma_f32_16x16x32_bf16 v[2:5], v[214:217], v[198:201], v[2:5]
	v_mfma_f32_16x16x32_bf16 v[54:57], v[210:213], v[178:181], v[54:57]
	v_mfma_f32_16x16x32_bf16 v[50:53], v[218:221], v[178:181], v[50:53]
	v_mfma_f32_16x16x32_bf16 v[38:41], v[210:213], v[186:189], v[38:41]
	v_mfma_f32_16x16x32_bf16 v[34:37], v[218:221], v[186:189], v[34:37]
	v_mfma_f32_16x16x32_bf16 v[22:25], v[210:213], v[194:197], v[22:25]
	v_mfma_f32_16x16x32_bf16 v[18:21], v[218:221], v[194:197], v[18:21]
	v_mfma_f32_16x16x32_bf16 v[6:9], v[210:213], v[202:205], v[6:9]
	v_mfma_f32_16x16x32_bf16 v[2:5], v[218:221], v[202:205], v[2:5]
	s_add_i32 s39, s39, 2
	s_add_u32 s6, s6, 0x100
	s_addc_u32 s7, s7, 0
	s_add_u32 s37, s37, 0x100
	s_addc_u32 s38, s38, 0
	s_cmp_gt_u32 s39, 29
	s_barrier
	s_cbranch_scc0 .LBB0_184
	v_lshl_add_u32 v150, s4, 8, v164
	v_ashrrev_i32_e32 v151, 31, v150
	v_lshl_add_u64 v[152:153], v[150:151], 2, s[12:13]
	s_nop 0
	s_cmp_lt_i32 s36, 4
	s_cselect_b64 s[34:35], -1, 0
	s_cmp_gt_i32 s36, 3
	s_cselect_b64 s[4:5], -1, 0
	s_cmp_gt_u32 s36, 15
	s_cselect_b64 s[38:39], -1, 0
	s_lshl_b32 s30, s36, 8
	v_mad_i64_i32 v[154:155], s[6:7], v150, s57, 0
	s_mov_b32 s8, s30
	v_lshlrev_b64 v[156:157], 9, v[150:151]
	s_mov_b64 s[6:7], -1
	s_and_b64 vcc, exec, s[4:5]
	s_cbranch_vccz .LBB0_191
	s_and_b64 vcc, exec, s[38:39]
	s_cbranch_vccz .LBB0_188
	v_lshl_add_u64 v[162:163], s[14:15], 0, v[156:157]
	s_mov_b64 s[6:7], 0

; #define PG8_STAGE(bufoff, gbase, voff) do { _Pragma("unroll") for (int _i = 0; _i < 2; ++_i) \
;     __builtin_amdgcn_global_load_lds((const unsigned*)((const char*)(gbase) + (voff)[_i]), (LAS unsigned*)(lds + (bufoff) + ldsw + _i * 8192), 16, 0, 0); } while (0)
; #define PG8_LDA(dst, b, h) do { _Pragma("unroll") for (int m = 0; m < 4; ++m) _Pragma("unroll") for (int k = 0; k < 2; ++k) dst[m][k] = *(const LAS bf16x8*)(lds + PG8_SA(b, h) + aoff + m * 2048 + k * 1024); } while (0)
; #define PG8_LDB(dst, b, h) do { _Pragma("unroll") for (int n = 0; n < 2; ++n) _Pragma("unroll") for (int k = 0; k < 2; ++k) dst[n][k] = *(const LAS bf16x8*)(lds + PG8_SB(b, h) + boff + n * 2048 + k * 1024); } while (0)
; #define PG8_MMA(ai, bj, At, Bt) do { __builtin_amdgcn_s_setprio(1); _Pragma("unroll") for (int m = 0; m < 4; ++m) _Pragma("unroll") for (int n = 0; n < 2; ++n) _Pragma("unroll") for (int k = 0; k < 2; ++k) \
;     acc[ai][bj][m][n] = __builtin_amdgcn_mfma_f32_16x16x32_bf16(Bt[n][k], At[m][k], acc[ai][bj][m][n], 0, 0, 0); __builtin_amdgcn_s_setprio(0); } while (0)
; #define PG8_WAIT_V(n) asm volatile("s_waitcnt vmcnt(" #n ")" ::: "memory")
; #define PG8_WAIT_L(n) asm volatile("s_waitcnt lgkmcnt(" #n ")" ::: "memory")
; #define PG8_BAR __builtin_amdgcn_s_barrier()
; #define PG8_SCHED __builtin_amdgcn_sched_barrier(0)
; template <class Epi>
; DI void gemm_phase(LAS unsigned char* lds, const Gemm g, const StaticOrder& S, const Epi& E) {
;     ...
;       PG8_LDB(B0, 0, 0); PG8_SCHED; PG8_LDA(At, 0, 0); PG8_STAGE(PG8_SA(1, 1), a1 + hstepA, voffA);
;       PG8_WAIT_L(8); PG8_BAR; PG8_WAIT_L(0); PG8_MMA(0, 0, At, B0); PG8_BAR; PG8_SCHED;
;       PG8_LDB(B1, 0, 1); PG8_STAGE(PG8_SB(0, 0), b2, voffB);
;       PG8_BAR; PG8_WAIT_L(0); PG8_MMA(0, 1, At, B1); PG8_BAR;
;       PG8_LDA(At, 0, 1); PG8_STAGE(PG8_SA(0, 0), a2, voffA);
;       PG8_BAR; PG8_WAIT_L(0); PG8_MMA(1, 0, At, B0); PG8_BAR; PG8_SCHED;
;       PG8_STAGE(PG8_SB(0, 1), b2 + hstepB, voffB);
;       PG8_WAIT_V(6); PG8_BAR; PG8_MMA(1, 1, At, B1); PG8_BAR;
.LBB0_484:
	ds_read_b128 v[154:157], v174
	ds_read_b128 v[158:161], v174 offset:1024
	ds_read_b128 v[162:165], v174 offset:2048
	ds_read_b128 v[178:181], v174 offset:3072
	s_add_u32 s28, s26, 0xfffc0080
	s_addc_u32 s29, s27, -1
	s_cmp_eq_u32 s53, 4
	s_cselect_b32 s31, s3, s29
	s_cselect_b32 s30, s5, s28
	s_cselect_b32 s29, s6, s33
	s_cselect_b32 s28, s19, s21
	v_lshl_add_u64 v[214:215], s[26:27], 0, v[146:147]
	s_add_i32 m0, s40, 0xc000
	ds_read_b128 v[182:185], v175
	ds_read_b128 v[186:189], v175 offset:1024
	ds_read_b128 v[190:193], v175 offset:2048
	ds_read_b128 v[194:197], v175 offset:3072
	ds_read_b128 v[198:201], v175 offset:4096
	ds_read_b128 v[202:205], v175 offset:5120
	ds_read_b128 v[206:209], v175 offset:6144
	ds_read_b128 v[210:213], v175 offset:7168
	global_load_lds_dwordx4 v[214:215], off
	v_lshl_add_u64 v[214:215], s[26:27], 0, v[148:149]
	s_add_i32 m0, s40, 0xe000
	s_nop 0
	global_load_lds_dwordx4 v[214:215], off
	s_waitcnt lgkmcnt(8)
	s_barrier
	s_waitcnt lgkmcnt(0)
	s_waitcnt lgkmcnt(0)
	v_mfma_f32_16x16x32_bf16 v[126:129], v[154:157], v[182:185], v[126:129]
	v_mfma_f32_16x16x32_bf16 v[122:125], v[162:165], v[182:185], v[122:125]
	v_mfma_f32_16x16x32_bf16 v[110:113], v[154:157], v[190:193], v[110:113]
	v_mfma_f32_16x16x32_bf16 v[106:109], v[162:165], v[190:193], v[106:109]
	v_mfma_f32_16x16x32_bf16 v[94:97], v[154:157], v[198:201], v[94:97]
	v_mfma_f32_16x16x32_bf16 v[90:93], v[162:165], v[198:201], v[90:93]
	v_mfma_f32_16x16x32_bf16 v[78:81], v[154:157], v[206:209], v[78:81]
	v_mfma_f32_16x16x32_bf16 v[74:77], v[162:165], v[206:209], v[74:77]
	v_mfma_f32_16x16x32_bf16 v[126:129], v[158:161], v[186:189], v[126:129]
	v_mfma_f32_16x16x32_bf16 v[122:125], v[178:181], v[186:189], v[122:125]
	v_mfma_f32_16x16x32_bf16 v[110:113], v[158:161], v[194:197], v[110:113]
	v_mfma_f32_16x16x32_bf16 v[106:109], v[178:181], v[194:197], v[106:109]
	v_mfma_f32_16x16x32_bf16 v[94:97], v[158:161], v[202:205], v[94:97]
	v_mfma_f32_16x16x32_bf16 v[90:93], v[178:181], v[202:205], v[90:93]
	v_mfma_f32_16x16x32_bf16 v[78:81], v[158:161], v[210:213], v[78:81]
	v_mfma_f32_16x16x32_bf16 v[74:77], v[178:181], v[210:213], v[74:77]
	s_barrier
	s_add_i32 s59, s51, s39
	v_lshl_add_u64 v[230:231], s[28:29], 0, v[132:133]
	s_mov_b32 m0, s59
	ds_read_b128 v[214:217], v176
	ds_read_b128 v[218:221], v176 offset:1024
	ds_read_b128 v[222:225], v176 offset:2048
	ds_read_b128 v[226:229], v176 offset:3072
	global_load_lds_dwordx4 v[230:231], off
	v_lshl_add_u64 v[232:233], s[28:29], 0, v[136:137]
	s_add_i32 m0, s59, 0x2000
	s_nop 0
	global_load_lds_dwordx4 v[232:233], off
	s_barrier
	s_waitcnt lgkmcnt(0)
	s_waitcnt lgkmcnt(0)
	v_mfma_f32_16x16x32_bf16 v[118:121], v[214:217], v[182:185], v[118:121]
	v_mfma_f32_16x16x32_bf16 v[114:117], v[222:225], v[182:185], v[114:117]
	v_mfma_f32_16x16x32_bf16 v[102:105], v[214:217], v[190:193], v[102:105]
	v_mfma_f32_16x16x32_bf16 v[98:101], v[222:225], v[190:193], v[98:101]
	v_mfma_f32_16x16x32_bf16 v[86:89], v[214:217], v[198:201], v[86:89]
	v_mfma_f32_16x16x32_bf16 v[82:85], v[222:225], v[198:201], v[82:85]
	v_mfma_f32_16x16x32_bf16 v[70:73], v[214:217], v[206:209], v[70:73]
	v_mfma_f32_16x16x32_bf16 v[66:69], v[222:225], v[206:209], v[66:69]
	v_mfma_f32_16x16x32_bf16 v[118:121], v[218:221], v[186:189], v[118:121]
	v_mfma_f32_16x16x32_bf16 v[114:117], v[226:229], v[186:189], v[114:117]
	v_mfma_f32_16x16x32_bf16 v[102:105], v[218:221], v[194:197], v[102:105]
	v_mfma_f32_16x16x32_bf16 v[98:101], v[226:229], v[194:197], v[98:101]
	v_mfma_f32_16x16x32_bf16 v[86:89], v[218:221], v[202:205], v[86:89]
	v_mfma_f32_16x16x32_bf16 v[82:85], v[226:229], v[202:205], v[82:85]
	v_mfma_f32_16x16x32_bf16 v[70:73], v[218:221], v[210:213], v[70:73]
	v_mfma_f32_16x16x32_bf16 v[66:69], v[226:229], v[210:213], v[66:69]
	s_mov_b32 m0, s40
	v_lshl_add_u64 v[234:235], s[30:31], 0, v[130:131]
	s_barrier
	ds_read_b128 v[182:185], v175 offset:16384
	ds_read_b128 v[186:189], v175 offset:17408
	ds_read_b128 v[190:193], v175 offset:18432
	ds_read_b128 v[194:197], v175 offset:19456
	ds_read_b128 v[198:201], v175 offset:20480
	ds_read_b128 v[202:205], v175 offset:21504
	ds_read_b128 v[206:209], v175 offset:22528
	ds_read_b128 v[210:213], v175 offset:23552
	global_load_lds_dwordx4 v[234:235], off
	v_lshl_add_u64 v[236:237], s[30:31], 0, v[134:135]
	s_mov_b32 m0, s41
	s_nop 0
	global_load_lds_dwordx4 v[236:237], off
	s_barrier
	s_waitcnt lgkmcnt(0)
	s_waitcnt lgkmcnt(0)
	v_mfma_f32_16x16x32_bf16 v[62:65], v[154:157], v[182:185], v[62:65]
	v_mfma_f32_16x16x32_bf16 v[58:61], v[162:165], v[182:185], v[58:61]
	v_mfma_f32_16x16x32_bf16 v[46:49], v[154:157], v[190:193], v[46:49]
	v_mfma_f32_16x16x32_bf16 v[42:45], v[162:165], v[190:193], v[42:45]
	v_mfma_f32_16x16x32_bf16 v[30:33], v[154:157], v[198:201], v[30:33]
	v_mfma_f32_16x16x32_bf16 v[26:29], v[162:165], v[198:201], v[26:29]
	v_mfma_f32_16x16x32_bf16 v[14:17], v[154:157], v[206:209], v[14:17]
	v_mfma_f32_16x16x32_bf16 v[10:13], v[162:165], v[206:209], v[10:13]
	v_mfma_f32_16x16x32_bf16 v[62:65], v[158:161], v[186:189], v[62:65]
	v_mfma_f32_16x16x32_bf16 v[58:61], v[178:181], v[186:189], v[58:61]
	v_mfma_f32_16x16x32_bf16 v[46:49], v[158:161], v[194:197], v[46:49]
	v_mfma_f32_16x16x32_bf16 v[42:45], v[178:181], v[194:197], v[42:45]
	v_mfma_f32_16x16x32_bf16 v[30:33], v[158:161], v[202:205], v[30:33]
	v_mfma_f32_16x16x32_bf16 v[26:29], v[178:181], v[202:205], v[26:29]
	v_mfma_f32_16x16x32_bf16 v[14:17], v[158:161], v[210:213], v[14:17]
	v_mfma_f32_16x16x32_bf16 v[10:13], v[178:181], v[210:213], v[10:13]
	s_barrier
; #define PG8_STAGE(bufoff, gbase, voff) do { _Pragma("unroll") for (int _i = 0; _i < 2; ++_i) \
;     __builtin_amdgcn_global_load_lds((const unsigned*)((const char*)(gbase) + (voff)[_i]), (LAS unsigned*)(lds + (bufoff) + ldsw + _i * 8192), 16, 0, 0); } while (0)
; #define PG8_LDA(dst, b, h) do { _Pragma("unroll") for (int m = 0; m < 4; ++m) _Pragma("unroll") for (int k = 0; k < 2; ++k) dst[m][k] = *(const LAS bf16x8*)(lds + PG8_SA(b, h) + aoff + m * 2048 + k * 1024); } while (0)
; #define PG8_LDB(dst, b, h) do { _Pragma("unroll") for (int n = 0; n < 2; ++n) _Pragma("unroll") for (int k = 0; k < 2; ++k) dst[n][k] = *(const LAS bf16x8*)(lds + PG8_SB(b, h) + boff + n * 2048 + k * 1024); } while (0)
; #define PG8_MMA(ai, bj, At, Bt) do { __builtin_amdgcn_s_setprio(1); _Pragma("unroll") for (int m = 0; m < 4; ++m) _Pragma("unroll") for (int n = 0; n < 2; ++n) _Pragma("unroll") for (int k = 0; k < 2; ++k) \
;     acc[ai][bj][m][n] = __builtin_amdgcn_mfma_f32_16x16x32_bf16(Bt[n][k], At[m][k], acc[ai][bj][m][n], 0, 0, 0); __builtin_amdgcn_s_setprio(0); } while (0)
; #define PG8_WAIT_V(n) asm volatile("s_waitcnt vmcnt(" #n ")" ::: "memory")
; #define PG8_WAIT_L(n) asm volatile("s_waitcnt lgkmcnt(" #n ")" ::: "memory")
; #define PG8_BAR __builtin_amdgcn_s_barrier()
; #define PG8_SCHED __builtin_amdgcn_sched_barrier(0)
; template <class Epi>
; DI void gemm_phase(LAS unsigned char* lds, const Gemm g, const StaticOrder& S, const Epi& E) {
;     ...
;       PG8_WAIT_V(6); PG8_BAR; PG8_MMA(1, 1, At, B1); PG8_BAR;
;       PG8_LDB(B0, 1, 0); PG8_SCHED; PG8_LDA(At, 1, 0); PG8_STAGE(PG8_SA(0, 1), a2 + hstepA, voffA);
;       PG8_WAIT_L(8); PG8_BAR; PG8_WAIT_L(0); PG8_MMA(0, 0, At, B0); PG8_BAR; PG8_SCHED;
;       PG8_LDB(B1, 1, 1); PG8_STAGE(PG8_SB(1, 0), b3, voffB);
;       PG8_BAR; PG8_WAIT_L(0); PG8_MMA(0, 1, At, B1); PG8_BAR;
;       PG8_LDA(At, 1, 1); PG8_STAGE(PG8_SA(1, 0), a3, voffA);
;       PG8_BAR; PG8_WAIT_L(0); PG8_MMA(1, 0, At, B0); PG8_BAR; PG8_SCHED;
	s_add_u32 s60, s28, 0x20000
	s_addc_u32 s61, s29, 0
	s_add_i32 s59, s52, s39
	v_lshl_add_u64 v[154:155], s[60:61], 0, v[132:133]
	s_mov_b32 m0, s59
	s_nop 0
	global_load_lds_dwordx4 v[154:155], off
	v_lshl_add_u64 v[154:155], s[60:61], 0, v[136:137]
	s_add_i32 m0, s59, 0x2000
	s_nop 0
	global_load_lds_dwordx4 v[154:155], off
	s_waitcnt vmcnt(6)
	s_barrier
	v_mfma_f32_16x16x32_bf16 v[54:57], v[214:217], v[182:185], v[54:57]
	v_mfma_f32_16x16x32_bf16 v[50:53], v[222:225], v[182:185], v[50:53]
	v_mfma_f32_16x16x32_bf16 v[38:41], v[214:217], v[190:193], v[38:41]
	v_mfma_f32_16x16x32_bf16 v[34:37], v[222:225], v[190:193], v[34:37]
	v_mfma_f32_16x16x32_bf16 v[22:25], v[214:217], v[198:201], v[22:25]
	v_mfma_f32_16x16x32_bf16 v[18:21], v[222:225], v[198:201], v[18:21]
	v_mfma_f32_16x16x32_bf16 v[6:9], v[214:217], v[206:209], v[6:9]
	v_mfma_f32_16x16x32_bf16 v[2:5], v[222:225], v[206:209], v[2:5]
	v_mfma_f32_16x16x32_bf16 v[54:57], v[218:221], v[186:189], v[54:57]
	v_mfma_f32_16x16x32_bf16 v[50:53], v[226:229], v[186:189], v[50:53]
	v_mfma_f32_16x16x32_bf16 v[38:41], v[218:221], v[194:197], v[38:41]
	v_mfma_f32_16x16x32_bf16 v[34:37], v[226:229], v[194:197], v[34:37]
	v_mfma_f32_16x16x32_bf16 v[22:25], v[218:221], v[202:205], v[22:25]
	v_mfma_f32_16x16x32_bf16 v[18:21], v[226:229], v[202:205], v[18:21]
	v_mfma_f32_16x16x32_bf16 v[6:9], v[218:221], v[210:213], v[6:9]
	v_mfma_f32_16x16x32_bf16 v[2:5], v[226:229], v[210:213], v[2:5]
	s_add_i32 s59, 0, 0x18000
	v_add_u32_e32 v138, s59, v173
	s_barrier
	ds_read_b128 v[154:157], v138
	ds_read_b128 v[158:161], v138 offset:1024
	ds_read_b128 v[162:165], v138 offset:2048
	ds_read_b128 v[178:181], v138 offset:3072
	s_add_u32 s30, s30, 0x40000
	s_addc_u32 s31, s31, 0
	s_mov_b32 m0, s42
	v_lshl_add_u64 v[214:215], s[30:31], 0, v[130:131]
	ds_read_b128 v[182:185], v175 offset:32768
	ds_read_b128 v[186:189], v175 offset:33792
	ds_read_b128 v[190:193], v175 offset:34816
	ds_read_b128 v[194:197], v175 offset:35840
	ds_read_b128 v[198:201], v175 offset:36864
	ds_read_b128 v[202:205], v175 offset:37888
	ds_read_b128 v[206:209], v175 offset:38912
	ds_read_b128 v[210:213], v175 offset:39936
	global_load_lds_dwordx4 v[214:215], off
	v_lshl_add_u64 v[214:215], s[30:31], 0, v[134:135]
	s_mov_b32 m0, s43
	s_nop 0
	global_load_lds_dwordx4 v[214:215], off
	s_waitcnt lgkmcnt(8)
	s_barrier
	s_waitcnt lgkmcnt(0)
	s_waitcnt lgkmcnt(0)
	v_mfma_f32_16x16x32_bf16 v[126:129], v[154:157], v[182:185], v[126:129]
	v_mfma_f32_16x16x32_bf16 v[122:125], v[162:165], v[182:185], v[122:125]
	v_mfma_f32_16x16x32_bf16 v[110:113], v[154:157], v[190:193], v[110:113]
	v_mfma_f32_16x16x32_bf16 v[106:109], v[162:165], v[190:193], v[106:109]
	v_mfma_f32_16x16x32_bf16 v[94:97], v[154:157], v[198:201], v[94:97]
	v_mfma_f32_16x16x32_bf16 v[90:93], v[162:165], v[198:201], v[90:93]
	v_mfma_f32_16x16x32_bf16 v[78:81], v[154:157], v[206:209], v[78:81]
	v_mfma_f32_16x16x32_bf16 v[74:77], v[162:165], v[206:209], v[74:77]
	v_mfma_f32_16x16x32_bf16 v[126:129], v[158:161], v[186:189], v[126:129]
	v_mfma_f32_16x16x32_bf16 v[122:125], v[178:181], v[186:189], v[122:125]
	v_mfma_f32_16x16x32_bf16 v[110:113], v[158:161], v[194:197], v[110:113]
	v_mfma_f32_16x16x32_bf16 v[106:109], v[178:181], v[194:197], v[106:109]
	v_mfma_f32_16x16x32_bf16 v[94:97], v[158:161], v[202:205], v[94:97]
	v_mfma_f32_16x16x32_bf16 v[90:93], v[178:181], v[202:205], v[90:93]
	v_mfma_f32_16x16x32_bf16 v[78:81], v[158:161], v[210:213], v[78:81]
	v_mfma_f32_16x16x32_bf16 v[74:77], v[178:181], v[210:213], v[74:77]
	s_barrier
	s_add_i32 s30, 0, 0x1c000
	s_add_i32 s31, s59, s39
	v_add_u32_e32 v138, s30, v173
	v_lshl_add_u64 v[230:231], v[230:231], 0, s[8:9]
	s_mov_b32 m0, s31
	ds_read_b128 v[214:217], v138
	ds_read_b128 v[218:221], v138 offset:1024
	ds_read_b128 v[222:225], v138 offset:2048
	ds_read_b128 v[226:229], v138 offset:3072
	global_load_lds_dwordx4 v[230:231], off
	v_lshl_add_u64 v[230:231], v[232:233], 0, s[8:9]
	s_add_i32 m0, s31, 0x2000
	s_nop 0
	global_load_lds_dwordx4 v[230:231], off
	s_barrier
	s_waitcnt lgkmcnt(0)
	s_waitcnt lgkmcnt(0)
	v_mfma_f32_16x16x32_bf16 v[118:121], v[214:217], v[182:185], v[118:121]
	v_mfma_f32_16x16x32_bf16 v[114:117], v[222:225], v[182:185], v[114:117]
	v_mfma_f32_16x16x32_bf16 v[102:105], v[214:217], v[190:193], v[102:105]
	v_mfma_f32_16x16x32_bf16 v[98:101], v[222:225], v[190:193], v[98:101]
	v_mfma_f32_16x16x32_bf16 v[86:89], v[214:217], v[198:201], v[86:89]
	v_mfma_f32_16x16x32_bf16 v[82:85], v[222:225], v[198:201], v[82:85]
	v_mfma_f32_16x16x32_bf16 v[70:73], v[214:217], v[206:209], v[70:73]
	v_mfma_f32_16x16x32_bf16 v[66:69], v[222:225], v[206:209], v[66:69]
	v_mfma_f32_16x16x32_bf16 v[118:121], v[218:221], v[186:189], v[118:121]
	v_mfma_f32_16x16x32_bf16 v[114:117], v[226:229], v[186:189], v[114:117]
	v_mfma_f32_16x16x32_bf16 v[102:105], v[218:221], v[194:197], v[102:105]
	v_mfma_f32_16x16x32_bf16 v[98:101], v[226:229], v[194:197], v[98:101]
	v_mfma_f32_16x16x32_bf16 v[86:89], v[218:221], v[202:205], v[86:89]
	v_mfma_f32_16x16x32_bf16 v[82:85], v[226:229], v[202:205], v[82:85]
	v_mfma_f32_16x16x32_bf16 v[70:73], v[218:221], v[210:213], v[70:73]
	v_mfma_f32_16x16x32_bf16 v[66:69], v[226:229], v[210:213], v[66:69]
	s_mov_b32 m0, s45
	v_lshl_add_u64 v[230:231], v[234:235], 0, s[8:9]
	s_barrier
	ds_read_b128 v[182:185], v175 offset:49152
	ds_read_b128 v[186:189], v175 offset:50176
	ds_read_b128 v[190:193], v175 offset:51200
	ds_read_b128 v[194:197], v175 offset:52224
	ds_read_b128 v[198:201], v175 offset:53248
	ds_read_b128 v[202:205], v175 offset:54272
	ds_read_b128 v[206:209], v175 offset:55296
	ds_read_b128 v[210:213], v175 offset:56320
	global_load_lds_dwordx4 v[230:231], off
	v_lshl_add_u64 v[230:231], v[236:237], 0, s[8:9]
	s_mov_b32 m0, s46
	s_nop 0
	global_load_lds_dwordx4 v[230:231], off
	s_barrier
; #define PG8_BAR __builtin_amdgcn_s_barrier()
; template <class Epi>
; DI void gemm_phase(LAS unsigned char* lds, const Gemm g, const StaticOrder& S, const Epi& E) {
;     ...
;       PG8_BAR; PG8_WAIT_L(0); PG8_MMA(1, 0, At, B0); PG8_BAR; PG8_SCHED;
;       PG8_STAGE(PG8_SB(1, 1), b3 + hstepB, voffB);
;       PG8_WAIT_V(6); PG8_BAR; PG8_MMA(1, 1, At, B1); PG8_BAR;
;     }
;     E(acc, cur, wr, wc, fr, fq);
;   DI void operator()(const f32x4 (&acc)[2][2][4][2], const pg8::Unit& u, int wr, int wc, int fr, int fq) const {
;     ...
;         const int row = u.pm * 256 + ai * 128 + wr * 64 + m * 16 + fr;
;         const int grow = rowbase + row;
;         float rs = 1.f;
;         if (MODE == EP_IN) rs = ((const float*)(ws + OFF_RS0))[grow];
;         if (MODE == EP_UP) rs = ((const float*)(ws + OFF_RS2))[grow];
;         if (MODE == EP_Q || MODE == EP_KV) {
;           const f32x4* sp = (const f32x4*)(ws + OFF_SSQA) + (size_t)grow * 4 + (MODE == EP_KV ? 2 : 0);
;           const f32x4 s0 = sp[0], s1 = sp[1];
;           const float ss = (s0[0] + s0[1]) + (s0[2] + s0[3]) + (s1[0] + s1[1]) + (s1[2] + s1[3]);
;           rs = __builtin_amdgcn_rsqf(ss * (1.0f / 512) + EPS);
;           if (MODE == EP_Q) rs *= QSCALE;
;         }
;         float ssq = 0.f;
; #pragma unroll
;         for (int bj = 0; bj < 2; ++bj) {
;           f32x4 v0 = acc[ai][bj][m][0] * rs, v1 = acc[ai][bj][m][1] * rs;
;           if (MODE == EP_IN || MODE == EP_MIX || MODE == EP_DOWN) {
; #pragma unroll
;             for (int j = 0; j < 4; ++j) ssq += v0[j] * v0[j] + v1[j] * v1[j];
;           }
;           if (MODE == EP_UP) {
; #pragma unroll
;             for (int j = 0; j < 4; ++j) { float a = fmaxf(v0[j], 0.f), b = fmaxf(v1[j], 0.f); v0[j] = a * a; v1[j] = b * b; }
;           }
;           bf16_t* dst;
;           const int ct = bj * 128 + cl;
;           if (MODE == EP_IN) {
;             if (pn < 4) dst = (bf16_t*)(ws + OFF_PROJA) + (size_t)grow * 1024 + pn * 256 + ct;
;             else if (pn < 16) dst = (bf16_t*)(ws + OFF_PROJG) + (size_t)grow * 3072 + (pn - 4) * 256 + ct;
;             else dst = (bf16_t*)(ws + OFF_PROJS) + (size_t)grow * 256 + ct;
;           } else if (MODE == EP_Q) {
;             if (pn < 4) dst = (bf16_t*)(dout + DO_Q) + (size_t)grow * 1536 + (pn * 2 + bj) * 192 + cl;
;             else {
;               const int mm = (pn - 4) * 256 + ct, h = mm >> 6, r = mm & 63;
	s_waitcnt lgkmcnt(0)
	s_waitcnt lgkmcnt(0)
	v_mfma_f32_16x16x32_bf16 v[62:65], v[154:157], v[182:185], v[62:65]
	v_mfma_f32_16x16x32_bf16 v[58:61], v[162:165], v[182:185], v[58:61]
	v_mfma_f32_16x16x32_bf16 v[46:49], v[154:157], v[190:193], v[46:49]
	v_mfma_f32_16x16x32_bf16 v[42:45], v[162:165], v[190:193], v[42:45]
	v_mfma_f32_16x16x32_bf16 v[30:33], v[154:157], v[198:201], v[30:33]
	v_mfma_f32_16x16x32_bf16 v[26:29], v[162:165], v[198:201], v[26:29]
	v_mfma_f32_16x16x32_bf16 v[14:17], v[154:157], v[206:209], v[14:17]
	v_mfma_f32_16x16x32_bf16 v[10:13], v[162:165], v[206:209], v[10:13]
	v_mfma_f32_16x16x32_bf16 v[62:65], v[158:161], v[186:189], v[62:65]
	v_mfma_f32_16x16x32_bf16 v[58:61], v[178:181], v[186:189], v[58:61]
	v_mfma_f32_16x16x32_bf16 v[46:49], v[158:161], v[194:197], v[46:49]
	v_mfma_f32_16x16x32_bf16 v[42:45], v[178:181], v[194:197], v[42:45]
	v_mfma_f32_16x16x32_bf16 v[30:33], v[158:161], v[202:205], v[30:33]
	v_mfma_f32_16x16x32_bf16 v[26:29], v[178:181], v[202:205], v[26:29]
	v_mfma_f32_16x16x32_bf16 v[14:17], v[158:161], v[210:213], v[14:17]
	v_mfma_f32_16x16x32_bf16 v[10:13], v[178:181], v[210:213], v[10:13]
	s_barrier
	s_add_u32 s28, s28, 0x20080
	s_addc_u32 s29, s29, 0
	s_add_i32 s30, s30, s39
	v_lshl_add_u64 v[154:155], s[28:29], 0, v[132:133]
	s_mov_b32 m0, s30
	s_nop 0
	global_load_lds_dwordx4 v[154:155], off
	v_lshl_add_u64 v[154:155], s[28:29], 0, v[136:137]
	s_add_i32 m0, s30, 0x2000
	s_nop 0
	global_load_lds_dwordx4 v[154:155], off
	s_waitcnt vmcnt(6)
	s_barrier
	v_mfma_f32_16x16x32_bf16 v[54:57], v[214:217], v[182:185], v[54:57]
	v_mfma_f32_16x16x32_bf16 v[50:53], v[222:225], v[182:185], v[50:53]
	v_mfma_f32_16x16x32_bf16 v[38:41], v[214:217], v[190:193], v[38:41]
	v_mfma_f32_16x16x32_bf16 v[34:37], v[222:225], v[190:193], v[34:37]
	v_mfma_f32_16x16x32_bf16 v[22:25], v[214:217], v[198:201], v[22:25]
	v_mfma_f32_16x16x32_bf16 v[18:21], v[222:225], v[198:201], v[18:21]
	v_mfma_f32_16x16x32_bf16 v[6:9], v[214:217], v[206:209], v[6:9]
	v_mfma_f32_16x16x32_bf16 v[2:5], v[222:225], v[206:209], v[2:5]
	v_mfma_f32_16x16x32_bf16 v[54:57], v[218:221], v[186:189], v[54:57]
	v_mfma_f32_16x16x32_bf16 v[50:53], v[226:229], v[186:189], v[50:53]
	v_mfma_f32_16x16x32_bf16 v[38:41], v[218:221], v[194:197], v[38:41]
	v_mfma_f32_16x16x32_bf16 v[34:37], v[226:229], v[194:197], v[34:37]
	v_mfma_f32_16x16x32_bf16 v[22:25], v[218:221], v[202:205], v[22:25]
	v_mfma_f32_16x16x32_bf16 v[18:21], v[226:229], v[202:205], v[18:21]
	v_mfma_f32_16x16x32_bf16 v[6:9], v[218:221], v[210:213], v[6:9]
	v_mfma_f32_16x16x32_bf16 v[2:5], v[226:229], v[210:213], v[2:5]
	s_add_i32 s53, s53, 2
	s_add_u32 s26, s26, 0x100
	s_addc_u32 s27, s27, 0
	s_add_u32 s21, s21, 0x100
	s_addc_u32 s33, s33, 0
	s_cmp_gt_u32 s53, 5
	s_barrier
	s_cbranch_scc0 .LBB0_484
	v_lshl_add_u32 v156, s4, 8, v172
	v_ashrrev_i32_e32 v157, 31, v156
	v_lshlrev_b64 v[154:155], 6, v[156:157]
	v_lshl_add_u64 v[154:155], s[10:11], 0, v[154:155]
	global_load_dwordx4 v[160:163], v[154:155], off
	global_load_dwordx4 v[178:181], v[154:155], off offset:16
	v_and_b32_e32 v138, 0xfcf, v156
	v_add_u32_e32 v155, 0xffffc000, v156
	v_cmp_gt_i32_e32 vcc, s44, v156
	s_cmp_gt_i32 s2, 3
	v_readlane_b32 s60, v238, 32
	v_cndmask_b32_e32 v138, v155, v138, vcc
	s_cselect_b64 s[4:5], -1, 0
	s_lshl_b32 s19, s2, 8
	v_mad_i64_i32 v[158:159], s[28:29], v156, s54, 0
	v_readlane_b32 s66, v238, 38
	v_readlane_b32 s67, v238, 39
	s_mov_b64 s[26:27], -1
	v_lshlrev_b32_e32 v154, 1, v142
	s_add_i32 s19, s19, s47
	s_and_b64 vcc, exec, s[4:5]
	v_lshl_add_u64 v[158:159], s[66:67], 0, v[158:159]
	v_readlane_b32 s61, v238, 33
	v_readlane_b32 s62, v238, 34
	v_readlane_b32 s63, v238, 35
	v_readlane_b32 s64, v238, 36
	v_readlane_b32 s65, v238, 37
	s_waitcnt vmcnt(0)
	v_mov_b32_e32 v182, v161
	v_mov_b32_e32 v183, v162
	v_mov_b32_e32 v161, v163
	v_mov_b32_e32 v162, v180
	v_mov_b32_e32 v163, v178
	v_mov_b32_e32 v178, v181
	v_pk_add_f32 v[160:161], v[182:183], v[160:161]
	v_pk_add_f32 v[162:163], v[162:163], v[178:179]
	v_add_f32_e32 v155, v160, v161
	v_add_f32_e32 v155, v155, v163
	v_add_f32_e32 v155, v162, v155
	v_fmamk_f32 v155, v155, 0x3b000000, v177
	v_rsq_f32_e32 v155, v155
	v_lshlrev_b32_e32 v160, 5, v138
	v_ashrrev_i32_e32 v161, 31, v160
	v_lshl_add_u64 v[160:161], v[160:161], 3, v[144:145]
	v_mul_f32_e32 v162, 0x3dd53b94, v155
	v_pk_mul_f32 v[128:129], v[128:129], v[162:163] op_sel_hi:[1,0]
	v_pk_mul_f32 v[126:127], v[126:127], v[162:163] op_sel_hi:[1,0]
	v_pk_mul_f32 v[124:125], v[124:125], v[162:163] op_sel_hi:[1,0]
	v_pk_mul_f32 v[122:123], v[122:123], v[162:163] op_sel_hi:[1,0]
	s_cbranch_vccz .LBB0_487
	global_load_dwordx4 v[178:181], v[160:161], off
	global_load_dwordx4 v[182:185], v[160:161], off offset:16
	s_lshr_b32 s3, s19, 6
	s_mul_i32 s6, s3, 0xc0
	v_mov_b32_e32 v155, v139
	v_lshl_add_u64 v[164:165], s[6:7], 1, v[158:159]
	v_lshl_add_u64 v[164:165], v[164:165], 0, v[154:155]
	s_mov_b64 s[26:27], 0
	v_lshl_add_u64 v[164:165], v[164:165], 0, s[12:13]
	s_waitcnt vmcnt(0)
	v_pk_mul_f32 v[188:189], v[126:127], v[178:179] op_sel:[1,1] op_sel_hi:[0,1]
	v_mul_f32_e32 v138, v129, v181
	v_mul_f32_e32 v190, v128, v181
	v_pk_mul_f32 v[194:195], v[122:123], v[182:183] op_sel:[1,1] op_sel_hi:[0,1]
	v_mul_f32_e32 v196, v125, v185
	v_mul_f32_e32 v198, v124, v185
	v_pk_mul_f32 v[186:187], v[126:127], v[178:179]
	v_pk_mul_f32 v[192:193], v[122:123], v[182:183]
	v_pk_fma_f32 v[126:127], v[126:127], v[178:179], v[188:189] op_sel_hi:[1,0,1]
	v_pk_fma_f32 v[178:179], v[128:129], v[180:181], v[138:139] op_sel_hi:[1,1,0] neg_lo:[0,0,1] neg_hi:[0,0,1]
	v_pk_fma_f32 v[128:129], v[128:129], v[180:181], v[190:191] op_sel:[1,0,0] op_sel_hi:[0,1,0]
	v_pk_fma_f32 v[122:123], v[122:123], v[182:183], v[194:195] op_sel_hi:[1,0,1]
	v_pk_fma_f32 v[180:181], v[124:125], v[184:185], v[196:197] op_sel_hi:[1,1,0] neg_lo:[0,0,1] neg_hi:[0,0,1]
	v_pk_fma_f32 v[124:125], v[124:125], v[184:185], v[198:199] op_sel:[1,0,0] op_sel_hi:[0,1,0]
	v_sub_f32_e32 v122, v192, v194
	v_sub_f32_e32 v126, v186, v188
	v_mov_b32_e32 v129, v128
	v_mov_b32_e32 v128, v178
	v_mov_b32_e32 v125, v124
	v_mov_b32_e32 v124, v180

; #define PG8_STAGE(bufoff, gbase, voff) do { _Pragma("unroll") for (int _i = 0; _i < 2; ++_i) \
;     __builtin_amdgcn_global_load_lds((const unsigned*)((const char*)(gbase) + (voff)[_i]), (LAS unsigned*)(lds + (bufoff) + ldsw + _i * 8192), 16, 0, 0); } while (0)
; #define PG8_LDA(dst, b, h) do { _Pragma("unroll") for (int m = 0; m < 4; ++m) _Pragma("unroll") for (int k = 0; k < 2; ++k) dst[m][k] = *(const LAS bf16x8*)(lds + PG8_SA(b, h) + aoff + m * 2048 + k * 1024); } while (0)
; #define PG8_LDB(dst, b, h) do { _Pragma("unroll") for (int n = 0; n < 2; ++n) _Pragma("unroll") for (int k = 0; k < 2; ++k) dst[n][k] = *(const LAS bf16x8*)(lds + PG8_SB(b, h) + boff + n * 2048 + k * 1024); } while (0)
; #define PG8_MMA(ai, bj, At, Bt) do { __builtin_amdgcn_s_setprio(1); _Pragma("unroll") for (int m = 0; m < 4; ++m) _Pragma("unroll") for (int n = 0; n < 2; ++n) _Pragma("unroll") for (int k = 0; k < 2; ++k) \
;     acc[ai][bj][m][n] = __builtin_amdgcn_mfma_f32_16x16x32_bf16(Bt[n][k], At[m][k], acc[ai][bj][m][n], 0, 0, 0); __builtin_amdgcn_s_setprio(0); } while (0)
; #define PG8_WAIT_V(n) asm volatile("s_waitcnt vmcnt(" #n ")" ::: "memory")
; #define PG8_WAIT_L(n) asm volatile("s_waitcnt lgkmcnt(" #n ")" ::: "memory")
; #define PG8_BAR __builtin_amdgcn_s_barrier()
; #define PG8_SCHED __builtin_amdgcn_sched_barrier(0)
; template <class Epi>
; DI void gemm_phase(LAS unsigned char* lds, const Gemm g, const StaticOrder& S, const Epi& E) {
;     ...
;       PG8_LDB(B0, 0, 0); PG8_SCHED; PG8_LDA(At, 0, 0); PG8_STAGE(PG8_SA(1, 1), a1 + hstepA, voffA);
;       PG8_WAIT_L(8); PG8_BAR; PG8_WAIT_L(0); PG8_MMA(0, 0, At, B0); PG8_BAR; PG8_SCHED;
;       PG8_LDB(B1, 0, 1); PG8_STAGE(PG8_SB(0, 0), b2, voffB);
;       PG8_BAR; PG8_WAIT_L(0); PG8_MMA(0, 1, At, B1); PG8_BAR;
;       PG8_LDA(At, 0, 1); PG8_STAGE(PG8_SA(0, 0), a2, voffA);
;       PG8_BAR; PG8_WAIT_L(0); PG8_MMA(1, 0, At, B0); PG8_BAR; PG8_SCHED;
;       PG8_STAGE(PG8_SB(0, 1), b2 + hstepB, voffB);
;       PG8_WAIT_V(6); PG8_BAR; PG8_MMA(1, 1, At, B1); PG8_BAR;
.LBB0_567:
	ds_read_b128 v[156:159], v1
	ds_read_b128 v[160:163], v1 offset:1024
	ds_read_b128 v[164:167], v1 offset:2048
	ds_read_b128 v[168:171], v1 offset:3072
	s_add_u32 s20, s18, 0xfffc0080
	s_addc_u32 s21, s19, -1
	s_cmp_eq_u32 s47, 4
	s_cselect_b32 s23, s11, s21
	s_cselect_b32 s22, s43, s20
	s_cselect_b32 s21, s9, s46
	s_cselect_b32 s20, s44, s45
	v_lshl_add_u64 v[148:149], s[18:19], 0, v[140:141]
	s_add_i32 m0, s17, 0xc000
	ds_read_b128 v[172:175], v152
	ds_read_b128 v[176:179], v152 offset:1024
	ds_read_b128 v[180:183], v152 offset:2048
	ds_read_b128 v[184:187], v152 offset:3072
	ds_read_b128 v[188:191], v152 offset:4096
	ds_read_b128 v[192:195], v152 offset:5120
	ds_read_b128 v[196:199], v152 offset:6144
	ds_read_b128 v[200:203], v152 offset:7168
	global_load_lds_dwordx4 v[148:149], off
	v_lshl_add_u64 v[148:149], s[18:19], 0, v[142:143]
	s_add_i32 m0, s17, 0xe000
	s_nop 0
	global_load_lds_dwordx4 v[148:149], off
	s_waitcnt lgkmcnt(8)
	s_barrier
	s_waitcnt lgkmcnt(0)
	s_waitcnt lgkmcnt(0)
	v_mfma_f32_16x16x32_bf16 v[126:129], v[156:159], v[172:175], v[126:129]
	v_mfma_f32_16x16x32_bf16 v[122:125], v[164:167], v[172:175], v[122:125]
	v_mfma_f32_16x16x32_bf16 v[110:113], v[156:159], v[180:183], v[110:113]
	v_mfma_f32_16x16x32_bf16 v[106:109], v[164:167], v[180:183], v[106:109]
	v_mfma_f32_16x16x32_bf16 v[94:97], v[156:159], v[188:191], v[94:97]
	v_mfma_f32_16x16x32_bf16 v[90:93], v[164:167], v[188:191], v[90:93]
	v_mfma_f32_16x16x32_bf16 v[78:81], v[156:159], v[196:199], v[78:81]
	v_mfma_f32_16x16x32_bf16 v[74:77], v[164:167], v[196:199], v[74:77]
	v_mfma_f32_16x16x32_bf16 v[126:129], v[160:163], v[176:179], v[126:129]
	v_mfma_f32_16x16x32_bf16 v[122:125], v[168:171], v[176:179], v[122:125]
	v_mfma_f32_16x16x32_bf16 v[110:113], v[160:163], v[184:187], v[110:113]
	v_mfma_f32_16x16x32_bf16 v[106:109], v[168:171], v[184:187], v[106:109]
	v_mfma_f32_16x16x32_bf16 v[94:97], v[160:163], v[192:195], v[94:97]
	v_mfma_f32_16x16x32_bf16 v[90:93], v[168:171], v[192:195], v[90:93]
	v_mfma_f32_16x16x32_bf16 v[78:81], v[160:163], v[200:203], v[78:81]
	v_mfma_f32_16x16x32_bf16 v[74:77], v[168:171], v[200:203], v[74:77]
	s_barrier
	s_add_i32 s48, s39, s30
	v_lshl_add_u64 v[148:149], s[20:21], 0, v[132:133]
	s_mov_b32 m0, s48
	ds_read_b128 v[204:207], v153
	ds_read_b128 v[208:211], v153 offset:1024
	ds_read_b128 v[212:215], v153 offset:2048
	ds_read_b128 v[216:219], v153 offset:3072
	global_load_lds_dwordx4 v[148:149], off
	v_lshl_add_u64 v[220:221], s[20:21], 0, v[136:137]
	s_add_i32 m0, s48, 0x2000
	s_nop 0
	global_load_lds_dwordx4 v[220:221], off
	s_barrier
	s_waitcnt lgkmcnt(0)
	s_waitcnt lgkmcnt(0)
	v_mfma_f32_16x16x32_bf16 v[118:121], v[204:207], v[172:175], v[118:121]
	v_mfma_f32_16x16x32_bf16 v[114:117], v[212:215], v[172:175], v[114:117]
	v_mfma_f32_16x16x32_bf16 v[102:105], v[204:207], v[180:183], v[102:105]
	v_mfma_f32_16x16x32_bf16 v[98:101], v[212:215], v[180:183], v[98:101]
	v_mfma_f32_16x16x32_bf16 v[86:89], v[204:207], v[188:191], v[86:89]
	v_mfma_f32_16x16x32_bf16 v[82:85], v[212:215], v[188:191], v[82:85]
	v_mfma_f32_16x16x32_bf16 v[70:73], v[204:207], v[196:199], v[70:73]
	v_mfma_f32_16x16x32_bf16 v[66:69], v[212:215], v[196:199], v[66:69]
	v_mfma_f32_16x16x32_bf16 v[118:121], v[208:211], v[176:179], v[118:121]
	v_mfma_f32_16x16x32_bf16 v[114:117], v[216:219], v[176:179], v[114:117]
	v_mfma_f32_16x16x32_bf16 v[102:105], v[208:211], v[184:187], v[102:105]
	v_mfma_f32_16x16x32_bf16 v[98:101], v[216:219], v[184:187], v[98:101]
	v_mfma_f32_16x16x32_bf16 v[86:89], v[208:211], v[192:195], v[86:89]
	v_mfma_f32_16x16x32_bf16 v[82:85], v[216:219], v[192:195], v[82:85]
	v_mfma_f32_16x16x32_bf16 v[70:73], v[208:211], v[200:203], v[70:73]
	v_mfma_f32_16x16x32_bf16 v[66:69], v[216:219], v[200:203], v[66:69]
	s_mov_b32 m0, s17
	v_lshl_add_u64 v[222:223], s[22:23], 0, v[130:131]
	s_barrier
	ds_read_b128 v[172:175], v152 offset:16384
	ds_read_b128 v[176:179], v152 offset:17408
	ds_read_b128 v[180:183], v152 offset:18432
	ds_read_b128 v[184:187], v152 offset:19456
	ds_read_b128 v[188:191], v152 offset:20480
	ds_read_b128 v[192:195], v152 offset:21504
	ds_read_b128 v[196:199], v152 offset:22528
	ds_read_b128 v[200:203], v152 offset:23552
	global_load_lds_dwordx4 v[222:223], off
	v_lshl_add_u64 v[224:225], s[22:23], 0, v[134:135]
	s_mov_b32 m0, s31
	s_nop 0
	global_load_lds_dwordx4 v[224:225], off
	s_barrier
	s_waitcnt lgkmcnt(0)
	s_waitcnt lgkmcnt(0)
	v_mfma_f32_16x16x32_bf16 v[62:65], v[156:159], v[172:175], v[62:65]
	v_mfma_f32_16x16x32_bf16 v[58:61], v[164:167], v[172:175], v[58:61]
	v_mfma_f32_16x16x32_bf16 v[46:49], v[156:159], v[180:183], v[46:49]
	v_mfma_f32_16x16x32_bf16 v[42:45], v[164:167], v[180:183], v[42:45]
	v_mfma_f32_16x16x32_bf16 v[30:33], v[156:159], v[188:191], v[30:33]
	v_mfma_f32_16x16x32_bf16 v[26:29], v[164:167], v[188:191], v[26:29]
	v_mfma_f32_16x16x32_bf16 v[14:17], v[156:159], v[196:199], v[14:17]
	v_mfma_f32_16x16x32_bf16 v[10:13], v[164:167], v[196:199], v[10:13]
	v_mfma_f32_16x16x32_bf16 v[62:65], v[160:163], v[176:179], v[62:65]
	v_mfma_f32_16x16x32_bf16 v[58:61], v[168:171], v[176:179], v[58:61]
	v_mfma_f32_16x16x32_bf16 v[46:49], v[160:163], v[184:187], v[46:49]
	v_mfma_f32_16x16x32_bf16 v[42:45], v[168:171], v[184:187], v[42:45]
	v_mfma_f32_16x16x32_bf16 v[30:33], v[160:163], v[192:195], v[30:33]
	v_mfma_f32_16x16x32_bf16 v[26:29], v[168:171], v[192:195], v[26:29]
	v_mfma_f32_16x16x32_bf16 v[14:17], v[160:163], v[200:203], v[14:17]
	v_mfma_f32_16x16x32_bf16 v[10:13], v[168:171], v[200:203], v[10:13]
	s_barrier
; #define PG8_STAGE(bufoff, gbase, voff) do { _Pragma("unroll") for (int _i = 0; _i < 2; ++_i) \
;     __builtin_amdgcn_global_load_lds((const unsigned*)((const char*)(gbase) + (voff)[_i]), (LAS unsigned*)(lds + (bufoff) + ldsw + _i * 8192), 16, 0, 0); } while (0)
; #define PG8_LDA(dst, b, h) do { _Pragma("unroll") for (int m = 0; m < 4; ++m) _Pragma("unroll") for (int k = 0; k < 2; ++k) dst[m][k] = *(const LAS bf16x8*)(lds + PG8_SA(b, h) + aoff + m * 2048 + k * 1024); } while (0)
; #define PG8_LDB(dst, b, h) do { _Pragma("unroll") for (int n = 0; n < 2; ++n) _Pragma("unroll") for (int k = 0; k < 2; ++k) dst[n][k] = *(const LAS bf16x8*)(lds + PG8_SB(b, h) + boff + n * 2048 + k * 1024); } while (0)
; #define PG8_MMA(ai, bj, At, Bt) do { __builtin_amdgcn_s_setprio(1); _Pragma("unroll") for (int m = 0; m < 4; ++m) _Pragma("unroll") for (int n = 0; n < 2; ++n) _Pragma("unroll") for (int k = 0; k < 2; ++k) \
;     acc[ai][bj][m][n] = __builtin_amdgcn_mfma_f32_16x16x32_bf16(Bt[n][k], At[m][k], acc[ai][bj][m][n], 0, 0, 0); __builtin_amdgcn_s_setprio(0); } while (0)
; #define PG8_WAIT_V(n) asm volatile("s_waitcnt vmcnt(" #n ")" ::: "memory")
; #define PG8_WAIT_L(n) asm volatile("s_waitcnt lgkmcnt(" #n ")" ::: "memory")
; #define PG8_BAR __builtin_amdgcn_s_barrier()
; #define PG8_SCHED __builtin_amdgcn_sched_barrier(0)
; template <class Epi>
; DI void gemm_phase(LAS unsigned char* lds, const Gemm g, const StaticOrder& S, const Epi& E) {
;     ...
;       PG8_WAIT_V(6); PG8_BAR; PG8_MMA(1, 1, At, B1); PG8_BAR;
;       PG8_LDB(B0, 1, 0); PG8_SCHED; PG8_LDA(At, 1, 0); PG8_STAGE(PG8_SA(0, 1), a2 + hstepA, voffA);
;       PG8_WAIT_L(8); PG8_BAR; PG8_WAIT_L(0); PG8_MMA(0, 0, At, B0); PG8_BAR; PG8_SCHED;
;       PG8_LDB(B1, 1, 1); PG8_STAGE(PG8_SB(1, 0), b3, voffB);
;       PG8_BAR; PG8_WAIT_L(0); PG8_MMA(0, 1, At, B1); PG8_BAR;
;       PG8_LDA(At, 1, 1); PG8_STAGE(PG8_SA(1, 0), a3, voffA);
;       PG8_BAR; PG8_WAIT_L(0); PG8_MMA(1, 0, At, B0); PG8_BAR; PG8_SCHED;
	s_add_u32 s48, s20, 0x20000
	s_addc_u32 s49, s21, 0
	s_add_i32 s50, s40, s30
	v_lshl_add_u64 v[156:157], s[48:49], 0, v[132:133]
	s_mov_b32 m0, s50
	s_nop 0
	global_load_lds_dwordx4 v[156:157], off
	v_lshl_add_u64 v[156:157], s[48:49], 0, v[136:137]
	s_add_i32 m0, s50, 0x2000
	s_nop 0
	global_load_lds_dwordx4 v[156:157], off
	s_waitcnt vmcnt(6)
	s_barrier
	v_mfma_f32_16x16x32_bf16 v[54:57], v[204:207], v[172:175], v[54:57]
	v_mfma_f32_16x16x32_bf16 v[50:53], v[212:215], v[172:175], v[50:53]
	v_mfma_f32_16x16x32_bf16 v[38:41], v[204:207], v[180:183], v[38:41]
	v_mfma_f32_16x16x32_bf16 v[34:37], v[212:215], v[180:183], v[34:37]
	v_mfma_f32_16x16x32_bf16 v[22:25], v[204:207], v[188:191], v[22:25]
	v_mfma_f32_16x16x32_bf16 v[18:21], v[212:215], v[188:191], v[18:21]
	v_mfma_f32_16x16x32_bf16 v[6:9], v[204:207], v[196:199], v[6:9]
	v_mfma_f32_16x16x32_bf16 v[2:5], v[212:215], v[196:199], v[2:5]
	v_mfma_f32_16x16x32_bf16 v[54:57], v[208:211], v[176:179], v[54:57]
	v_mfma_f32_16x16x32_bf16 v[50:53], v[216:219], v[176:179], v[50:53]
	v_mfma_f32_16x16x32_bf16 v[38:41], v[208:211], v[184:187], v[38:41]
	v_mfma_f32_16x16x32_bf16 v[34:37], v[216:219], v[184:187], v[34:37]
	v_mfma_f32_16x16x32_bf16 v[22:25], v[208:211], v[192:195], v[22:25]
	v_mfma_f32_16x16x32_bf16 v[18:21], v[216:219], v[192:195], v[18:21]
	v_mfma_f32_16x16x32_bf16 v[6:9], v[208:211], v[200:203], v[6:9]
	v_mfma_f32_16x16x32_bf16 v[2:5], v[216:219], v[200:203], v[2:5]
	s_add_i32 s48, 0, 0x18000
	v_add_u32_e32 v155, s48, v151
	s_barrier
	ds_read_b128 v[156:159], v155
	ds_read_b128 v[160:163], v155 offset:1024
	ds_read_b128 v[164:167], v155 offset:2048
	ds_read_b128 v[168:171], v155 offset:3072
	s_add_u32 s22, s22, 0x40000
	s_addc_u32 s23, s23, 0
	s_mov_b32 m0, s33
	v_lshl_add_u64 v[204:205], s[22:23], 0, v[130:131]
	ds_read_b128 v[172:175], v152 offset:32768
	ds_read_b128 v[176:179], v152 offset:33792
	ds_read_b128 v[180:183], v152 offset:34816
	ds_read_b128 v[184:187], v152 offset:35840
	ds_read_b128 v[188:191], v152 offset:36864
	ds_read_b128 v[192:195], v152 offset:37888
	ds_read_b128 v[196:199], v152 offset:38912
	ds_read_b128 v[200:203], v152 offset:39936
	global_load_lds_dwordx4 v[204:205], off
	v_lshl_add_u64 v[204:205], s[22:23], 0, v[134:135]
	s_mov_b32 m0, s34
	s_nop 0
	global_load_lds_dwordx4 v[204:205], off
	s_waitcnt lgkmcnt(8)
	s_barrier
	s_waitcnt lgkmcnt(0)
	s_waitcnt lgkmcnt(0)
	v_mfma_f32_16x16x32_bf16 v[126:129], v[156:159], v[172:175], v[126:129]
	v_mfma_f32_16x16x32_bf16 v[122:125], v[164:167], v[172:175], v[122:125]
	v_mfma_f32_16x16x32_bf16 v[110:113], v[156:159], v[180:183], v[110:113]
	v_mfma_f32_16x16x32_bf16 v[106:109], v[164:167], v[180:183], v[106:109]
	v_mfma_f32_16x16x32_bf16 v[94:97], v[156:159], v[188:191], v[94:97]
	v_mfma_f32_16x16x32_bf16 v[90:93], v[164:167], v[188:191], v[90:93]
	v_mfma_f32_16x16x32_bf16 v[78:81], v[156:159], v[196:199], v[78:81]
	v_mfma_f32_16x16x32_bf16 v[74:77], v[164:167], v[196:199], v[74:77]
	v_mfma_f32_16x16x32_bf16 v[126:129], v[160:163], v[176:179], v[126:129]
	v_mfma_f32_16x16x32_bf16 v[122:125], v[168:171], v[176:179], v[122:125]
	v_mfma_f32_16x16x32_bf16 v[110:113], v[160:163], v[184:187], v[110:113]
	v_mfma_f32_16x16x32_bf16 v[106:109], v[168:171], v[184:187], v[106:109]
	v_mfma_f32_16x16x32_bf16 v[94:97], v[160:163], v[192:195], v[94:97]
	v_mfma_f32_16x16x32_bf16 v[90:93], v[168:171], v[192:195], v[90:93]
	v_mfma_f32_16x16x32_bf16 v[78:81], v[160:163], v[200:203], v[78:81]
	v_mfma_f32_16x16x32_bf16 v[74:77], v[168:171], v[200:203], v[74:77]
	s_barrier
	s_add_i32 s22, 0, 0x1c000
	s_add_i32 s23, s48, s30
	v_add_u32_e32 v155, s22, v151
	v_lshl_add_u64 v[148:149], v[148:149], 0, s[2:3]
	s_mov_b32 m0, s23
	ds_read_b128 v[204:207], v155
	ds_read_b128 v[208:211], v155 offset:1024
	ds_read_b128 v[212:215], v155 offset:2048
	ds_read_b128 v[216:219], v155 offset:3072
	global_load_lds_dwordx4 v[148:149], off
	v_lshl_add_u64 v[148:149], v[220:221], 0, s[2:3]
	s_add_i32 m0, s23, 0x2000
	s_nop 0
	global_load_lds_dwordx4 v[148:149], off
	s_barrier
	s_waitcnt lgkmcnt(0)
	s_waitcnt lgkmcnt(0)
	v_mfma_f32_16x16x32_bf16 v[118:121], v[204:207], v[172:175], v[118:121]
	v_mfma_f32_16x16x32_bf16 v[114:117], v[212:215], v[172:175], v[114:117]
	v_mfma_f32_16x16x32_bf16 v[102:105], v[204:207], v[180:183], v[102:105]
	v_mfma_f32_16x16x32_bf16 v[98:101], v[212:215], v[180:183], v[98:101]
	v_mfma_f32_16x16x32_bf16 v[86:89], v[204:207], v[188:191], v[86:89]
	v_mfma_f32_16x16x32_bf16 v[82:85], v[212:215], v[188:191], v[82:85]
	v_mfma_f32_16x16x32_bf16 v[70:73], v[204:207], v[196:199], v[70:73]
	v_mfma_f32_16x16x32_bf16 v[66:69], v[212:215], v[196:199], v[66:69]
	v_mfma_f32_16x16x32_bf16 v[118:121], v[208:211], v[176:179], v[118:121]
	v_mfma_f32_16x16x32_bf16 v[114:117], v[216:219], v[176:179], v[114:117]
	v_mfma_f32_16x16x32_bf16 v[102:105], v[208:211], v[184:187], v[102:105]
	v_mfma_f32_16x16x32_bf16 v[98:101], v[216:219], v[184:187], v[98:101]
	v_mfma_f32_16x16x32_bf16 v[86:89], v[208:211], v[192:195], v[86:89]
	v_mfma_f32_16x16x32_bf16 v[82:85], v[216:219], v[192:195], v[82:85]
	v_mfma_f32_16x16x32_bf16 v[70:73], v[208:211], v[200:203], v[70:73]
	v_mfma_f32_16x16x32_bf16 v[66:69], v[216:219], v[200:203], v[66:69]
	s_mov_b32 m0, s36
	v_lshl_add_u64 v[148:149], v[222:223], 0, s[2:3]
	s_barrier
	ds_read_b128 v[172:175], v152 offset:49152
	ds_read_b128 v[176:179], v152 offset:50176
	ds_read_b128 v[180:183], v152 offset:51200
	ds_read_b128 v[184:187], v152 offset:52224
	ds_read_b128 v[188:191], v152 offset:53248
	ds_read_b128 v[192:195], v152 offset:54272
	ds_read_b128 v[196:199], v152 offset:55296
	ds_read_b128 v[200:203], v152 offset:56320
	global_load_lds_dwordx4 v[148:149], off
	v_lshl_add_u64 v[148:149], v[224:225], 0, s[2:3]
	s_mov_b32 m0, s37
	s_nop 0
	global_load_lds_dwordx4 v[148:149], off
	s_barrier
; template <class Epi>
; DI void gemm_phase(LAS unsigned char* lds, const Gemm g, const StaticOrder& S, const Epi& E) {
;     ...
;       PG8_BAR; PG8_WAIT_L(0); PG8_MMA(0, 1, At, B1); PG8_BAR;
;       PG8_LDA(At, 1, 1); PG8_STAGE(PG8_SA(1, 0), a3, voffA);
;       PG8_BAR; PG8_WAIT_L(0); PG8_MMA(1, 0, At, B0); PG8_BAR; PG8_SCHED;
;       PG8_STAGE(PG8_SB(1, 1), b3 + hstepB, voffB);
;       PG8_WAIT_V(6); PG8_BAR; PG8_MMA(1, 1, At, B1); PG8_BAR;
;   DI void operator()(const f32x4 (&acc)[2][2][4][2], const pg8::Unit& u, int wr, int wc, int fr, int fq) const {
;     ...
;         if (MODE == EP_IN) rs = ((const float*)(ws + OFF_RS0))[grow];
;         if (MODE == EP_UP) rs = ((const float*)(ws + OFF_RS2))[grow];
;         if (MODE == EP_Q || MODE == EP_KV) {
;           const f32x4* sp = (const f32x4*)(ws + OFF_SSQA) + (size_t)grow * 4 + (MODE == EP_KV ? 2 : 0);
;           const f32x4 s0 = sp[0], s1 = sp[1];
;           const float ss = (s0[0] + s0[1]) + (s0[2] + s0[3]) + (s1[0] + s1[1]) + (s1[2] + s1[3]);
;           rs = __builtin_amdgcn_rsqf(ss * (1.0f / 512) + EPS);
;           if (MODE == EP_Q) rs *= QSCALE;
;         }
;         float ssq = 0.f;
; #pragma unroll
;         for (int bj = 0; bj < 2; ++bj) {
;           f32x4 v0 = acc[ai][bj][m][0] * rs, v1 = acc[ai][bj][m][1] * rs;
;           if (MODE == EP_IN || MODE == EP_MIX || MODE == EP_DOWN) {
; #pragma unroll
;             for (int j = 0; j < 4; ++j) ssq += v0[j] * v0[j] + v1[j] * v1[j];
;           }
;           if (MODE == EP_UP) {
; #pragma unroll
;             for (int j = 0; j < 4; ++j) { float a = fmaxf(v0[j], 0.f), b = fmaxf(v1[j], 0.f); v0[j] = a * a; v1[j] = b * b; }
;           }
;           bf16_t* dst;
;           const int ct = bj * 128 + cl;
;           if (MODE == EP_IN) {
;             if (pn < 4) dst = (bf16_t*)(ws + OFF_PROJA) + (size_t)grow * 1024 + pn * 256 + ct;
;             else if (pn < 16) dst = (bf16_t*)(ws + OFF_PROJG) + (size_t)grow * 3072 + (pn - 4) * 256 + ct;
;             else dst = (bf16_t*)(ws + OFF_PROJS) + (size_t)grow * 256 + ct;
;           } else if (MODE == EP_Q) {
;             if (pn < 4) dst = (bf16_t*)(dout + DO_Q) + (size_t)grow * 1536 + (pn * 2 + bj) * 192 + cl;
;             else {
;               const int mm = (pn - 4) * 256 + ct, h = mm >> 6, r = mm & 63;
;               dst = (bf16_t*)(dout + DO_Q) + (size_t)grow * 1536 + h * 192 + 128 + r;
	s_waitcnt lgkmcnt(0)
	s_waitcnt lgkmcnt(0)
	v_mfma_f32_16x16x32_bf16 v[62:65], v[156:159], v[172:175], v[62:65]
	v_mfma_f32_16x16x32_bf16 v[58:61], v[164:167], v[172:175], v[58:61]
	v_mfma_f32_16x16x32_bf16 v[46:49], v[156:159], v[180:183], v[46:49]
	v_mfma_f32_16x16x32_bf16 v[42:45], v[164:167], v[180:183], v[42:45]
	v_mfma_f32_16x16x32_bf16 v[30:33], v[156:159], v[188:191], v[30:33]
	v_mfma_f32_16x16x32_bf16 v[26:29], v[164:167], v[188:191], v[26:29]
	v_mfma_f32_16x16x32_bf16 v[14:17], v[156:159], v[196:199], v[14:17]
	v_mfma_f32_16x16x32_bf16 v[10:13], v[164:167], v[196:199], v[10:13]
	v_mfma_f32_16x16x32_bf16 v[62:65], v[160:163], v[176:179], v[62:65]
	v_mfma_f32_16x16x32_bf16 v[58:61], v[168:171], v[176:179], v[58:61]
	v_mfma_f32_16x16x32_bf16 v[46:49], v[160:163], v[184:187], v[46:49]
	v_mfma_f32_16x16x32_bf16 v[42:45], v[168:171], v[184:187], v[42:45]
	v_mfma_f32_16x16x32_bf16 v[30:33], v[160:163], v[192:195], v[30:33]
	v_mfma_f32_16x16x32_bf16 v[26:29], v[168:171], v[192:195], v[26:29]
	v_mfma_f32_16x16x32_bf16 v[14:17], v[160:163], v[200:203], v[14:17]
	v_mfma_f32_16x16x32_bf16 v[10:13], v[168:171], v[200:203], v[10:13]
	s_barrier
	s_add_u32 s20, s20, 0x20080
	s_addc_u32 s21, s21, 0
	s_add_i32 s22, s22, s30
	v_lshl_add_u64 v[148:149], s[20:21], 0, v[132:133]
	s_mov_b32 m0, s22
	s_nop 0
	global_load_lds_dwordx4 v[148:149], off
	v_lshl_add_u64 v[148:149], s[20:21], 0, v[136:137]
	s_add_i32 m0, s22, 0x2000
	s_nop 0
	global_load_lds_dwordx4 v[148:149], off
	s_waitcnt vmcnt(6)
	s_barrier
	v_mfma_f32_16x16x32_bf16 v[54:57], v[204:207], v[172:175], v[54:57]
	v_mfma_f32_16x16x32_bf16 v[50:53], v[212:215], v[172:175], v[50:53]
	v_mfma_f32_16x16x32_bf16 v[38:41], v[204:207], v[180:183], v[38:41]
	v_mfma_f32_16x16x32_bf16 v[34:37], v[212:215], v[180:183], v[34:37]
	v_mfma_f32_16x16x32_bf16 v[22:25], v[204:207], v[188:191], v[22:25]
	v_mfma_f32_16x16x32_bf16 v[18:21], v[212:215], v[188:191], v[18:21]
	v_mfma_f32_16x16x32_bf16 v[6:9], v[204:207], v[196:199], v[6:9]
	v_mfma_f32_16x16x32_bf16 v[2:5], v[212:215], v[196:199], v[2:5]
	v_mfma_f32_16x16x32_bf16 v[54:57], v[208:211], v[176:179], v[54:57]
	v_mfma_f32_16x16x32_bf16 v[50:53], v[216:219], v[176:179], v[50:53]
	v_mfma_f32_16x16x32_bf16 v[38:41], v[208:211], v[184:187], v[38:41]
	v_mfma_f32_16x16x32_bf16 v[34:37], v[216:219], v[184:187], v[34:37]
	v_mfma_f32_16x16x32_bf16 v[22:25], v[208:211], v[192:195], v[22:25]
	v_mfma_f32_16x16x32_bf16 v[18:21], v[216:219], v[192:195], v[18:21]
	v_mfma_f32_16x16x32_bf16 v[6:9], v[208:211], v[200:203], v[6:9]
	v_mfma_f32_16x16x32_bf16 v[2:5], v[216:219], v[200:203], v[2:5]
	s_add_i32 s47, s47, 2
	s_add_u32 s18, s18, 0x100
	s_addc_u32 s19, s19, 0
	s_add_u32 s45, s45, 0x100
	s_addc_u32 s46, s46, 0
	s_cmp_gt_u32 s47, 5
	s_barrier
	s_cbranch_scc0 .LBB0_567
	v_lshl_add_u32 v148, s16, 8, v150
	v_ashrrev_i32_e32 v149, 31, v148
	v_lshlrev_b64 v[156:157], 6, v[148:149]
	v_lshl_add_u64 v[160:161], s[84:85], 0, v[156:157]
	v_add_co_u32_e32 v156, vcc, 0x5e00000, v160
	v_lshlrev_b64 v[166:167], 12, v[148:149]
	s_nop 0
	v_addc_co_u32_e32 v157, vcc, 0, v161, vcc
	global_load_dwordx4 v[156:159], v[156:157], off offset:32
	v_lshl_add_u64 v[160:161], v[160:161], 0, s[6:7]
	global_load_dwordx4 v[160:163], v[160:161], off offset:16
	s_lshl_b32 s18, s42, 8
	v_or_b32_e32 v164, 16, v148
	s_ashr_i32 s19, s18, 31
	v_ashrrev_i32_e32 v165, 31, v164
	s_lshl_b64 s[18:19], s[18:19], 1
	v_lshl_add_u64 v[166:167], s[4:5], 0, v[166:167]
	v_lshlrev_b64 v[168:169], 6, v[164:165]
	v_lshl_add_u64 v[166:167], v[166:167], 0, s[18:19]
	v_lshl_add_u64 v[168:169], s[84:85], 0, v[168:169]
	v_lshl_add_u64 v[166:167], v[166:167], 0, v[138:139]
	s_mov_b32 s42, s8
	s_mov_b32 s16, s10
	s_mov_b64 s[20:21], s[14:15]
	s_mov_b64 s[22:23], s[12:13]
	s_waitcnt vmcnt(0)
	v_mov_b32_e32 v170, v157
	v_mov_b32_e32 v171, v158
	v_mov_b32_e32 v157, v159
	v_mov_b32_e32 v158, v162
	v_mov_b32_e32 v159, v160
	v_mov_b32_e32 v160, v163
	v_pk_add_f32 v[156:157], v[170:171], v[156:157]
	v_pk_add_f32 v[158:159], v[158:159], v[160:161]
	v_add_f32_e32 v149, v156, v157
	v_add_f32_e32 v149, v149, v159
	v_add_f32_e32 v149, v158, v149
	v_fmamk_f32 v149, v149, 0x3b000000, v154
	v_rsq_f32_e32 v156, v149
	v_add_co_u32_e32 v158, vcc, s41, v168
	v_pk_mul_f32 v[128:129], v[128:129], v[156:157] op_sel_hi:[1,0]
	v_pk_mul_f32 v[126:127], v[126:127], v[156:157] op_sel_hi:[1,0]
	v_pk_mul_f32 v[124:125], v[124:125], v[156:157] op_sel_hi:[1,0]
	v_pk_mul_f32 v[122:123], v[122:123], v[156:157] op_sel_hi:[1,0]
	v_pk_mul_f32 v[120:121], v[120:121], v[156:157] op_sel_hi:[1,0]
	v_pk_mul_f32 v[118:119], v[118:119], v[156:157] op_sel_hi:[1,0]
	v_pk_mul_f32 v[160:161], v[116:117], v[156:157] op_sel_hi:[1,0]
	v_pk_mul_f32 v[156:157], v[114:115], v[156:157] op_sel_hi:[1,0]
	v_cvt_pk_bf16_f32 v114, v126, v127
	v_cvt_pk_bf16_f32 v115, v128, v129
	v_cvt_pk_bf16_f32 v116, v122, v123
	v_cvt_pk_bf16_f32 v117, v124, v125
	v_addc_co_u32_e32 v159, vcc, 0, v169, vcc
	v_cvt_pk_bf16_f32 v118, v118, v119
	v_cvt_pk_bf16_f32 v119, v120, v121
	v_cvt_pk_bf16_f32 v120, v156, v157
	v_cvt_pk_bf16_f32 v121, v160, v161
	global_store_dwordx4 v[166:167], v[114:117], off
	global_store_dwordx4 v[166:167], v[118:121], off offset:256
	global_load_dwordx4 v[114:117], v[158:159], off offset:32
	v_or_b32_e32 v122, 32, v148
	v_lshl_add_u64 v[118:119], v[168:169], 0, s[6:7]
	global_load_dwordx4 v[118:121], v[118:119], off offset:16
	v_ashrrev_i32_e32 v123, 31, v122
	v_lshlrev_b64 v[124:125], 12, v[164:165]
	v_lshlrev_b64 v[126:127], 6, v[122:123]
	v_lshl_add_u64 v[124:125], s[4:5], 0, v[124:125]
	v_lshl_add_u64 v[126:127], s[84:85], 0, v[126:127]
	v_lshl_add_u64 v[124:125], v[124:125], 0, s[18:19]
	s_waitcnt vmcnt(0)
;   DI void operator()(const f32x4 (&acc)[2][2][4][2], const pg8::Unit& u, int wr, int wc, int fr, int fq) const {
;     ...
;         const int row = u.pm * 256 + ai * 128 + wr * 64 + m * 16 + fr;
;         const int grow = rowbase + row;
;         float rs = 1.f;
;         if (MODE == EP_IN) rs = ((const float*)(ws + OFF_RS0))[grow];
;         if (MODE == EP_UP) rs = ((const float*)(ws + OFF_RS2))[grow];
;         if (MODE == EP_Q || MODE == EP_KV) {
;           const f32x4* sp = (const f32x4*)(ws + OFF_SSQA) + (size_t)grow * 4 + (MODE == EP_KV ? 2 : 0);
;           const f32x4 s0 = sp[0], s1 = sp[1];
;           const float ss = (s0[0] + s0[1]) + (s0[2] + s0[3]) + (s1[0] + s1[1]) + (s1[2] + s1[3]);
;           rs = __builtin_amdgcn_rsqf(ss * (1.0f / 512) + EPS);
;           if (MODE == EP_Q) rs *= QSCALE;
;         }
;         float ssq = 0.f;
; #pragma unroll
;         for (int bj = 0; bj < 2; ++bj) {
;           f32x4 v0 = acc[ai][bj][m][0] * rs, v1 = acc[ai][bj][m][1] * rs;
;           if (MODE == EP_IN || MODE == EP_MIX || MODE == EP_DOWN) {
; #pragma unroll
;             for (int j = 0; j < 4; ++j) ssq += v0[j] * v0[j] + v1[j] * v1[j];
;           }
;           if (MODE == EP_UP) {
; #pragma unroll
;             for (int j = 0; j < 4; ++j) { float a = fmaxf(v0[j], 0.f), b = fmaxf(v1[j], 0.f); v0[j] = a * a; v1[j] = b * b; }
;           }
;           bf16_t* dst;
;           const int ct = bj * 128 + cl;
;           if (MODE == EP_IN) {
;             if (pn < 4) dst = (bf16_t*)(ws + OFF_PROJA) + (size_t)grow * 1024 + pn * 256 + ct;
;             else if (pn < 16) dst = (bf16_t*)(ws + OFF_PROJG) + (size_t)grow * 3072 + (pn - 4) * 256 + ct;
;             else dst = (bf16_t*)(ws + OFF_PROJS) + (size_t)grow * 256 + ct;
;           } else if (MODE == EP_Q) {
;             if (pn < 4) dst = (bf16_t*)(dout + DO_Q) + (size_t)grow * 1536 + (pn * 2 + bj) * 192 + cl;
;             else {
;               const int mm = (pn - 4) * 256 + ct, h = mm >> 6, r = mm & 63;
;               dst = (bf16_t*)(dout + DO_Q) + (size_t)grow * 1536 + h * 192 + 128 + r;
;               const int pos = grow < TP ? (grow & 4095) : grow - TP;
;               const f32x4* tb = (const f32x4*)((const f32x2*)(ws + OFF_ROPE) + pos * 32 + (r >> 1));
;               const f32x4 t0 = tb[0], t1 = tb[1];
;               f32x4 o0, o1;
	v_mov_b32_e32 v128, v115
	v_mov_b32_e32 v129, v116
	v_mov_b32_e32 v115, v117
	v_mov_b32_e32 v116, v120
	v_mov_b32_e32 v117, v118
	v_mov_b32_e32 v118, v121
	v_pk_add_f32 v[114:115], v[128:129], v[114:115]
	v_pk_add_f32 v[116:117], v[116:117], v[118:119]
	v_add_f32_e32 v114, v114, v115
	v_add_f32_e32 v114, v114, v117
	v_add_f32_e32 v114, v116, v114
	v_fmamk_f32 v114, v114, 0x3b000000, v154
	v_rsq_f32_e32 v114, v114
	v_add_co_u32_e32 v116, vcc, s41, v126
	v_lshl_add_u64 v[118:119], v[124:125], 0, v[138:139]
	v_pk_mul_f32 v[112:113], v[112:113], v[114:115] op_sel_hi:[1,0]
	v_pk_mul_f32 v[110:111], v[110:111], v[114:115] op_sel_hi:[1,0]
	v_pk_mul_f32 v[108:109], v[108:109], v[114:115] op_sel_hi:[1,0]
	v_pk_mul_f32 v[106:107], v[106:107], v[114:115] op_sel_hi:[1,0]
	v_pk_mul_f32 v[104:105], v[104:105], v[114:115] op_sel_hi:[1,0]
	v_pk_mul_f32 v[102:103], v[102:103], v[114:115] op_sel_hi:[1,0]
	v_pk_mul_f32 v[120:121], v[100:101], v[114:115] op_sel_hi:[1,0]
	v_pk_mul_f32 v[114:115], v[98:99], v[114:115] op_sel_hi:[1,0]
	v_cvt_pk_bf16_f32 v98, v110, v111
	v_cvt_pk_bf16_f32 v99, v112, v113
	v_cvt_pk_bf16_f32 v100, v106, v107
	v_cvt_pk_bf16_f32 v101, v108, v109
	v_addc_co_u32_e32 v117, vcc, 0, v127, vcc
	v_cvt_pk_bf16_f32 v102, v102, v103
	v_cvt_pk_bf16_f32 v103, v104, v105
	v_cvt_pk_bf16_f32 v104, v114, v115
	v_cvt_pk_bf16_f32 v105, v120, v121
	global_store_dwordx4 v[118:119], v[98:101], off
	global_store_dwordx4 v[118:119], v[102:105], off offset:256
	global_load_dwordx4 v[98:101], v[116:117], off offset:32
	v_or_b32_e32 v106, 48, v148
	v_lshl_add_u64 v[102:103], v[126:127], 0, s[6:7]
	global_load_dwordx4 v[102:105], v[102:103], off offset:16
	v_ashrrev_i32_e32 v107, 31, v106
	v_lshlrev_b64 v[108:109], 12, v[122:123]
	v_lshlrev_b64 v[110:111], 6, v[106:107]
	v_lshl_add_u64 v[108:109], s[4:5], 0, v[108:109]
	v_lshl_add_u64 v[110:111], s[84:85], 0, v[110:111]
	v_lshl_add_u64 v[108:109], v[108:109], 0, s[18:19]
	s_waitcnt vmcnt(0)
	v_mov_b32_e32 v112, v99
	v_mov_b32_e32 v113, v100
	v_mov_b32_e32 v99, v101
	v_mov_b32_e32 v100, v104
	v_mov_b32_e32 v101, v102
	v_mov_b32_e32 v102, v105
	v_pk_add_f32 v[98:99], v[112:113], v[98:99]
	v_pk_add_f32 v[100:101], v[100:101], v[102:103]
	v_add_f32_e32 v98, v98, v99
	v_add_f32_e32 v98, v98, v101
	v_add_f32_e32 v98, v100, v98
	v_fmamk_f32 v98, v98, 0x3b000000, v154
	v_rsq_f32_e32 v98, v98
	v_add_co_u32_e32 v100, vcc, s41, v110
	v_lshl_add_u64 v[102:103], v[108:109], 0, v[138:139]
	v_pk_mul_f32 v[96:97], v[96:97], v[98:99] op_sel_hi:[1,0]
	v_pk_mul_f32 v[94:95], v[94:95], v[98:99] op_sel_hi:[1,0]
	v_pk_mul_f32 v[92:93], v[92:93], v[98:99] op_sel_hi:[1,0]
	v_pk_mul_f32 v[90:91], v[90:91], v[98:99] op_sel_hi:[1,0]
	v_pk_mul_f32 v[88:89], v[88:89], v[98:99] op_sel_hi:[1,0]
	v_pk_mul_f32 v[86:87], v[86:87], v[98:99] op_sel_hi:[1,0]
	v_pk_mul_f32 v[104:105], v[84:85], v[98:99] op_sel_hi:[1,0]
	v_pk_mul_f32 v[98:99], v[82:83], v[98:99] op_sel_hi:[1,0]
	v_cvt_pk_bf16_f32 v82, v94, v95
	v_cvt_pk_bf16_f32 v83, v96, v97
	v_cvt_pk_bf16_f32 v84, v90, v91
	v_cvt_pk_bf16_f32 v85, v92, v93
	v_addc_co_u32_e32 v101, vcc, 0, v111, vcc
	v_cvt_pk_bf16_f32 v86, v86, v87
	v_cvt_pk_bf16_f32 v87, v88, v89
	v_cvt_pk_bf16_f32 v88, v98, v99
	v_cvt_pk_bf16_f32 v89, v104, v105
	global_store_dwordx4 v[102:103], v[82:85], off
	global_store_dwordx4 v[102:103], v[86:89], off offset:256
	global_load_dwordx4 v[82:85], v[100:101], off offset:32
	v_add_u32_e32 v90, 0x80, v148
	v_lshl_add_u64 v[86:87], v[110:111], 0, s[6:7]
	global_load_dwordx4 v[86:89], v[86:87], off offset:16
	v_ashrrev_i32_e32 v91, 31, v90
	v_lshlrev_b64 v[92:93], 12, v[106:107]
	v_lshlrev_b64 v[94:95], 6, v[90:91]
	v_lshl_add_u64 v[92:93], s[4:5], 0, v[92:93]
	v_lshl_add_u64 v[94:95], s[84:85], 0, v[94:95]
	v_lshl_add_u64 v[92:93], v[92:93], 0, s[18:19]
	s_waitcnt vmcnt(0)
	v_mov_b32_e32 v96, v83
	v_mov_b32_e32 v97, v84
	v_mov_b32_e32 v83, v85
	v_mov_b32_e32 v84, v88
	v_mov_b32_e32 v85, v86
	v_mov_b32_e32 v86, v89
	v_pk_add_f32 v[82:83], v[96:97], v[82:83]
	v_pk_add_f32 v[84:85], v[84:85], v[86:87]
	v_add_f32_e32 v82, v82, v83
	v_add_f32_e32 v82, v82, v85
	v_add_f32_e32 v82, v84, v82
	v_fmamk_f32 v82, v82, 0x3b000000, v154
	v_rsq_f32_e32 v82, v82
	v_add_co_u32_e32 v84, vcc, s41, v94
	v_lshl_add_u64 v[86:87], v[92:93], 0, v[138:139]
	v_pk_mul_f32 v[80:81], v[80:81], v[82:83] op_sel_hi:[1,0]
	v_pk_mul_f32 v[78:79], v[78:79], v[82:83] op_sel_hi:[1,0]
	v_pk_mul_f32 v[76:77], v[76:77], v[82:83] op_sel_hi:[1,0]
	v_pk_mul_f32 v[74:75], v[74:75], v[82:83] op_sel_hi:[1,0]
	v_pk_mul_f32 v[72:73], v[72:73], v[82:83] op_sel_hi:[1,0]
	v_pk_mul_f32 v[70:71], v[70:71], v[82:83] op_sel_hi:[1,0]
	v_pk_mul_f32 v[88:89], v[68:69], v[82:83] op_sel_hi:[1,0]
	v_pk_mul_f32 v[82:83], v[66:67], v[82:83] op_sel_hi:[1,0]
	v_cvt_pk_bf16_f32 v66, v78, v79
	v_cvt_pk_bf16_f32 v67, v80, v81
	v_cvt_pk_bf16_f32 v68, v74, v75
	v_cvt_pk_bf16_f32 v69, v76, v77
	v_addc_co_u32_e32 v85, vcc, 0, v95, vcc
	v_cvt_pk_bf16_f32 v70, v70, v71
	v_cvt_pk_bf16_f32 v71, v72, v73
	v_cvt_pk_bf16_f32 v72, v82, v83
	v_cvt_pk_bf16_f32 v73, v88, v89
	global_store_dwordx4 v[86:87], v[66:69], off
	global_store_dwordx4 v[86:87], v[70:73], off offset:256
	global_load_dwordx4 v[66:69], v[84:85], off offset:32
	v_add_u32_e32 v74, 0x90, v148
	v_lshl_add_u64 v[70:71], v[94:95], 0, s[6:7]
	global_load_dwordx4 v[70:73], v[70:71], off offset:16
	v_ashrrev_i32_e32 v75, 31, v74
	v_lshlrev_b64 v[76:77], 12, v[90:91]
	v_lshlrev_b64 v[78:79], 6, v[74:75]
	v_lshl_add_u64 v[76:77], s[4:5], 0, v[76:77]
	v_lshl_add_u64 v[78:79], s[84:85], 0, v[78:79]
	v_lshl_add_u64 v[76:77], v[76:77], 0, s[18:19]
	s_waitcnt vmcnt(0)
;   DI void operator()(const f32x4 (&acc)[2][2][4][2], const pg8::Unit& u, int wr, int wc, int fr, int fq) const {
;     ...
;         const int row = u.pm * 256 + ai * 128 + wr * 64 + m * 16 + fr;
;         const int grow = rowbase + row;
;         float rs = 1.f;
;         if (MODE == EP_IN) rs = ((const float*)(ws + OFF_RS0))[grow];
;         if (MODE == EP_UP) rs = ((const float*)(ws + OFF_RS2))[grow];
;         if (MODE == EP_Q || MODE == EP_KV) {
;           const f32x4* sp = (const f32x4*)(ws + OFF_SSQA) + (size_t)grow * 4 + (MODE == EP_KV ? 2 : 0);
;           const f32x4 s0 = sp[0], s1 = sp[1];
;           const float ss = (s0[0] + s0[1]) + (s0[2] + s0[3]) + (s1[0] + s1[1]) + (s1[2] + s1[3]);
;           rs = __builtin_amdgcn_rsqf(ss * (1.0f / 512) + EPS);
;           if (MODE == EP_Q) rs *= QSCALE;
;         }
;         float ssq = 0.f;
; #pragma unroll
;         for (int bj = 0; bj < 2; ++bj) {
;           f32x4 v0 = acc[ai][bj][m][0] * rs, v1 = acc[ai][bj][m][1] * rs;
;           if (MODE == EP_IN || MODE == EP_MIX || MODE == EP_DOWN) {
; #pragma unroll
;             for (int j = 0; j < 4; ++j) ssq += v0[j] * v0[j] + v1[j] * v1[j];
;           }
;           if (MODE == EP_UP) {
; #pragma unroll
;             for (int j = 0; j < 4; ++j) { float a = fmaxf(v0[j], 0.f), b = fmaxf(v1[j], 0.f); v0[j] = a * a; v1[j] = b * b; }
;           }
;           bf16_t* dst;
;           const int ct = bj * 128 + cl;
;           if (MODE == EP_IN) {
;             if (pn < 4) dst = (bf16_t*)(ws + OFF_PROJA) + (size_t)grow * 1024 + pn * 256 + ct;
;             else if (pn < 16) dst = (bf16_t*)(ws + OFF_PROJG) + (size_t)grow * 3072 + (pn - 4) * 256 + ct;
;             else dst = (bf16_t*)(ws + OFF_PROJS) + (size_t)grow * 256 + ct;
;           } else if (MODE == EP_Q) {
;             if (pn < 4) dst = (bf16_t*)(dout + DO_Q) + (size_t)grow * 1536 + (pn * 2 + bj) * 192 + cl;
;             else {
;               const int mm = (pn - 4) * 256 + ct, h = mm >> 6, r = mm & 63;
;               dst = (bf16_t*)(dout + DO_Q) + (size_t)grow * 1536 + h * 192 + 128 + r;
;               const int pos = grow < TP ? (grow & 4095) : grow - TP;
;               const f32x4* tb = (const f32x4*)((const f32x2*)(ws + OFF_ROPE) + pos * 32 + (r >> 1));
;               const f32x4 t0 = tb[0], t1 = tb[1];
;               f32x4 o0, o1;
	v_mov_b32_e32 v80, v67
	v_mov_b32_e32 v81, v68
	v_mov_b32_e32 v67, v69
	v_mov_b32_e32 v68, v72
	v_mov_b32_e32 v69, v70
	v_mov_b32_e32 v70, v73
	v_pk_add_f32 v[66:67], v[80:81], v[66:67]
	v_pk_add_f32 v[68:69], v[68:69], v[70:71]
	v_add_f32_e32 v66, v66, v67
	v_add_f32_e32 v66, v66, v69
	v_add_f32_e32 v66, v68, v66
	v_fmamk_f32 v66, v66, 0x3b000000, v154
	v_rsq_f32_e32 v66, v66
	v_add_co_u32_e32 v68, vcc, s41, v78
	v_lshl_add_u64 v[70:71], v[76:77], 0, v[138:139]
	v_pk_mul_f32 v[64:65], v[64:65], v[66:67] op_sel_hi:[1,0]
	v_pk_mul_f32 v[62:63], v[62:63], v[66:67] op_sel_hi:[1,0]
	v_pk_mul_f32 v[60:61], v[60:61], v[66:67] op_sel_hi:[1,0]
	v_pk_mul_f32 v[58:59], v[58:59], v[66:67] op_sel_hi:[1,0]
	v_pk_mul_f32 v[56:57], v[56:57], v[66:67] op_sel_hi:[1,0]
	v_pk_mul_f32 v[54:55], v[54:55], v[66:67] op_sel_hi:[1,0]
	v_pk_mul_f32 v[72:73], v[52:53], v[66:67] op_sel_hi:[1,0]
	v_pk_mul_f32 v[66:67], v[50:51], v[66:67] op_sel_hi:[1,0]
	v_cvt_pk_bf16_f32 v50, v62, v63
	v_cvt_pk_bf16_f32 v51, v64, v65
	v_cvt_pk_bf16_f32 v52, v58, v59
	v_cvt_pk_bf16_f32 v53, v60, v61
	v_addc_co_u32_e32 v69, vcc, 0, v79, vcc
	v_cvt_pk_bf16_f32 v54, v54, v55
	v_cvt_pk_bf16_f32 v55, v56, v57
	v_cvt_pk_bf16_f32 v56, v66, v67
	v_cvt_pk_bf16_f32 v57, v72, v73
	global_store_dwordx4 v[70:71], v[50:53], off
	global_store_dwordx4 v[70:71], v[54:57], off offset:256
	global_load_dwordx4 v[50:53], v[68:69], off offset:32
	v_add_u32_e32 v58, 0xa0, v148
	v_lshl_add_u64 v[54:55], v[78:79], 0, s[6:7]
	global_load_dwordx4 v[54:57], v[54:55], off offset:16
	v_ashrrev_i32_e32 v59, 31, v58
	v_lshlrev_b64 v[60:61], 12, v[74:75]
	v_lshlrev_b64 v[62:63], 6, v[58:59]
	v_lshl_add_u64 v[60:61], s[4:5], 0, v[60:61]
	v_lshl_add_u64 v[62:63], s[84:85], 0, v[62:63]
	v_lshl_add_u64 v[60:61], v[60:61], 0, s[18:19]
	s_waitcnt vmcnt(0)
	v_mov_b32_e32 v64, v51
	v_mov_b32_e32 v65, v52
	v_mov_b32_e32 v51, v53
	v_mov_b32_e32 v52, v56
	v_mov_b32_e32 v53, v54
	v_mov_b32_e32 v54, v57
	v_pk_add_f32 v[50:51], v[64:65], v[50:51]
	v_pk_add_f32 v[52:53], v[52:53], v[54:55]
	v_add_f32_e32 v50, v50, v51
	v_add_f32_e32 v50, v50, v53
	v_add_f32_e32 v50, v52, v50
	v_fmamk_f32 v50, v50, 0x3b000000, v154
	v_rsq_f32_e32 v50, v50
	v_add_co_u32_e32 v52, vcc, s41, v62
	v_lshl_add_u64 v[54:55], v[60:61], 0, v[138:139]
	v_pk_mul_f32 v[48:49], v[48:49], v[50:51] op_sel_hi:[1,0]
	v_pk_mul_f32 v[46:47], v[46:47], v[50:51] op_sel_hi:[1,0]
	v_pk_mul_f32 v[44:45], v[44:45], v[50:51] op_sel_hi:[1,0]
	v_pk_mul_f32 v[42:43], v[42:43], v[50:51] op_sel_hi:[1,0]
	v_pk_mul_f32 v[40:41], v[40:41], v[50:51] op_sel_hi:[1,0]
	v_pk_mul_f32 v[38:39], v[38:39], v[50:51] op_sel_hi:[1,0]
	v_pk_mul_f32 v[56:57], v[36:37], v[50:51] op_sel_hi:[1,0]
	v_pk_mul_f32 v[50:51], v[34:35], v[50:51] op_sel_hi:[1,0]
	v_cvt_pk_bf16_f32 v34, v46, v47
	v_cvt_pk_bf16_f32 v35, v48, v49
	v_cvt_pk_bf16_f32 v36, v42, v43
	v_cvt_pk_bf16_f32 v37, v44, v45
	v_addc_co_u32_e32 v53, vcc, 0, v63, vcc
	v_cvt_pk_bf16_f32 v38, v38, v39
	v_cvt_pk_bf16_f32 v39, v40, v41
	v_cvt_pk_bf16_f32 v40, v50, v51
	v_cvt_pk_bf16_f32 v41, v56, v57
	global_store_dwordx4 v[54:55], v[34:37], off
	global_store_dwordx4 v[54:55], v[38:41], off offset:256
	global_load_dwordx4 v[34:37], v[52:53], off offset:32
	v_add_u32_e32 v42, 0xb0, v148
	v_lshl_add_u64 v[38:39], v[62:63], 0, s[6:7]
	global_load_dwordx4 v[38:41], v[38:39], off offset:16
	v_ashrrev_i32_e32 v43, 31, v42
	v_lshlrev_b64 v[44:45], 12, v[58:59]
	v_lshlrev_b64 v[46:47], 6, v[42:43]
	v_lshl_add_u64 v[44:45], s[4:5], 0, v[44:45]
	v_lshl_add_u64 v[46:47], s[84:85], 0, v[46:47]
	v_lshl_add_u64 v[44:45], v[44:45], 0, s[18:19]
	s_waitcnt vmcnt(0)
	v_mov_b32_e32 v48, v35
	v_mov_b32_e32 v49, v36
	v_mov_b32_e32 v35, v37
	v_mov_b32_e32 v36, v40
	v_mov_b32_e32 v37, v38
	v_mov_b32_e32 v38, v41
	v_pk_add_f32 v[34:35], v[48:49], v[34:35]
	v_pk_add_f32 v[36:37], v[36:37], v[38:39]
	v_add_f32_e32 v34, v34, v35
	v_add_f32_e32 v34, v34, v37
	v_add_f32_e32 v34, v36, v34
	v_fmamk_f32 v34, v34, 0x3b000000, v154
	v_rsq_f32_e32 v34, v34
	v_add_co_u32_e32 v36, vcc, s41, v46
	v_lshl_add_u64 v[38:39], v[44:45], 0, v[138:139]
	v_pk_mul_f32 v[32:33], v[32:33], v[34:35] op_sel_hi:[1,0]
	v_pk_mul_f32 v[30:31], v[30:31], v[34:35] op_sel_hi:[1,0]
	v_pk_mul_f32 v[28:29], v[28:29], v[34:35] op_sel_hi:[1,0]
	v_pk_mul_f32 v[26:27], v[26:27], v[34:35] op_sel_hi:[1,0]
	v_pk_mul_f32 v[24:25], v[24:25], v[34:35] op_sel_hi:[1,0]
	v_pk_mul_f32 v[22:23], v[22:23], v[34:35] op_sel_hi:[1,0]
	v_pk_mul_f32 v[40:41], v[20:21], v[34:35] op_sel_hi:[1,0]
	v_pk_mul_f32 v[34:35], v[18:19], v[34:35] op_sel_hi:[1,0]
	v_cvt_pk_bf16_f32 v18, v30, v31
	v_cvt_pk_bf16_f32 v19, v32, v33
	v_cvt_pk_bf16_f32 v20, v26, v27
	v_cvt_pk_bf16_f32 v21, v28, v29
	v_addc_co_u32_e32 v37, vcc, 0, v47, vcc
	v_cvt_pk_bf16_f32 v22, v22, v23
	v_cvt_pk_bf16_f32 v23, v24, v25
	v_cvt_pk_bf16_f32 v24, v34, v35
	v_cvt_pk_bf16_f32 v25, v40, v41
	global_store_dwordx4 v[38:39], v[18:21], off
	global_store_dwordx4 v[38:39], v[22:25], off offset:256
	global_load_dwordx4 v[18:21], v[36:37], off offset:32
	v_lshlrev_b64 v[26:27], 12, v[42:43]
	v_lshl_add_u64 v[22:23], v[46:47], 0, s[6:7]
	global_load_dwordx4 v[22:25], v[22:23], off offset:16
	s_and_b64 vcc, exec, s[0:1]
	s_waitcnt vmcnt(0)
	v_mov_b32_e32 v28, v19
	v_mov_b32_e32 v29, v20
	v_mov_b32_e32 v19, v21
	v_mov_b32_e32 v20, v24
	v_mov_b32_e32 v21, v22
	v_mov_b32_e32 v22, v25
	v_pk_add_f32 v[18:19], v[28:29], v[18:19]
	v_pk_add_f32 v[20:21], v[20:21], v[22:23]
	v_add_f32_e32 v18, v18, v19
	v_add_f32_e32 v18, v18, v21
	v_add_f32_e32 v18, v20, v18
	v_fmamk_f32 v18, v18, 0x3b000000, v154
	v_rsq_f32_e32 v18, v18
	v_lshl_add_u64 v[20:21], s[4:5], 0, v[26:27]
	v_lshl_add_u64 v[20:21], v[20:21], 0, s[18:19]
	v_lshl_add_u64 v[20:21], v[20:21], 0, v[138:139]
	v_pk_mul_f32 v[16:17], v[16:17], v[18:19] op_sel_hi:[1,0]
	v_pk_mul_f32 v[14:15], v[14:15], v[18:19] op_sel_hi:[1,0]
	v_pk_mul_f32 v[12:13], v[12:13], v[18:19] op_sel_hi:[1,0]
	v_pk_mul_f32 v[10:11], v[10:11], v[18:19] op_sel_hi:[1,0]
	v_pk_mul_f32 v[8:9], v[8:9], v[18:19] op_sel_hi:[1,0]
	v_pk_mul_f32 v[6:7], v[6:7], v[18:19] op_sel_hi:[1,0]
	v_pk_mul_f32 v[22:23], v[4:5], v[18:19] op_sel_hi:[1,0]
	v_pk_mul_f32 v[18:19], v[2:3], v[18:19] op_sel_hi:[1,0]
	v_cvt_pk_bf16_f32 v2, v14, v15
	v_cvt_pk_bf16_f32 v3, v16, v17
	v_cvt_pk_bf16_f32 v4, v10, v11
	v_cvt_pk_bf16_f32 v5, v12, v13
	v_cvt_pk_bf16_f32 v6, v6, v7
	v_cvt_pk_bf16_f32 v7, v8, v9
	v_cvt_pk_bf16_f32 v8, v18, v19
	v_cvt_pk_bf16_f32 v9, v22, v23
	global_store_dwordx4 v[20:21], v[2:5], off
	global_store_dwordx4 v[20:21], v[6:9], off offset:256
	s_cbranch_vccz .LBB0_560
	s_waitcnt vmcnt(0)
	s_cmpk_gt_u32 s24, 0xff
	s_cbranch_scc1 .LBB0_571
	s_barrier

; #define PG8_STAGE(bufoff, gbase, voff) do { _Pragma("unroll") for (int _i = 0; _i < 2; ++_i) \
;     __builtin_amdgcn_global_load_lds((const unsigned*)((const char*)(gbase) + (voff)[_i]), (LAS unsigned*)(lds + (bufoff) + ldsw + _i * 8192), 16, 0, 0); } while (0)
; #define PG8_LDA(dst, b, h) do { _Pragma("unroll") for (int m = 0; m < 4; ++m) _Pragma("unroll") for (int k = 0; k < 2; ++k) dst[m][k] = *(const LAS bf16x8*)(lds + PG8_SA(b, h) + aoff + m * 2048 + k * 1024); } while (0)
; #define PG8_LDB(dst, b, h) do { _Pragma("unroll") for (int n = 0; n < 2; ++n) _Pragma("unroll") for (int k = 0; k < 2; ++k) dst[n][k] = *(const LAS bf16x8*)(lds + PG8_SB(b, h) + boff + n * 2048 + k * 1024); } while (0)
; #define PG8_MMA(ai, bj, At, Bt) do { __builtin_amdgcn_s_setprio(1); _Pragma("unroll") for (int m = 0; m < 4; ++m) _Pragma("unroll") for (int n = 0; n < 2; ++n) _Pragma("unroll") for (int k = 0; k < 2; ++k) \
;     acc[ai][bj][m][n] = __builtin_amdgcn_mfma_f32_16x16x32_bf16(Bt[n][k], At[m][k], acc[ai][bj][m][n], 0, 0, 0); __builtin_amdgcn_s_setprio(0); } while (0)
; #define PG8_WAIT_V(n) asm volatile("s_waitcnt vmcnt(" #n ")" ::: "memory")
; #define PG8_WAIT_L(n) asm volatile("s_waitcnt lgkmcnt(" #n ")" ::: "memory")
; #define PG8_BAR __builtin_amdgcn_s_barrier()
; #define PG8_SCHED __builtin_amdgcn_sched_barrier(0)
; template <class Epi>
; DI void gemm_phase(LAS unsigned char* lds, const Gemm g, const StaticOrder& S, const Epi& E) {
;     ...
;     for (int t = 0; t < nt; t += 2) {
;       const bool last = (t == nt - 2);
;       const char* a1 = cA + PG8_AK(t + 1);
;       const char* a2 = last ? nA : cA + PG8_AK(t + 2); const char* b2 = last ? nB : cB + (size_t)(t + 2) * kstep;
;       const char* a3 = a2 + kstep; const char* b3 = b2 + kstep;
;       PG8_LDB(B0, 0, 0); PG8_SCHED; PG8_LDA(At, 0, 0); PG8_STAGE(PG8_SA(1, 1), a1 + hstepA, voffA);
;       PG8_WAIT_L(8); PG8_BAR; PG8_WAIT_L(0); PG8_MMA(0, 0, At, B0); PG8_BAR; PG8_SCHED;
;       PG8_LDB(B1, 0, 1); PG8_STAGE(PG8_SB(0, 0), b2, voffB);
;       PG8_BAR; PG8_WAIT_L(0); PG8_MMA(0, 1, At, B1); PG8_BAR;
;       PG8_LDA(At, 0, 1); PG8_STAGE(PG8_SA(0, 0), a2, voffA);
;       PG8_BAR; PG8_WAIT_L(0); PG8_MMA(1, 0, At, B0); PG8_BAR; PG8_SCHED;
;       PG8_STAGE(PG8_SB(0, 1), b2 + hstepB, voffB);
;       PG8_WAIT_V(6); PG8_BAR; PG8_MMA(1, 1, At, B1); PG8_BAR;
.LBB0_840:
	s_add_i32 s52, s24, 2
	s_cmp_gt_u32 s52, 15
	s_cselect_b32 s54, s39, 0
	s_cselect_b32 s55, s40, 0
	s_cmp_gt_u32 s52, 13
	s_cselect_b32 s26, s39, 0
	ds_read_b128 v[156:159], v151
	ds_read_b128 v[160:163], v151 offset:1024
	ds_read_b128 v[164:167], v151 offset:2048
	ds_read_b128 v[168:171], v151 offset:3072
	s_cselect_b32 s25, s40, 0
	s_add_u32 s26, s22, s26
	s_addc_u32 s25, s23, s25
	s_add_u32 s26, s26, 0xfffc0080
	s_addc_u32 s25, s25, -1
	s_cmp_eq_u32 s24, 28
	s_cselect_b32 s24, s49, s50
	s_cselect_b32 s27, s15, s25
	s_cselect_b32 s26, s21, s26
	s_cselect_b32 s25, s13, s51
	v_lshl_add_u64 v[148:149], s[22:23], 0, v[140:141]
	v_lshl_add_u64 v[148:149], v[148:149], 0, s[54:55]
	s_add_i32 m0, s35, 0xc000
	ds_read_b128 v[172:175], v152
	ds_read_b128 v[176:179], v152 offset:1024
	ds_read_b128 v[180:183], v152 offset:2048
	ds_read_b128 v[184:187], v152 offset:3072
	ds_read_b128 v[188:191], v152 offset:4096
	ds_read_b128 v[192:195], v152 offset:5120
	ds_read_b128 v[196:199], v152 offset:6144
	ds_read_b128 v[200:203], v152 offset:7168
	global_load_lds_dwordx4 v[148:149], off
	v_lshl_add_u64 v[148:149], s[22:23], 0, v[142:143]
	v_lshl_add_u64 v[148:149], v[148:149], 0, s[54:55]
	s_add_i32 m0, s35, 0xe000
	s_nop 0
	global_load_lds_dwordx4 v[148:149], off
	s_waitcnt lgkmcnt(8)
	s_barrier
	s_waitcnt lgkmcnt(0)
	s_waitcnt lgkmcnt(0)
	v_mfma_f32_16x16x32_bf16 v[126:129], v[156:159], v[172:175], v[126:129]
	v_mfma_f32_16x16x32_bf16 v[122:125], v[164:167], v[172:175], v[122:125]
	v_mfma_f32_16x16x32_bf16 v[110:113], v[156:159], v[180:183], v[110:113]
	v_mfma_f32_16x16x32_bf16 v[106:109], v[164:167], v[180:183], v[106:109]
	v_mfma_f32_16x16x32_bf16 v[94:97], v[156:159], v[188:191], v[94:97]
	v_mfma_f32_16x16x32_bf16 v[90:93], v[164:167], v[188:191], v[90:93]
	v_mfma_f32_16x16x32_bf16 v[78:81], v[156:159], v[196:199], v[78:81]
	v_mfma_f32_16x16x32_bf16 v[74:77], v[164:167], v[196:199], v[74:77]
	v_mfma_f32_16x16x32_bf16 v[126:129], v[160:163], v[176:179], v[126:129]
	v_mfma_f32_16x16x32_bf16 v[122:125], v[168:171], v[176:179], v[122:125]
	v_mfma_f32_16x16x32_bf16 v[110:113], v[160:163], v[184:187], v[110:113]
	v_mfma_f32_16x16x32_bf16 v[106:109], v[168:171], v[184:187], v[106:109]
	v_mfma_f32_16x16x32_bf16 v[94:97], v[160:163], v[192:195], v[94:97]
	v_mfma_f32_16x16x32_bf16 v[90:93], v[168:171], v[192:195], v[90:93]
	v_mfma_f32_16x16x32_bf16 v[78:81], v[160:163], v[200:203], v[78:81]
	v_mfma_f32_16x16x32_bf16 v[74:77], v[168:171], v[200:203], v[74:77]
	s_barrier
	s_add_i32 s53, s46, s34
	v_lshl_add_u64 v[148:149], s[24:25], 0, v[132:133]
	s_mov_b32 m0, s53
	ds_read_b128 v[204:207], v153
	ds_read_b128 v[208:211], v153 offset:1024
	ds_read_b128 v[212:215], v153 offset:2048
	ds_read_b128 v[216:219], v153 offset:3072
	global_load_lds_dwordx4 v[148:149], off
	v_lshl_add_u64 v[220:221], s[24:25], 0, v[136:137]
	s_add_i32 m0, s53, 0x2000
	s_nop 0
	global_load_lds_dwordx4 v[220:221], off
	s_barrier
	s_waitcnt lgkmcnt(0)
	s_waitcnt lgkmcnt(0)
	v_mfma_f32_16x16x32_bf16 v[118:121], v[204:207], v[172:175], v[118:121]
	v_mfma_f32_16x16x32_bf16 v[114:117], v[212:215], v[172:175], v[114:117]
	v_mfma_f32_16x16x32_bf16 v[102:105], v[204:207], v[180:183], v[102:105]
	v_mfma_f32_16x16x32_bf16 v[98:101], v[212:215], v[180:183], v[98:101]
	v_mfma_f32_16x16x32_bf16 v[86:89], v[204:207], v[188:191], v[86:89]
	v_mfma_f32_16x16x32_bf16 v[82:85], v[212:215], v[188:191], v[82:85]
	v_mfma_f32_16x16x32_bf16 v[70:73], v[204:207], v[196:199], v[70:73]
	v_mfma_f32_16x16x32_bf16 v[66:69], v[212:215], v[196:199], v[66:69]
	v_mfma_f32_16x16x32_bf16 v[118:121], v[208:211], v[176:179], v[118:121]
	v_mfma_f32_16x16x32_bf16 v[114:117], v[216:219], v[176:179], v[114:117]
	v_mfma_f32_16x16x32_bf16 v[102:105], v[208:211], v[184:187], v[102:105]
	v_mfma_f32_16x16x32_bf16 v[98:101], v[216:219], v[184:187], v[98:101]
	v_mfma_f32_16x16x32_bf16 v[86:89], v[208:211], v[192:195], v[86:89]
	v_mfma_f32_16x16x32_bf16 v[82:85], v[216:219], v[192:195], v[82:85]
	v_mfma_f32_16x16x32_bf16 v[70:73], v[208:211], v[200:203], v[70:73]
	v_mfma_f32_16x16x32_bf16 v[66:69], v[216:219], v[200:203], v[66:69]
	s_mov_b32 m0, s35
	v_lshl_add_u64 v[222:223], s[26:27], 0, v[130:131]
	s_barrier
	ds_read_b128 v[172:175], v152 offset:16384
	ds_read_b128 v[176:179], v152 offset:17408
	ds_read_b128 v[180:183], v152 offset:18432
	ds_read_b128 v[184:187], v152 offset:19456
	ds_read_b128 v[188:191], v152 offset:20480
	ds_read_b128 v[192:195], v152 offset:21504
	ds_read_b128 v[196:199], v152 offset:22528
	ds_read_b128 v[200:203], v152 offset:23552
	global_load_lds_dwordx4 v[222:223], off
	v_lshl_add_u64 v[224:225], s[26:27], 0, v[134:135]
	s_mov_b32 m0, s36
	s_nop 0
	global_load_lds_dwordx4 v[224:225], off
	s_barrier
	s_waitcnt lgkmcnt(0)
	s_waitcnt lgkmcnt(0)
	v_mfma_f32_16x16x32_bf16 v[62:65], v[156:159], v[172:175], v[62:65]
	v_mfma_f32_16x16x32_bf16 v[58:61], v[164:167], v[172:175], v[58:61]
	v_mfma_f32_16x16x32_bf16 v[46:49], v[156:159], v[180:183], v[46:49]
	v_mfma_f32_16x16x32_bf16 v[42:45], v[164:167], v[180:183], v[42:45]
	v_mfma_f32_16x16x32_bf16 v[30:33], v[156:159], v[188:191], v[30:33]
	v_mfma_f32_16x16x32_bf16 v[26:29], v[164:167], v[188:191], v[26:29]
	v_mfma_f32_16x16x32_bf16 v[14:17], v[156:159], v[196:199], v[14:17]
	v_mfma_f32_16x16x32_bf16 v[10:13], v[164:167], v[196:199], v[10:13]
	v_mfma_f32_16x16x32_bf16 v[62:65], v[160:163], v[176:179], v[62:65]
	v_mfma_f32_16x16x32_bf16 v[58:61], v[168:171], v[176:179], v[58:61]
	v_mfma_f32_16x16x32_bf16 v[46:49], v[160:163], v[184:187], v[46:49]
	v_mfma_f32_16x16x32_bf16 v[42:45], v[168:171], v[184:187], v[42:45]
	v_mfma_f32_16x16x32_bf16 v[30:33], v[160:163], v[192:195], v[30:33]
	v_mfma_f32_16x16x32_bf16 v[26:29], v[168:171], v[192:195], v[26:29]
	v_mfma_f32_16x16x32_bf16 v[14:17], v[160:163], v[200:203], v[14:17]
	v_mfma_f32_16x16x32_bf16 v[10:13], v[168:171], v[200:203], v[10:13]
	s_barrier
; #define PG8_STAGE(bufoff, gbase, voff) do { _Pragma("unroll") for (int _i = 0; _i < 2; ++_i) \
;     __builtin_amdgcn_global_load_lds((const unsigned*)((const char*)(gbase) + (voff)[_i]), (LAS unsigned*)(lds + (bufoff) + ldsw + _i * 8192), 16, 0, 0); } while (0)
; #define PG8_LDA(dst, b, h) do { _Pragma("unroll") for (int m = 0; m < 4; ++m) _Pragma("unroll") for (int k = 0; k < 2; ++k) dst[m][k] = *(const LAS bf16x8*)(lds + PG8_SA(b, h) + aoff + m * 2048 + k * 1024); } while (0)
; #define PG8_LDB(dst, b, h) do { _Pragma("unroll") for (int n = 0; n < 2; ++n) _Pragma("unroll") for (int k = 0; k < 2; ++k) dst[n][k] = *(const LAS bf16x8*)(lds + PG8_SB(b, h) + boff + n * 2048 + k * 1024); } while (0)
; #define PG8_MMA(ai, bj, At, Bt) do { __builtin_amdgcn_s_setprio(1); _Pragma("unroll") for (int m = 0; m < 4; ++m) _Pragma("unroll") for (int n = 0; n < 2; ++n) _Pragma("unroll") for (int k = 0; k < 2; ++k) \
;     acc[ai][bj][m][n] = __builtin_amdgcn_mfma_f32_16x16x32_bf16(Bt[n][k], At[m][k], acc[ai][bj][m][n], 0, 0, 0); __builtin_amdgcn_s_setprio(0); } while (0)
; #define PG8_WAIT_V(n) asm volatile("s_waitcnt vmcnt(" #n ")" ::: "memory")
; #define PG8_WAIT_L(n) asm volatile("s_waitcnt lgkmcnt(" #n ")" ::: "memory")
; #define PG8_BAR __builtin_amdgcn_s_barrier()
; #define PG8_SCHED __builtin_amdgcn_sched_barrier(0)
; template <class Epi>
; DI void gemm_phase(LAS unsigned char* lds, const Gemm g, const StaticOrder& S, const Epi& E) {
;     ...
;       PG8_STAGE(PG8_SB(0, 1), b2 + hstepB, voffB);
;       PG8_WAIT_V(6); PG8_BAR; PG8_MMA(1, 1, At, B1); PG8_BAR;
;       PG8_LDB(B0, 1, 0); PG8_SCHED; PG8_LDA(At, 1, 0); PG8_STAGE(PG8_SA(0, 1), a2 + hstepA, voffA);
;       PG8_WAIT_L(8); PG8_BAR; PG8_WAIT_L(0); PG8_MMA(0, 0, At, B0); PG8_BAR; PG8_SCHED;
;       PG8_LDB(B1, 1, 1); PG8_STAGE(PG8_SB(1, 0), b3, voffB);
;       PG8_BAR; PG8_WAIT_L(0); PG8_MMA(0, 1, At, B1); PG8_BAR;
;       PG8_LDA(At, 1, 1); PG8_STAGE(PG8_SA(1, 0), a3, voffA);
;       PG8_BAR; PG8_WAIT_L(0); PG8_MMA(1, 0, At, B0); PG8_BAR; PG8_SCHED;
	s_add_u32 s54, s24, 0x80000
	s_addc_u32 s55, s25, 0
	s_add_i32 s53, s47, s34
	v_lshl_add_u64 v[156:157], s[54:55], 0, v[132:133]
	s_mov_b32 m0, s53
	s_nop 0
	global_load_lds_dwordx4 v[156:157], off
	v_lshl_add_u64 v[156:157], s[54:55], 0, v[136:137]
	s_add_i32 m0, s53, 0x2000
	s_nop 0
	global_load_lds_dwordx4 v[156:157], off
	s_waitcnt vmcnt(6)
	s_barrier
	v_mfma_f32_16x16x32_bf16 v[54:57], v[204:207], v[172:175], v[54:57]
	v_mfma_f32_16x16x32_bf16 v[50:53], v[212:215], v[172:175], v[50:53]
	v_mfma_f32_16x16x32_bf16 v[38:41], v[204:207], v[180:183], v[38:41]
	v_mfma_f32_16x16x32_bf16 v[34:37], v[212:215], v[180:183], v[34:37]
	v_mfma_f32_16x16x32_bf16 v[22:25], v[204:207], v[188:191], v[22:25]
	v_mfma_f32_16x16x32_bf16 v[18:21], v[212:215], v[188:191], v[18:21]
	v_mfma_f32_16x16x32_bf16 v[6:9], v[204:207], v[196:199], v[6:9]
	v_mfma_f32_16x16x32_bf16 v[2:5], v[212:215], v[196:199], v[2:5]
	v_mfma_f32_16x16x32_bf16 v[54:57], v[208:211], v[176:179], v[54:57]
	v_mfma_f32_16x16x32_bf16 v[50:53], v[216:219], v[176:179], v[50:53]
	v_mfma_f32_16x16x32_bf16 v[38:41], v[208:211], v[184:187], v[38:41]
	v_mfma_f32_16x16x32_bf16 v[34:37], v[216:219], v[184:187], v[34:37]
	v_mfma_f32_16x16x32_bf16 v[22:25], v[208:211], v[192:195], v[22:25]
	v_mfma_f32_16x16x32_bf16 v[18:21], v[216:219], v[192:195], v[18:21]
	v_mfma_f32_16x16x32_bf16 v[6:9], v[208:211], v[200:203], v[6:9]
	v_mfma_f32_16x16x32_bf16 v[2:5], v[216:219], v[200:203], v[2:5]
	s_add_i32 s53, 0, 0x18000
	v_add_u32_e32 v155, s53, v150
	s_barrier
	ds_read_b128 v[156:159], v155
	ds_read_b128 v[160:163], v155 offset:1024
	ds_read_b128 v[164:167], v155 offset:2048
	ds_read_b128 v[168:171], v155 offset:3072
	s_add_u32 s26, s26, 0x40000
	s_addc_u32 s27, s27, 0
	s_mov_b32 m0, s37
	v_lshl_add_u64 v[204:205], s[26:27], 0, v[130:131]
	ds_read_b128 v[172:175], v152 offset:32768
	ds_read_b128 v[176:179], v152 offset:33792
	ds_read_b128 v[180:183], v152 offset:34816
	ds_read_b128 v[184:187], v152 offset:35840
	ds_read_b128 v[188:191], v152 offset:36864
	ds_read_b128 v[192:195], v152 offset:37888
	ds_read_b128 v[196:199], v152 offset:38912
	ds_read_b128 v[200:203], v152 offset:39936
	global_load_lds_dwordx4 v[204:205], off
	v_lshl_add_u64 v[204:205], s[26:27], 0, v[134:135]
	s_mov_b32 m0, s38
	s_nop 0
	global_load_lds_dwordx4 v[204:205], off
	s_waitcnt lgkmcnt(8)
	s_barrier
	s_waitcnt lgkmcnt(0)
	s_waitcnt lgkmcnt(0)
	v_mfma_f32_16x16x32_bf16 v[126:129], v[156:159], v[172:175], v[126:129]
	v_mfma_f32_16x16x32_bf16 v[122:125], v[164:167], v[172:175], v[122:125]
	v_mfma_f32_16x16x32_bf16 v[110:113], v[156:159], v[180:183], v[110:113]
	v_mfma_f32_16x16x32_bf16 v[106:109], v[164:167], v[180:183], v[106:109]
	v_mfma_f32_16x16x32_bf16 v[94:97], v[156:159], v[188:191], v[94:97]
	v_mfma_f32_16x16x32_bf16 v[90:93], v[164:167], v[188:191], v[90:93]
	v_mfma_f32_16x16x32_bf16 v[78:81], v[156:159], v[196:199], v[78:81]
	v_mfma_f32_16x16x32_bf16 v[74:77], v[164:167], v[196:199], v[74:77]
	v_mfma_f32_16x16x32_bf16 v[126:129], v[160:163], v[176:179], v[126:129]
	v_mfma_f32_16x16x32_bf16 v[122:125], v[168:171], v[176:179], v[122:125]
	v_mfma_f32_16x16x32_bf16 v[110:113], v[160:163], v[184:187], v[110:113]
	v_mfma_f32_16x16x32_bf16 v[106:109], v[168:171], v[184:187], v[106:109]
	v_mfma_f32_16x16x32_bf16 v[94:97], v[160:163], v[192:195], v[94:97]
	v_mfma_f32_16x16x32_bf16 v[90:93], v[168:171], v[192:195], v[90:93]
	v_mfma_f32_16x16x32_bf16 v[78:81], v[160:163], v[200:203], v[78:81]
	v_mfma_f32_16x16x32_bf16 v[74:77], v[168:171], v[200:203], v[74:77]
	s_barrier
	s_add_i32 s26, 0, 0x1c000
	s_add_i32 s27, s53, s34
	v_add_u32_e32 v155, s26, v150
	v_lshl_add_u64 v[148:149], v[148:149], 0, s[6:7]
	s_mov_b32 m0, s27
	ds_read_b128 v[204:207], v155
	ds_read_b128 v[208:211], v155 offset:1024
	ds_read_b128 v[212:215], v155 offset:2048
	ds_read_b128 v[216:219], v155 offset:3072
	global_load_lds_dwordx4 v[148:149], off
	v_lshl_add_u64 v[148:149], v[220:221], 0, s[6:7]
	s_add_i32 m0, s27, 0x2000
	s_nop 0
	global_load_lds_dwordx4 v[148:149], off
	s_barrier
	s_waitcnt lgkmcnt(0)
	s_waitcnt lgkmcnt(0)
	v_mfma_f32_16x16x32_bf16 v[118:121], v[204:207], v[172:175], v[118:121]
	v_mfma_f32_16x16x32_bf16 v[114:117], v[212:215], v[172:175], v[114:117]
	v_mfma_f32_16x16x32_bf16 v[102:105], v[204:207], v[180:183], v[102:105]
	v_mfma_f32_16x16x32_bf16 v[98:101], v[212:215], v[180:183], v[98:101]
	v_mfma_f32_16x16x32_bf16 v[86:89], v[204:207], v[188:191], v[86:89]
	v_mfma_f32_16x16x32_bf16 v[82:85], v[212:215], v[188:191], v[82:85]
	v_mfma_f32_16x16x32_bf16 v[70:73], v[204:207], v[196:199], v[70:73]
	v_mfma_f32_16x16x32_bf16 v[66:69], v[212:215], v[196:199], v[66:69]
	v_mfma_f32_16x16x32_bf16 v[118:121], v[208:211], v[176:179], v[118:121]
	v_mfma_f32_16x16x32_bf16 v[114:117], v[216:219], v[176:179], v[114:117]
	v_mfma_f32_16x16x32_bf16 v[102:105], v[208:211], v[184:187], v[102:105]
	v_mfma_f32_16x16x32_bf16 v[98:101], v[216:219], v[184:187], v[98:101]
	v_mfma_f32_16x16x32_bf16 v[86:89], v[208:211], v[192:195], v[86:89]
	v_mfma_f32_16x16x32_bf16 v[82:85], v[216:219], v[192:195], v[82:85]
	v_mfma_f32_16x16x32_bf16 v[70:73], v[208:211], v[200:203], v[70:73]
	v_mfma_f32_16x16x32_bf16 v[66:69], v[216:219], v[200:203], v[66:69]
	s_mov_b32 m0, s42
	v_lshl_add_u64 v[148:149], v[222:223], 0, s[6:7]
	s_barrier
; template <class Epi>
; DI void gemm_phase(LAS unsigned char* lds, const Gemm g, const StaticOrder& S, const Epi& E) {
;     ...
;       PG8_BAR; PG8_WAIT_L(0); PG8_MMA(1, 0, At, B0); PG8_BAR; PG8_SCHED;
;       PG8_STAGE(PG8_SB(1, 1), b3 + hstepB, voffB);
;       PG8_WAIT_V(6); PG8_BAR; PG8_MMA(1, 1, At, B1); PG8_BAR;
;     }
;   DI void operator()(const f32x4 (&acc)[2][2][4][2], const pg8::Unit& u, int wr, int wc, int fr, int fq) const {
;     ...
;         float ssq = 0.f;
; #pragma unroll
;         for (int bj = 0; bj < 2; ++bj) {
;           f32x4 v0 = acc[ai][bj][m][0] * rs, v1 = acc[ai][bj][m][1] * rs;
;           if (MODE == EP_IN || MODE == EP_MIX || MODE == EP_DOWN) {
; #pragma unroll
;             for (int j = 0; j < 4; ++j) ssq += v0[j] * v0[j] + v1[j] * v1[j];
;           }
;           if (MODE == EP_UP) {
; #pragma unroll
;             for (int j = 0; j < 4; ++j) { float a = fmaxf(v0[j], 0.f), b = fmaxf(v1[j], 0.f); v0[j] = a * a; v1[j] = b * b; }
;           }
;           bf16_t* dst;
;           const int ct = bj * 128 + cl;
;           if (MODE == EP_IN) {
;             if (pn < 4) dst = (bf16_t*)(ws + OFF_PROJA) + (size_t)grow * 1024 + pn * 256 + ct;
;             else if (pn < 16) dst = (bf16_t*)(ws + OFF_PROJG) + (size_t)grow * 3072 + (pn - 4) * 256 + ct;
;             else dst = (bf16_t*)(ws + OFF_PROJS) + (size_t)grow * 256 + ct;
;           } else if (MODE == EP_Q) {
;             if (pn < 4) dst = (bf16_t*)(dout + DO_Q) + (size_t)grow * 1536 + (pn * 2 + bj) * 192 + cl;
;             else {
;               const int mm = (pn - 4) * 256 + ct, h = mm >> 6, r = mm & 63;
;               dst = (bf16_t*)(dout + DO_Q) + (size_t)grow * 1536 + h * 192 + 128 + r;
;               const int pos = grow < TP ? (grow & 4095) : grow - TP;
;               const f32x4* tb = (const f32x4*)((const f32x2*)(ws + OFF_ROPE) + pos * 32 + (r >> 1));
;               const f32x4 t0 = tb[0], t1 = tb[1];
;               f32x4 o0, o1;
;               o0[0] = v0[0] * t0[0] - v0[1] * t0[1]; o0[1] = v0[1] * t0[0] + v0[0] * t0[1];
;               o0[2] = v0[2] * t0[2] - v0[3] * t0[3]; o0[3] = v0[3] * t0[2] + v0[2] * t0[3];
;               o1[0] = v1[0] * t1[0] - v1[1] * t1[1]; o1[1] = v1[1] * t1[0] + v1[0] * t1[1];
;               o1[2] = v1[2] * t1[2] - v1[3] * t1[3]; o1[3] = v1[3] * t1[2] + v1[2] * t1[3];
;               v0 = o0; v1 = o1;
;             }
	ds_read_b128 v[172:175], v152 offset:49152
	ds_read_b128 v[176:179], v152 offset:50176
	ds_read_b128 v[180:183], v152 offset:51200
	ds_read_b128 v[184:187], v152 offset:52224
	ds_read_b128 v[188:191], v152 offset:53248
	ds_read_b128 v[192:195], v152 offset:54272
	ds_read_b128 v[196:199], v152 offset:55296
	ds_read_b128 v[200:203], v152 offset:56320
	global_load_lds_dwordx4 v[148:149], off
	v_lshl_add_u64 v[148:149], v[224:225], 0, s[6:7]
	s_mov_b32 m0, s43
	s_nop 0
	global_load_lds_dwordx4 v[148:149], off
	s_barrier
	s_waitcnt lgkmcnt(0)
	s_waitcnt lgkmcnt(0)
	v_mfma_f32_16x16x32_bf16 v[62:65], v[156:159], v[172:175], v[62:65]
	v_mfma_f32_16x16x32_bf16 v[58:61], v[164:167], v[172:175], v[58:61]
	v_mfma_f32_16x16x32_bf16 v[46:49], v[156:159], v[180:183], v[46:49]
	v_mfma_f32_16x16x32_bf16 v[42:45], v[164:167], v[180:183], v[42:45]
	v_mfma_f32_16x16x32_bf16 v[30:33], v[156:159], v[188:191], v[30:33]
	v_mfma_f32_16x16x32_bf16 v[26:29], v[164:167], v[188:191], v[26:29]
	v_mfma_f32_16x16x32_bf16 v[14:17], v[156:159], v[196:199], v[14:17]
	v_mfma_f32_16x16x32_bf16 v[10:13], v[164:167], v[196:199], v[10:13]
	v_mfma_f32_16x16x32_bf16 v[62:65], v[160:163], v[176:179], v[62:65]
	v_mfma_f32_16x16x32_bf16 v[58:61], v[168:171], v[176:179], v[58:61]
	v_mfma_f32_16x16x32_bf16 v[46:49], v[160:163], v[184:187], v[46:49]
	v_mfma_f32_16x16x32_bf16 v[42:45], v[168:171], v[184:187], v[42:45]
	v_mfma_f32_16x16x32_bf16 v[30:33], v[160:163], v[192:195], v[30:33]
	v_mfma_f32_16x16x32_bf16 v[26:29], v[168:171], v[192:195], v[26:29]
	v_mfma_f32_16x16x32_bf16 v[14:17], v[160:163], v[200:203], v[14:17]
	v_mfma_f32_16x16x32_bf16 v[10:13], v[168:171], v[200:203], v[10:13]
	s_barrier
	s_add_u32 s24, s24, 0x80080
	s_addc_u32 s25, s25, 0
	s_add_i32 s26, s26, s34
	v_lshl_add_u64 v[148:149], s[24:25], 0, v[132:133]
	s_mov_b32 m0, s26
	s_nop 0
	global_load_lds_dwordx4 v[148:149], off
	v_lshl_add_u64 v[148:149], s[24:25], 0, v[136:137]
	s_add_i32 m0, s26, 0x2000
	s_nop 0
	global_load_lds_dwordx4 v[148:149], off
	s_waitcnt vmcnt(6)
	s_barrier
	v_mfma_f32_16x16x32_bf16 v[54:57], v[204:207], v[172:175], v[54:57]
	v_mfma_f32_16x16x32_bf16 v[50:53], v[212:215], v[172:175], v[50:53]
	v_mfma_f32_16x16x32_bf16 v[38:41], v[204:207], v[180:183], v[38:41]
	v_mfma_f32_16x16x32_bf16 v[34:37], v[212:215], v[180:183], v[34:37]
	v_mfma_f32_16x16x32_bf16 v[22:25], v[204:207], v[188:191], v[22:25]
	v_mfma_f32_16x16x32_bf16 v[18:21], v[212:215], v[188:191], v[18:21]
	v_mfma_f32_16x16x32_bf16 v[6:9], v[204:207], v[196:199], v[6:9]
	v_mfma_f32_16x16x32_bf16 v[2:5], v[212:215], v[196:199], v[2:5]
	v_mfma_f32_16x16x32_bf16 v[54:57], v[208:211], v[176:179], v[54:57]
	v_mfma_f32_16x16x32_bf16 v[50:53], v[216:219], v[176:179], v[50:53]
	v_mfma_f32_16x16x32_bf16 v[38:41], v[208:211], v[184:187], v[38:41]
	v_mfma_f32_16x16x32_bf16 v[34:37], v[216:219], v[184:187], v[34:37]
	v_mfma_f32_16x16x32_bf16 v[22:25], v[208:211], v[192:195], v[22:25]
	v_mfma_f32_16x16x32_bf16 v[18:21], v[216:219], v[192:195], v[18:21]
	v_mfma_f32_16x16x32_bf16 v[6:9], v[208:211], v[200:203], v[6:9]
	v_mfma_f32_16x16x32_bf16 v[2:5], v[216:219], v[200:203], v[2:5]
	s_add_u32 s22, s22, 0x100
	s_addc_u32 s23, s23, 0
	s_add_u32 s50, s50, 0x100
	s_addc_u32 s51, s51, 0
	s_cmp_gt_u32 s52, 29
	s_mov_b32 s24, s52
	s_barrier
	s_cbranch_scc0 .LBB0_840
	v_mul_f32_e32 v157, v122, v122
	v_mul_f32_e32 v160, v123, v123
	v_fmac_f32_e32 v157, v126, v126
	v_fmac_f32_e32 v160, v127, v127
	v_add_f32_e32 v157, v157, v160
	v_mul_f32_e32 v160, v124, v124
	v_fmac_f32_e32 v160, v128, v128
	v_add_f32_e32 v157, v160, v157
	v_mul_f32_e32 v160, v125, v125
	v_fmac_f32_e32 v160, v129, v129
	v_cvt_pk_bf16_f32 v126, v126, v127
	v_cvt_pk_bf16_f32 v127, v128, v129
	v_mul_f32_e32 v128, v114, v114
	v_add_f32_e32 v157, v160, v157
	v_fmac_f32_e32 v128, v118, v118
	v_mul_f32_e32 v129, v115, v115
	v_add_f32_e32 v128, v157, v128
	v_fmac_f32_e32 v129, v119, v119
	v_and_b32_e32 v155, 64, v154
	v_add_f32_e32 v128, v129, v128
	v_mul_f32_e32 v129, v116, v116
	v_xor_b32_e32 v149, 16, v154
	v_add_u32_e32 v155, 64, v155
	v_fmac_f32_e32 v129, v120, v120
	v_cmp_lt_i32_e32 vcc, v149, v155
	v_add_f32_e32 v128, v129, v128
	v_mul_f32_e32 v129, v117, v117
	v_cndmask_b32_e32 v149, v154, v149, vcc
	v_fmac_f32_e32 v129, v121, v121
	v_lshlrev_b32_e32 v156, 2, v149
	v_add_f32_e32 v157, v129, v128
	ds_bpermute_b32 v160, v156, v157
	v_xor_b32_e32 v149, 32, v154
	v_cmp_lt_i32_e32 vcc, v149, v155
	v_lshl_add_u32 v148, s20, 8, v1
	v_cvt_pk_bf16_f32 v128, v122, v123
	v_cndmask_b32_e32 v149, v154, v149, vcc
	v_lshlrev_b32_e32 v155, 2, v149
	v_cvt_pk_bf16_f32 v122, v118, v119
	s_waitcnt lgkmcnt(0)
	v_add_f32_e32 v118, v157, v160
	v_ashrrev_i32_e32 v149, 31, v148
	ds_bpermute_b32 v119, v155, v118
	s_lshl_b32 s22, s4, 8
	v_lshlrev_b64 v[158:159], 12, v[148:149]
	s_ashr_i32 s23, s22, 31
	v_lshl_add_u64 v[158:159], s[8:9], 0, v[158:159]
	s_lshl_b32 s20, s4, 2
	v_lshl_add_u64 v[158:159], s[22:23], 1, v[158:159]
	s_ashr_i32 s21, s20, 31
	v_lshl_add_u64 v[158:159], v[158:159], 0, v[138:139]
	v_cvt_pk_bf16_f32 v129, v124, v125
	v_cvt_pk_bf16_f32 v123, v120, v121
	v_cvt_pk_bf16_f32 v124, v114, v115
	v_cvt_pk_bf16_f32 v125, v116, v117
	global_store_dwordx4 v[158:159], v[126:129], off
	global_store_dwordx4 v[158:159], v[122:125], off offset:256
	s_and_saveexec_b64 s[24:25], s[0:1]
	s_cbranch_execz .LBB0_843
	v_lshlrev_b64 v[114:115], 7, v[148:149]
	v_lshl_add_u64 v[114:115], s[10:11], 0, v[114:115]
	v_lshl_add_u64 v[114:115], s[20:21], 2, v[114:115]
	s_lshl_b32 s4, s41, 2
	v_lshl_add_u64 v[114:115], v[114:115], 0, s[4:5]
	s_waitcnt lgkmcnt(0)
	v_add_f32_e32 v116, v118, v119
	global_store_dword v[114:115], v116, off

; #define PG8_STAGE(bufoff, gbase, voff) do { _Pragma("unroll") for (int _i = 0; _i < 2; ++_i) \
;     __builtin_amdgcn_global_load_lds((const unsigned*)((const char*)(gbase) + (voff)[_i]), (LAS unsigned*)(lds + (bufoff) + ldsw + _i * 8192), 16, 0, 0); } while (0)
; #define PG8_LDA(dst, b, h) do { _Pragma("unroll") for (int m = 0; m < 4; ++m) _Pragma("unroll") for (int k = 0; k < 2; ++k) dst[m][k] = *(const LAS bf16x8*)(lds + PG8_SA(b, h) + aoff + m * 2048 + k * 1024); } while (0)
; #define PG8_LDB(dst, b, h) do { _Pragma("unroll") for (int n = 0; n < 2; ++n) _Pragma("unroll") for (int k = 0; k < 2; ++k) dst[n][k] = *(const LAS bf16x8*)(lds + PG8_SB(b, h) + boff + n * 2048 + k * 1024); } while (0)
; #define PG8_MMA(ai, bj, At, Bt) do { __builtin_amdgcn_s_setprio(1); _Pragma("unroll") for (int m = 0; m < 4; ++m) _Pragma("unroll") for (int n = 0; n < 2; ++n) _Pragma("unroll") for (int k = 0; k < 2; ++k) \
;     acc[ai][bj][m][n] = __builtin_amdgcn_mfma_f32_16x16x32_bf16(Bt[n][k], At[m][k], acc[ai][bj][m][n], 0, 0, 0); __builtin_amdgcn_s_setprio(0); } while (0)
; #define PG8_WAIT_V(n) asm volatile("s_waitcnt vmcnt(" #n ")" ::: "memory")
; #define PG8_WAIT_L(n) asm volatile("s_waitcnt lgkmcnt(" #n ")" ::: "memory")
; #define PG8_BAR __builtin_amdgcn_s_barrier()
; #define PG8_SCHED __builtin_amdgcn_sched_barrier(0)
; template <class Epi>
; DI void gemm_phase(LAS unsigned char* lds, const Gemm g, const StaticOrder& S, const Epi& E) {
;     ...
;     for (int t = 0; t < nt; t += 2) {
;       const bool last = (t == nt - 2);
;       const char* a1 = cA + PG8_AK(t + 1);
;       const char* a2 = last ? nA : cA + PG8_AK(t + 2); const char* b2 = last ? nB : cB + (size_t)(t + 2) * kstep;
;       const char* a3 = a2 + kstep; const char* b3 = b2 + kstep;
;       PG8_LDB(B0, 0, 0); PG8_SCHED; PG8_LDA(At, 0, 0); PG8_STAGE(PG8_SA(1, 1), a1 + hstepA, voffA);
;       PG8_WAIT_L(8); PG8_BAR; PG8_WAIT_L(0); PG8_MMA(0, 0, At, B0); PG8_BAR; PG8_SCHED;
;       PG8_LDB(B1, 0, 1); PG8_STAGE(PG8_SB(0, 0), b2, voffB);
;       PG8_BAR; PG8_WAIT_L(0); PG8_MMA(0, 1, At, B1); PG8_BAR;
;       PG8_LDA(At, 0, 1); PG8_STAGE(PG8_SA(0, 0), a2, voffA);
;       PG8_BAR; PG8_WAIT_L(0); PG8_MMA(1, 0, At, B0); PG8_BAR; PG8_SCHED;
;       PG8_STAGE(PG8_SB(0, 1), b2 + hstepB, voffB);
;       PG8_WAIT_V(6); PG8_BAR; PG8_MMA(1, 1, At, B1); PG8_BAR;
.LBB0_921:
	ds_read_b128 v[154:157], v151
	ds_read_b128 v[158:161], v151 offset:1024
	ds_read_b128 v[162:165], v151 offset:2048
	ds_read_b128 v[166:169], v151 offset:3072
	s_add_u32 s20, s18, 0xfff80080
	s_addc_u32 s21, s19, -1
	s_cmp_eq_u32 s46, 28
	s_cselect_b32 s23, s11, s21
	s_cselect_b32 s22, s42, s20
	s_cselect_b32 s21, s9, s45
	s_cselect_b32 s20, s43, s44
	v_lshl_add_u64 v[148:149], s[18:19], 0, v[140:141]
	s_add_i32 m0, s17, 0xc000
	ds_read_b128 v[170:173], v152
	ds_read_b128 v[174:177], v152 offset:1024
	ds_read_b128 v[178:181], v152 offset:2048
	ds_read_b128 v[182:185], v152 offset:3072
	ds_read_b128 v[186:189], v152 offset:4096
	ds_read_b128 v[190:193], v152 offset:5120
	ds_read_b128 v[194:197], v152 offset:6144
	ds_read_b128 v[198:201], v152 offset:7168
	global_load_lds_dwordx4 v[148:149], off
	v_lshl_add_u64 v[148:149], s[18:19], 0, v[142:143]
	s_add_i32 m0, s17, 0xe000
	s_nop 0
	global_load_lds_dwordx4 v[148:149], off
	s_waitcnt lgkmcnt(8)
	s_barrier
	s_waitcnt lgkmcnt(0)
	s_waitcnt lgkmcnt(0)
	v_mfma_f32_16x16x32_bf16 v[126:129], v[154:157], v[170:173], v[126:129]
	v_mfma_f32_16x16x32_bf16 v[122:125], v[162:165], v[170:173], v[122:125]
	v_mfma_f32_16x16x32_bf16 v[110:113], v[154:157], v[178:181], v[110:113]
	v_mfma_f32_16x16x32_bf16 v[106:109], v[162:165], v[178:181], v[106:109]
	v_mfma_f32_16x16x32_bf16 v[94:97], v[154:157], v[186:189], v[94:97]
	v_mfma_f32_16x16x32_bf16 v[90:93], v[162:165], v[186:189], v[90:93]
	v_mfma_f32_16x16x32_bf16 v[78:81], v[154:157], v[194:197], v[78:81]
	v_mfma_f32_16x16x32_bf16 v[74:77], v[162:165], v[194:197], v[74:77]
	v_mfma_f32_16x16x32_bf16 v[126:129], v[158:161], v[174:177], v[126:129]
	v_mfma_f32_16x16x32_bf16 v[122:125], v[166:169], v[174:177], v[122:125]
	v_mfma_f32_16x16x32_bf16 v[110:113], v[158:161], v[182:185], v[110:113]
	v_mfma_f32_16x16x32_bf16 v[106:109], v[166:169], v[182:185], v[106:109]
	v_mfma_f32_16x16x32_bf16 v[94:97], v[158:161], v[190:193], v[94:97]
	v_mfma_f32_16x16x32_bf16 v[90:93], v[166:169], v[190:193], v[90:93]
	v_mfma_f32_16x16x32_bf16 v[78:81], v[158:161], v[198:201], v[78:81]
	v_mfma_f32_16x16x32_bf16 v[74:77], v[166:169], v[198:201], v[74:77]
	s_barrier
	s_add_i32 s47, s39, s30
	v_lshl_add_u64 v[148:149], s[20:21], 0, v[132:133]
	s_mov_b32 m0, s47
	ds_read_b128 v[202:205], v153
	ds_read_b128 v[206:209], v153 offset:1024
	ds_read_b128 v[210:213], v153 offset:2048
	ds_read_b128 v[214:217], v153 offset:3072
	global_load_lds_dwordx4 v[148:149], off
	v_lshl_add_u64 v[218:219], s[20:21], 0, v[136:137]
	s_add_i32 m0, s47, 0x2000
	s_nop 0
	global_load_lds_dwordx4 v[218:219], off
	s_barrier
	s_waitcnt lgkmcnt(0)
	s_waitcnt lgkmcnt(0)
	v_mfma_f32_16x16x32_bf16 v[118:121], v[202:205], v[170:173], v[118:121]
	v_mfma_f32_16x16x32_bf16 v[114:117], v[210:213], v[170:173], v[114:117]
	v_mfma_f32_16x16x32_bf16 v[102:105], v[202:205], v[178:181], v[102:105]
	v_mfma_f32_16x16x32_bf16 v[98:101], v[210:213], v[178:181], v[98:101]
	v_mfma_f32_16x16x32_bf16 v[86:89], v[202:205], v[186:189], v[86:89]
	v_mfma_f32_16x16x32_bf16 v[82:85], v[210:213], v[186:189], v[82:85]
	v_mfma_f32_16x16x32_bf16 v[70:73], v[202:205], v[194:197], v[70:73]
	v_mfma_f32_16x16x32_bf16 v[66:69], v[210:213], v[194:197], v[66:69]
	v_mfma_f32_16x16x32_bf16 v[118:121], v[206:209], v[174:177], v[118:121]
	v_mfma_f32_16x16x32_bf16 v[114:117], v[214:217], v[174:177], v[114:117]
	v_mfma_f32_16x16x32_bf16 v[102:105], v[206:209], v[182:185], v[102:105]
	v_mfma_f32_16x16x32_bf16 v[98:101], v[214:217], v[182:185], v[98:101]
	v_mfma_f32_16x16x32_bf16 v[86:89], v[206:209], v[190:193], v[86:89]
	v_mfma_f32_16x16x32_bf16 v[82:85], v[214:217], v[190:193], v[82:85]
	v_mfma_f32_16x16x32_bf16 v[70:73], v[206:209], v[198:201], v[70:73]
	v_mfma_f32_16x16x32_bf16 v[66:69], v[214:217], v[198:201], v[66:69]
	s_mov_b32 m0, s17
	v_lshl_add_u64 v[220:221], s[22:23], 0, v[130:131]
	s_barrier
	ds_read_b128 v[170:173], v152 offset:16384
	ds_read_b128 v[174:177], v152 offset:17408
	ds_read_b128 v[178:181], v152 offset:18432
	ds_read_b128 v[182:185], v152 offset:19456
	ds_read_b128 v[186:189], v152 offset:20480
	ds_read_b128 v[190:193], v152 offset:21504
	ds_read_b128 v[194:197], v152 offset:22528
	ds_read_b128 v[198:201], v152 offset:23552
	global_load_lds_dwordx4 v[220:221], off
	v_lshl_add_u64 v[222:223], s[22:23], 0, v[134:135]
	s_mov_b32 m0, s31
	s_nop 0
	global_load_lds_dwordx4 v[222:223], off
	s_barrier
	s_waitcnt lgkmcnt(0)
	s_waitcnt lgkmcnt(0)
	v_mfma_f32_16x16x32_bf16 v[62:65], v[154:157], v[170:173], v[62:65]
	v_mfma_f32_16x16x32_bf16 v[58:61], v[162:165], v[170:173], v[58:61]
	v_mfma_f32_16x16x32_bf16 v[46:49], v[154:157], v[178:181], v[46:49]
	v_mfma_f32_16x16x32_bf16 v[42:45], v[162:165], v[178:181], v[42:45]
	v_mfma_f32_16x16x32_bf16 v[30:33], v[154:157], v[186:189], v[30:33]
	v_mfma_f32_16x16x32_bf16 v[26:29], v[162:165], v[186:189], v[26:29]
	v_mfma_f32_16x16x32_bf16 v[14:17], v[154:157], v[194:197], v[14:17]
	v_mfma_f32_16x16x32_bf16 v[10:13], v[162:165], v[194:197], v[10:13]
	v_mfma_f32_16x16x32_bf16 v[62:65], v[158:161], v[174:177], v[62:65]
	v_mfma_f32_16x16x32_bf16 v[58:61], v[166:169], v[174:177], v[58:61]
	v_mfma_f32_16x16x32_bf16 v[46:49], v[158:161], v[182:185], v[46:49]
	v_mfma_f32_16x16x32_bf16 v[42:45], v[166:169], v[182:185], v[42:45]
	v_mfma_f32_16x16x32_bf16 v[30:33], v[158:161], v[190:193], v[30:33]
	v_mfma_f32_16x16x32_bf16 v[26:29], v[166:169], v[190:193], v[26:29]
	v_mfma_f32_16x16x32_bf16 v[14:17], v[158:161], v[198:201], v[14:17]
	v_mfma_f32_16x16x32_bf16 v[10:13], v[166:169], v[198:201], v[10:13]
	s_barrier
; #define PG8_STAGE(bufoff, gbase, voff) do { _Pragma("unroll") for (int _i = 0; _i < 2; ++_i) \
;     __builtin_amdgcn_global_load_lds((const unsigned*)((const char*)(gbase) + (voff)[_i]), (LAS unsigned*)(lds + (bufoff) + ldsw + _i * 8192), 16, 0, 0); } while (0)
; #define PG8_LDA(dst, b, h) do { _Pragma("unroll") for (int m = 0; m < 4; ++m) _Pragma("unroll") for (int k = 0; k < 2; ++k) dst[m][k] = *(const LAS bf16x8*)(lds + PG8_SA(b, h) + aoff + m * 2048 + k * 1024); } while (0)
; #define PG8_LDB(dst, b, h) do { _Pragma("unroll") for (int n = 0; n < 2; ++n) _Pragma("unroll") for (int k = 0; k < 2; ++k) dst[n][k] = *(const LAS bf16x8*)(lds + PG8_SB(b, h) + boff + n * 2048 + k * 1024); } while (0)
; #define PG8_MMA(ai, bj, At, Bt) do { __builtin_amdgcn_s_setprio(1); _Pragma("unroll") for (int m = 0; m < 4; ++m) _Pragma("unroll") for (int n = 0; n < 2; ++n) _Pragma("unroll") for (int k = 0; k < 2; ++k) \
;     acc[ai][bj][m][n] = __builtin_amdgcn_mfma_f32_16x16x32_bf16(Bt[n][k], At[m][k], acc[ai][bj][m][n], 0, 0, 0); __builtin_amdgcn_s_setprio(0); } while (0)
; #define PG8_WAIT_V(n) asm volatile("s_waitcnt vmcnt(" #n ")" ::: "memory")
; #define PG8_WAIT_L(n) asm volatile("s_waitcnt lgkmcnt(" #n ")" ::: "memory")
; #define PG8_BAR __builtin_amdgcn_s_barrier()
; #define PG8_SCHED __builtin_amdgcn_sched_barrier(0)
; template <class Epi>
; DI void gemm_phase(LAS unsigned char* lds, const Gemm g, const StaticOrder& S, const Epi& E) {
;     ...
;       PG8_STAGE(PG8_SB(0, 1), b2 + hstepB, voffB);
;       PG8_WAIT_V(6); PG8_BAR; PG8_MMA(1, 1, At, B1); PG8_BAR;
;       PG8_LDB(B0, 1, 0); PG8_SCHED; PG8_LDA(At, 1, 0); PG8_STAGE(PG8_SA(0, 1), a2 + hstepA, voffA);
;       PG8_WAIT_L(8); PG8_BAR; PG8_WAIT_L(0); PG8_MMA(0, 0, At, B0); PG8_BAR; PG8_SCHED;
;       PG8_LDB(B1, 1, 1); PG8_STAGE(PG8_SB(1, 0), b3, voffB);
;       PG8_BAR; PG8_WAIT_L(0); PG8_MMA(0, 1, At, B1); PG8_BAR;
;       PG8_LDA(At, 1, 1); PG8_STAGE(PG8_SA(1, 0), a3, voffA);
;       PG8_BAR; PG8_WAIT_L(0); PG8_MMA(1, 0, At, B0); PG8_BAR; PG8_SCHED;
	s_add_u32 s48, s20, 0x80000
	s_addc_u32 s49, s21, 0
	s_add_i32 s47, s40, s30
	v_lshl_add_u64 v[154:155], s[48:49], 0, v[132:133]
	s_mov_b32 m0, s47
	s_nop 0
	global_load_lds_dwordx4 v[154:155], off
	v_lshl_add_u64 v[154:155], s[48:49], 0, v[136:137]
	s_add_i32 m0, s47, 0x2000
	s_nop 0
	global_load_lds_dwordx4 v[154:155], off
	s_waitcnt vmcnt(6)
	s_barrier
	v_mfma_f32_16x16x32_bf16 v[54:57], v[202:205], v[170:173], v[54:57]
	v_mfma_f32_16x16x32_bf16 v[50:53], v[210:213], v[170:173], v[50:53]
	v_mfma_f32_16x16x32_bf16 v[38:41], v[202:205], v[178:181], v[38:41]
	v_mfma_f32_16x16x32_bf16 v[34:37], v[210:213], v[178:181], v[34:37]
	v_mfma_f32_16x16x32_bf16 v[22:25], v[202:205], v[186:189], v[22:25]
	v_mfma_f32_16x16x32_bf16 v[18:21], v[210:213], v[186:189], v[18:21]
	v_mfma_f32_16x16x32_bf16 v[6:9], v[202:205], v[194:197], v[6:9]
	v_mfma_f32_16x16x32_bf16 v[2:5], v[210:213], v[194:197], v[2:5]
	v_mfma_f32_16x16x32_bf16 v[54:57], v[206:209], v[174:177], v[54:57]
	v_mfma_f32_16x16x32_bf16 v[50:53], v[214:217], v[174:177], v[50:53]
	v_mfma_f32_16x16x32_bf16 v[38:41], v[206:209], v[182:185], v[38:41]
	v_mfma_f32_16x16x32_bf16 v[34:37], v[214:217], v[182:185], v[34:37]
	v_mfma_f32_16x16x32_bf16 v[22:25], v[206:209], v[190:193], v[22:25]
	v_mfma_f32_16x16x32_bf16 v[18:21], v[214:217], v[190:193], v[18:21]
	v_mfma_f32_16x16x32_bf16 v[6:9], v[206:209], v[198:201], v[6:9]
	v_mfma_f32_16x16x32_bf16 v[2:5], v[214:217], v[198:201], v[2:5]
	s_add_i32 s47, 0, 0x18000
	v_add_u32_e32 v166, s47, v150
	s_barrier
	ds_read_b128 v[154:157], v166
	ds_read_b128 v[158:161], v166 offset:1024
	ds_read_b128 v[162:165], v166 offset:2048
	ds_read_b128 v[166:169], v166 offset:3072
	s_add_u32 s22, s22, 0x80000
	s_addc_u32 s23, s23, 0
	s_mov_b32 m0, s33
	v_lshl_add_u64 v[202:203], s[22:23], 0, v[130:131]
	ds_read_b128 v[170:173], v152 offset:32768
	ds_read_b128 v[174:177], v152 offset:33792
	ds_read_b128 v[178:181], v152 offset:34816
	ds_read_b128 v[182:185], v152 offset:35840
	ds_read_b128 v[186:189], v152 offset:36864
	ds_read_b128 v[190:193], v152 offset:37888
	ds_read_b128 v[194:197], v152 offset:38912
	ds_read_b128 v[198:201], v152 offset:39936
	global_load_lds_dwordx4 v[202:203], off
	v_lshl_add_u64 v[202:203], s[22:23], 0, v[134:135]
	s_mov_b32 m0, s34
	s_nop 0
	global_load_lds_dwordx4 v[202:203], off
	s_waitcnt lgkmcnt(8)
	s_barrier
	s_waitcnt lgkmcnt(0)
	s_waitcnt lgkmcnt(0)
	v_mfma_f32_16x16x32_bf16 v[126:129], v[154:157], v[170:173], v[126:129]
	v_mfma_f32_16x16x32_bf16 v[122:125], v[162:165], v[170:173], v[122:125]
	v_mfma_f32_16x16x32_bf16 v[110:113], v[154:157], v[178:181], v[110:113]
	v_mfma_f32_16x16x32_bf16 v[106:109], v[162:165], v[178:181], v[106:109]
	v_mfma_f32_16x16x32_bf16 v[94:97], v[154:157], v[186:189], v[94:97]
	v_mfma_f32_16x16x32_bf16 v[90:93], v[162:165], v[186:189], v[90:93]
	v_mfma_f32_16x16x32_bf16 v[78:81], v[154:157], v[194:197], v[78:81]
	v_mfma_f32_16x16x32_bf16 v[74:77], v[162:165], v[194:197], v[74:77]
	v_mfma_f32_16x16x32_bf16 v[126:129], v[158:161], v[174:177], v[126:129]
	v_mfma_f32_16x16x32_bf16 v[122:125], v[166:169], v[174:177], v[122:125]
	v_mfma_f32_16x16x32_bf16 v[110:113], v[158:161], v[182:185], v[110:113]
	v_mfma_f32_16x16x32_bf16 v[106:109], v[166:169], v[182:185], v[106:109]
	v_mfma_f32_16x16x32_bf16 v[94:97], v[158:161], v[190:193], v[94:97]
	v_mfma_f32_16x16x32_bf16 v[90:93], v[166:169], v[190:193], v[90:93]
	v_mfma_f32_16x16x32_bf16 v[78:81], v[158:161], v[198:201], v[78:81]
	v_mfma_f32_16x16x32_bf16 v[74:77], v[166:169], v[198:201], v[74:77]
	s_barrier
	s_add_i32 s22, 0, 0x1c000
	s_add_i32 s23, s47, s30
	v_add_u32_e32 v214, s22, v150
	v_lshl_add_u64 v[148:149], v[148:149], 0, s[2:3]
	s_mov_b32 m0, s23
	ds_read_b128 v[202:205], v214
	ds_read_b128 v[206:209], v214 offset:1024
	ds_read_b128 v[210:213], v214 offset:2048
	ds_read_b128 v[214:217], v214 offset:3072
	global_load_lds_dwordx4 v[148:149], off
	v_lshl_add_u64 v[148:149], v[218:219], 0, s[2:3]
	s_add_i32 m0, s23, 0x2000
	s_nop 0
	global_load_lds_dwordx4 v[148:149], off
	s_barrier
	s_waitcnt lgkmcnt(0)
	s_waitcnt lgkmcnt(0)
	v_mfma_f32_16x16x32_bf16 v[118:121], v[202:205], v[170:173], v[118:121]
	v_mfma_f32_16x16x32_bf16 v[114:117], v[210:213], v[170:173], v[114:117]
	v_mfma_f32_16x16x32_bf16 v[102:105], v[202:205], v[178:181], v[102:105]
	v_mfma_f32_16x16x32_bf16 v[98:101], v[210:213], v[178:181], v[98:101]
	v_mfma_f32_16x16x32_bf16 v[86:89], v[202:205], v[186:189], v[86:89]
	v_mfma_f32_16x16x32_bf16 v[82:85], v[210:213], v[186:189], v[82:85]
	v_mfma_f32_16x16x32_bf16 v[70:73], v[202:205], v[194:197], v[70:73]
	v_mfma_f32_16x16x32_bf16 v[66:69], v[210:213], v[194:197], v[66:69]
	v_mfma_f32_16x16x32_bf16 v[118:121], v[206:209], v[174:177], v[118:121]
	v_mfma_f32_16x16x32_bf16 v[114:117], v[214:217], v[174:177], v[114:117]
	v_mfma_f32_16x16x32_bf16 v[102:105], v[206:209], v[182:185], v[102:105]
	v_mfma_f32_16x16x32_bf16 v[98:101], v[214:217], v[182:185], v[98:101]
	v_mfma_f32_16x16x32_bf16 v[86:89], v[206:209], v[190:193], v[86:89]
	v_mfma_f32_16x16x32_bf16 v[82:85], v[214:217], v[190:193], v[82:85]
	v_mfma_f32_16x16x32_bf16 v[70:73], v[206:209], v[198:201], v[70:73]
	v_mfma_f32_16x16x32_bf16 v[66:69], v[214:217], v[198:201], v[66:69]
	s_mov_b32 m0, s36
	v_lshl_add_u64 v[148:149], v[220:221], 0, s[2:3]
	s_barrier
	ds_read_b128 v[170:173], v152 offset:49152
	ds_read_b128 v[174:177], v152 offset:50176
	ds_read_b128 v[178:181], v152 offset:51200
	ds_read_b128 v[182:185], v152 offset:52224
	ds_read_b128 v[186:189], v152 offset:53248
	ds_read_b128 v[190:193], v152 offset:54272
	ds_read_b128 v[194:197], v152 offset:55296
	ds_read_b128 v[198:201], v152 offset:56320
	global_load_lds_dwordx4 v[148:149], off
	v_lshl_add_u64 v[148:149], v[222:223], 0, s[2:3]
	s_mov_b32 m0, s37
	s_nop 0
	global_load_lds_dwordx4 v[148:149], off
	s_barrier
; template <class Epi>
; DI void gemm_phase(LAS unsigned char* lds, const Gemm g, const StaticOrder& S, const Epi& E) {
;     ...
;       PG8_BAR; PG8_WAIT_L(0); PG8_MMA(1, 0, At, B0); PG8_BAR; PG8_SCHED;
;       PG8_STAGE(PG8_SB(1, 1), b3 + hstepB, voffB);
;       PG8_WAIT_V(6); PG8_BAR; PG8_MMA(1, 1, At, B1); PG8_BAR;
;     }
;   DI void operator()(const f32x4 (&acc)[2][2][4][2], const pg8::Unit& u, int wr, int wc, int fr, int fq) const {
;     ...
;         if (MODE == EP_UP) rs = ((const float*)(ws + OFF_RS2))[grow];
;         if (MODE == EP_Q || MODE == EP_KV) {
;           const f32x4* sp = (const f32x4*)(ws + OFF_SSQA) + (size_t)grow * 4 + (MODE == EP_KV ? 2 : 0);
;           const f32x4 s0 = sp[0], s1 = sp[1];
;           const float ss = (s0[0] + s0[1]) + (s0[2] + s0[3]) + (s1[0] + s1[1]) + (s1[2] + s1[3]);
;           rs = __builtin_amdgcn_rsqf(ss * (1.0f / 512) + EPS);
;           if (MODE == EP_Q) rs *= QSCALE;
;         }
;         float ssq = 0.f;
; #pragma unroll
;         for (int bj = 0; bj < 2; ++bj) {
;           f32x4 v0 = acc[ai][bj][m][0] * rs, v1 = acc[ai][bj][m][1] * rs;
;           if (MODE == EP_IN || MODE == EP_MIX || MODE == EP_DOWN) {
; #pragma unroll
;             for (int j = 0; j < 4; ++j) ssq += v0[j] * v0[j] + v1[j] * v1[j];
;           }
;           if (MODE == EP_UP) {
; #pragma unroll
;             for (int j = 0; j < 4; ++j) { float a = fmaxf(v0[j], 0.f), b = fmaxf(v1[j], 0.f); v0[j] = a * a; v1[j] = b * b; }
;           }
;           bf16_t* dst;
;           const int ct = bj * 128 + cl;
;           if (MODE == EP_IN) {
;             if (pn < 4) dst = (bf16_t*)(ws + OFF_PROJA) + (size_t)grow * 1024 + pn * 256 + ct;
;             else if (pn < 16) dst = (bf16_t*)(ws + OFF_PROJG) + (size_t)grow * 3072 + (pn - 4) * 256 + ct;
;             else dst = (bf16_t*)(ws + OFF_PROJS) + (size_t)grow * 256 + ct;
;           } else if (MODE == EP_Q) {
;             if (pn < 4) dst = (bf16_t*)(dout + DO_Q) + (size_t)grow * 1536 + (pn * 2 + bj) * 192 + cl;
;             else {
;               const int mm = (pn - 4) * 256 + ct, h = mm >> 6, r = mm & 63;
;               dst = (bf16_t*)(dout + DO_Q) + (size_t)grow * 1536 + h * 192 + 128 + r;
;               const int pos = grow < TP ? (grow & 4095) : grow - TP;
;               const f32x4* tb = (const f32x4*)((const f32x2*)(ws + OFF_ROPE) + pos * 32 + (r >> 1));
	s_waitcnt lgkmcnt(0)
	s_waitcnt lgkmcnt(0)
	v_mfma_f32_16x16x32_bf16 v[62:65], v[154:157], v[170:173], v[62:65]
	v_mfma_f32_16x16x32_bf16 v[58:61], v[162:165], v[170:173], v[58:61]
	v_mfma_f32_16x16x32_bf16 v[46:49], v[154:157], v[178:181], v[46:49]
	v_mfma_f32_16x16x32_bf16 v[42:45], v[162:165], v[178:181], v[42:45]
	v_mfma_f32_16x16x32_bf16 v[30:33], v[154:157], v[186:189], v[30:33]
	v_mfma_f32_16x16x32_bf16 v[26:29], v[162:165], v[186:189], v[26:29]
	v_mfma_f32_16x16x32_bf16 v[14:17], v[154:157], v[194:197], v[14:17]
	v_mfma_f32_16x16x32_bf16 v[10:13], v[162:165], v[194:197], v[10:13]
	v_mfma_f32_16x16x32_bf16 v[62:65], v[158:161], v[174:177], v[62:65]
	v_mfma_f32_16x16x32_bf16 v[58:61], v[166:169], v[174:177], v[58:61]
	v_mfma_f32_16x16x32_bf16 v[46:49], v[158:161], v[182:185], v[46:49]
	v_mfma_f32_16x16x32_bf16 v[42:45], v[166:169], v[182:185], v[42:45]
	v_mfma_f32_16x16x32_bf16 v[30:33], v[158:161], v[190:193], v[30:33]
	v_mfma_f32_16x16x32_bf16 v[26:29], v[166:169], v[190:193], v[26:29]
	v_mfma_f32_16x16x32_bf16 v[14:17], v[158:161], v[198:201], v[14:17]
	v_mfma_f32_16x16x32_bf16 v[10:13], v[166:169], v[198:201], v[10:13]
	s_barrier
	s_add_u32 s20, s20, 0x80080
	s_addc_u32 s21, s21, 0
	s_add_i32 s22, s22, s30
	v_lshl_add_u64 v[148:149], s[20:21], 0, v[132:133]
	s_mov_b32 m0, s22
	s_nop 0
	global_load_lds_dwordx4 v[148:149], off
	v_lshl_add_u64 v[148:149], s[20:21], 0, v[136:137]
	s_add_i32 m0, s22, 0x2000
	s_nop 0
	global_load_lds_dwordx4 v[148:149], off
	s_waitcnt vmcnt(6)
	s_barrier
	v_mfma_f32_16x16x32_bf16 v[54:57], v[202:205], v[170:173], v[54:57]
	v_mfma_f32_16x16x32_bf16 v[50:53], v[210:213], v[170:173], v[50:53]
	v_mfma_f32_16x16x32_bf16 v[38:41], v[202:205], v[178:181], v[38:41]
	v_mfma_f32_16x16x32_bf16 v[34:37], v[210:213], v[178:181], v[34:37]
	v_mfma_f32_16x16x32_bf16 v[22:25], v[202:205], v[186:189], v[22:25]
	v_mfma_f32_16x16x32_bf16 v[18:21], v[210:213], v[186:189], v[18:21]
	v_mfma_f32_16x16x32_bf16 v[6:9], v[202:205], v[194:197], v[6:9]
	v_mfma_f32_16x16x32_bf16 v[2:5], v[210:213], v[194:197], v[2:5]
	v_mfma_f32_16x16x32_bf16 v[54:57], v[206:209], v[174:177], v[54:57]
	v_mfma_f32_16x16x32_bf16 v[50:53], v[214:217], v[174:177], v[50:53]
	v_mfma_f32_16x16x32_bf16 v[38:41], v[206:209], v[182:185], v[38:41]
	v_mfma_f32_16x16x32_bf16 v[34:37], v[214:217], v[182:185], v[34:37]
	v_mfma_f32_16x16x32_bf16 v[22:25], v[206:209], v[190:193], v[22:25]
	v_mfma_f32_16x16x32_bf16 v[18:21], v[214:217], v[190:193], v[18:21]
	v_mfma_f32_16x16x32_bf16 v[6:9], v[206:209], v[198:201], v[6:9]
	v_mfma_f32_16x16x32_bf16 v[2:5], v[214:217], v[198:201], v[2:5]
	s_add_i32 s46, s46, 2
	s_add_u32 s18, s18, 0x100
	s_addc_u32 s19, s19, 0
	s_add_u32 s44, s44, 0x100
	s_addc_u32 s45, s45, 0
	s_cmp_gt_u32 s46, 29
	s_barrier
	s_cbranch_scc0 .LBB0_921
	v_lshl_add_u32 v148, s16, 8, v1
	v_ashrrev_i32_e32 v149, 31, v148
	v_lshl_add_u64 v[154:155], v[148:149], 2, s[4:5]
	s_nop 0
	s_lshl_b32 s18, s41, 8
	s_ashr_i32 s19, s18, 31
	v_lshlrev_b64 v[158:159], 14, v[148:149]
	s_lshl_b64 s[18:19], s[18:19], 1
	v_lshl_add_u64 v[158:159], s[6:7], 0, v[158:159]
	v_or_b32_e32 v156, 16, v148
	v_lshl_add_u64 v[158:159], v[158:159], 0, s[18:19]
	v_ashrrev_i32_e32 v157, 31, v156
	v_lshl_add_u64 v[158:159], v[158:159], 0, v[138:139]
	v_lshl_add_u64 v[160:161], v[156:157], 2, s[4:5]
	s_and_b64 vcc, exec, s[0:1]
	s_mov_b32 s41, s8
	s_mov_b32 s16, s10
	s_mov_b64 s[20:21], s[14:15]
	s_mov_b64 s[22:23], s[12:13]
	v_mov_b32_e32 v154, v247
	v_pk_mul_f32 v[128:129], v[128:129], v[154:155] op_sel_hi:[1,0]
	v_pk_mul_f32 v[126:127], v[126:127], v[154:155] op_sel_hi:[1,0]
	v_pk_mul_f32 v[124:125], v[124:125], v[154:155] op_sel_hi:[1,0]
	v_pk_mul_f32 v[122:123], v[122:123], v[154:155] op_sel_hi:[1,0]
	v_pk_mul_f32 v[120:121], v[120:121], v[154:155] op_sel_hi:[1,0]
	v_pk_mul_f32 v[118:119], v[118:119], v[154:155] op_sel_hi:[1,0]
	v_pk_mul_f32 v[116:117], v[116:117], v[154:155] op_sel_hi:[1,0]
	v_pk_mul_f32 v[114:115], v[114:115], v[154:155] op_sel_hi:[1,0]
	v_max_f32_e32 v126, 0, v126
	v_max_f32_e32 v122, 0, v122
	v_max_f32_e32 v127, 0, v127
	v_max_f32_e32 v123, 0, v123
	v_max_f32_e32 v128, 0, v128
	v_max_f32_e32 v124, 0, v124
	v_max_f32_e32 v129, 0, v129
	v_max_f32_e32 v125, 0, v125
	v_max_f32_e32 v118, 0, v118
	v_max_f32_e32 v114, 0, v114
	v_max_f32_e32 v119, 0, v119
	v_max_f32_e32 v115, 0, v115
	v_max_f32_e32 v120, 0, v120
	v_max_f32_e32 v116, 0, v116
	v_max_f32_e32 v121, 0, v121
	v_max_f32_e32 v117, 0, v117
	v_pk_mul_f32 v[126:127], v[126:127], v[126:127]
	v_pk_mul_f32 v[122:123], v[122:123], v[122:123]
	v_pk_mul_f32 v[128:129], v[128:129], v[128:129]
	v_pk_mul_f32 v[124:125], v[124:125], v[124:125]
	v_pk_mul_f32 v[118:119], v[118:119], v[118:119]
	v_pk_mul_f32 v[154:155], v[114:115], v[114:115]
	v_pk_mul_f32 v[120:121], v[120:121], v[120:121]
	v_pk_mul_f32 v[162:163], v[116:117], v[116:117]
	v_cvt_pk_bf16_f32 v114, v126, v127
	v_cvt_pk_bf16_f32 v115, v128, v129
	v_cvt_pk_bf16_f32 v116, v122, v123
	v_cvt_pk_bf16_f32 v117, v124, v125
	v_cvt_pk_bf16_f32 v118, v118, v119
	v_cvt_pk_bf16_f32 v119, v120, v121
	v_cvt_pk_bf16_f32 v120, v154, v155
	v_cvt_pk_bf16_f32 v121, v162, v163
	global_store_dwordx4 v[158:159], v[114:117], off
	global_store_dwordx4 v[158:159], v[118:121], off offset:256
	s_nop 0
	v_or_b32_e32 v116, 32, v148
	v_lshlrev_b64 v[118:119], 14, v[156:157]
	v_lshl_add_u64 v[118:119], s[6:7], 0, v[118:119]
	v_lshl_add_u64 v[118:119], v[118:119], 0, s[18:19]
	v_ashrrev_i32_e32 v117, 31, v116
	v_lshl_add_u64 v[118:119], v[118:119], 0, v[138:139]
	v_lshl_add_u64 v[120:121], v[116:117], 2, s[4:5]
	v_mov_b32_e32 v114, v240
	v_pk_mul_f32 v[112:113], v[112:113], v[114:115] op_sel_hi:[1,0]
;   DI void operator()(const f32x4 (&acc)[2][2][4][2], const pg8::Unit& u, int wr, int wc, int fr, int fq) const {
;     ...
;       for (int m = 0; m < 4; ++m) {
;         const int row = u.pm * 256 + ai * 128 + wr * 64 + m * 16 + fr;
;         const int grow = rowbase + row;
;         float rs = 1.f;
;         if (MODE == EP_IN) rs = ((const float*)(ws + OFF_RS0))[grow];
;         if (MODE == EP_UP) rs = ((const float*)(ws + OFF_RS2))[grow];
;         if (MODE == EP_Q || MODE == EP_KV) {
;           const f32x4* sp = (const f32x4*)(ws + OFF_SSQA) + (size_t)grow * 4 + (MODE == EP_KV ? 2 : 0);
;           const f32x4 s0 = sp[0], s1 = sp[1];
;           const float ss = (s0[0] + s0[1]) + (s0[2] + s0[3]) + (s1[0] + s1[1]) + (s1[2] + s1[3]);
;           rs = __builtin_amdgcn_rsqf(ss * (1.0f / 512) + EPS);
;           if (MODE == EP_Q) rs *= QSCALE;
;         }
;         float ssq = 0.f;
; #pragma unroll
;         for (int bj = 0; bj < 2; ++bj) {
;           f32x4 v0 = acc[ai][bj][m][0] * rs, v1 = acc[ai][bj][m][1] * rs;
;           if (MODE == EP_IN || MODE == EP_MIX || MODE == EP_DOWN) {
; #pragma unroll
;             for (int j = 0; j < 4; ++j) ssq += v0[j] * v0[j] + v1[j] * v1[j];
;           }
;           if (MODE == EP_UP) {
; #pragma unroll
;             for (int j = 0; j < 4; ++j) { float a = fmaxf(v0[j], 0.f), b = fmaxf(v1[j], 0.f); v0[j] = a * a; v1[j] = b * b; }
;           }
;           bf16_t* dst;
;           const int ct = bj * 128 + cl;
;           if (MODE == EP_IN) {
;             if (pn < 4) dst = (bf16_t*)(ws + OFF_PROJA) + (size_t)grow * 1024 + pn * 256 + ct;
;             else if (pn < 16) dst = (bf16_t*)(ws + OFF_PROJG) + (size_t)grow * 3072 + (pn - 4) * 256 + ct;
;             else dst = (bf16_t*)(ws + OFF_PROJS) + (size_t)grow * 256 + ct;
;           } else if (MODE == EP_Q) {
;             if (pn < 4) dst = (bf16_t*)(dout + DO_Q) + (size_t)grow * 1536 + (pn * 2 + bj) * 192 + cl;
;             else {
;               const int mm = (pn - 4) * 256 + ct, h = mm >> 6, r = mm & 63;
;               dst = (bf16_t*)(dout + DO_Q) + (size_t)grow * 1536 + h * 192 + 128 + r;
;               const int pos = grow < TP ? (grow & 4095) : grow - TP;
;               const f32x4* tb = (const f32x4*)((const f32x2*)(ws + OFF_ROPE) + pos * 32 + (r >> 1));
;               const f32x4 t0 = tb[0], t1 = tb[1];
;               f32x4 o0, o1;
	v_pk_mul_f32 v[110:111], v[110:111], v[114:115] op_sel_hi:[1,0]
	v_pk_mul_f32 v[108:109], v[108:109], v[114:115] op_sel_hi:[1,0]
	v_pk_mul_f32 v[106:107], v[106:107], v[114:115] op_sel_hi:[1,0]
	v_pk_mul_f32 v[104:105], v[104:105], v[114:115] op_sel_hi:[1,0]
	v_pk_mul_f32 v[102:103], v[102:103], v[114:115] op_sel_hi:[1,0]
	v_pk_mul_f32 v[100:101], v[100:101], v[114:115] op_sel_hi:[1,0]
	v_pk_mul_f32 v[98:99], v[98:99], v[114:115] op_sel_hi:[1,0]
	v_max_f32_e32 v110, 0, v110
	v_max_f32_e32 v106, 0, v106
	v_max_f32_e32 v111, 0, v111
	v_max_f32_e32 v107, 0, v107
	v_max_f32_e32 v112, 0, v112
	v_max_f32_e32 v108, 0, v108
	v_max_f32_e32 v113, 0, v113
	v_max_f32_e32 v109, 0, v109
	v_max_f32_e32 v102, 0, v102
	v_max_f32_e32 v98, 0, v98
	v_max_f32_e32 v103, 0, v103
	v_max_f32_e32 v99, 0, v99
	v_max_f32_e32 v104, 0, v104
	v_max_f32_e32 v100, 0, v100
	v_max_f32_e32 v105, 0, v105
	v_max_f32_e32 v101, 0, v101
	v_pk_mul_f32 v[110:111], v[110:111], v[110:111]
	v_pk_mul_f32 v[106:107], v[106:107], v[106:107]
	v_pk_mul_f32 v[112:113], v[112:113], v[112:113]
	v_pk_mul_f32 v[108:109], v[108:109], v[108:109]
	v_pk_mul_f32 v[102:103], v[102:103], v[102:103]
	v_pk_mul_f32 v[114:115], v[98:99], v[98:99]
	v_pk_mul_f32 v[104:105], v[104:105], v[104:105]
	v_pk_mul_f32 v[122:123], v[100:101], v[100:101]
	v_cvt_pk_bf16_f32 v98, v110, v111
	v_cvt_pk_bf16_f32 v99, v112, v113
	v_cvt_pk_bf16_f32 v100, v106, v107
	v_cvt_pk_bf16_f32 v101, v108, v109
	v_cvt_pk_bf16_f32 v102, v102, v103
	v_cvt_pk_bf16_f32 v103, v104, v105
	v_cvt_pk_bf16_f32 v104, v114, v115
	v_cvt_pk_bf16_f32 v105, v122, v123
	global_store_dwordx4 v[118:119], v[98:101], off
	global_store_dwordx4 v[118:119], v[102:105], off offset:256
	s_nop 0
	v_or_b32_e32 v100, 48, v148
	v_lshlrev_b64 v[102:103], 14, v[116:117]
	v_lshl_add_u64 v[102:103], s[6:7], 0, v[102:103]
	v_lshl_add_u64 v[102:103], v[102:103], 0, s[18:19]
	v_ashrrev_i32_e32 v101, 31, v100
	v_lshl_add_u64 v[102:103], v[102:103], 0, v[138:139]
	v_lshl_add_u64 v[104:105], v[100:101], 2, s[4:5]
	v_mov_b32_e32 v98, v241
	v_pk_mul_f32 v[96:97], v[96:97], v[98:99] op_sel_hi:[1,0]
	v_pk_mul_f32 v[94:95], v[94:95], v[98:99] op_sel_hi:[1,0]
	v_pk_mul_f32 v[92:93], v[92:93], v[98:99] op_sel_hi:[1,0]
	v_pk_mul_f32 v[90:91], v[90:91], v[98:99] op_sel_hi:[1,0]
	v_pk_mul_f32 v[88:89], v[88:89], v[98:99] op_sel_hi:[1,0]
	v_pk_mul_f32 v[86:87], v[86:87], v[98:99] op_sel_hi:[1,0]
	v_pk_mul_f32 v[84:85], v[84:85], v[98:99] op_sel_hi:[1,0]
	v_pk_mul_f32 v[82:83], v[82:83], v[98:99] op_sel_hi:[1,0]
	v_max_f32_e32 v94, 0, v94
	v_max_f32_e32 v90, 0, v90
	v_max_f32_e32 v95, 0, v95
	v_max_f32_e32 v91, 0, v91
	v_max_f32_e32 v96, 0, v96
	v_max_f32_e32 v92, 0, v92
	v_max_f32_e32 v97, 0, v97
	v_max_f32_e32 v93, 0, v93
	v_max_f32_e32 v86, 0, v86
	v_max_f32_e32 v82, 0, v82
	v_max_f32_e32 v87, 0, v87
	v_max_f32_e32 v83, 0, v83
	v_max_f32_e32 v88, 0, v88
	v_max_f32_e32 v84, 0, v84
	v_max_f32_e32 v89, 0, v89
	v_max_f32_e32 v85, 0, v85
	v_pk_mul_f32 v[94:95], v[94:95], v[94:95]
	v_pk_mul_f32 v[90:91], v[90:91], v[90:91]
	v_pk_mul_f32 v[96:97], v[96:97], v[96:97]
	v_pk_mul_f32 v[92:93], v[92:93], v[92:93]
	v_pk_mul_f32 v[86:87], v[86:87], v[86:87]
	v_pk_mul_f32 v[98:99], v[82:83], v[82:83]
	v_pk_mul_f32 v[88:89], v[88:89], v[88:89]
	v_pk_mul_f32 v[106:107], v[84:85], v[84:85]
	v_cvt_pk_bf16_f32 v82, v94, v95
	v_cvt_pk_bf16_f32 v83, v96, v97
	v_cvt_pk_bf16_f32 v84, v90, v91
	v_cvt_pk_bf16_f32 v85, v92, v93
	v_cvt_pk_bf16_f32 v86, v86, v87
	v_cvt_pk_bf16_f32 v87, v88, v89
	v_cvt_pk_bf16_f32 v88, v98, v99
	v_cvt_pk_bf16_f32 v89, v106, v107
	global_store_dwordx4 v[102:103], v[82:85], off
	global_store_dwordx4 v[102:103], v[86:89], off offset:256
	s_nop 0
	v_add_u32_e32 v84, 0x80, v148
	v_lshlrev_b64 v[86:87], 14, v[100:101]
	v_lshl_add_u64 v[86:87], s[6:7], 0, v[86:87]
	v_lshl_add_u64 v[86:87], v[86:87], 0, s[18:19]
	v_ashrrev_i32_e32 v85, 31, v84
	v_lshl_add_u64 v[86:87], v[86:87], 0, v[138:139]
	v_lshl_add_u64 v[88:89], v[84:85], 2, s[4:5]
	v_mov_b32_e32 v82, v242
	v_pk_mul_f32 v[80:81], v[80:81], v[82:83] op_sel_hi:[1,0]
	v_pk_mul_f32 v[78:79], v[78:79], v[82:83] op_sel_hi:[1,0]
	v_pk_mul_f32 v[76:77], v[76:77], v[82:83] op_sel_hi:[1,0]
	v_pk_mul_f32 v[74:75], v[74:75], v[82:83] op_sel_hi:[1,0]
	v_pk_mul_f32 v[72:73], v[72:73], v[82:83] op_sel_hi:[1,0]
	v_pk_mul_f32 v[70:71], v[70:71], v[82:83] op_sel_hi:[1,0]
	v_pk_mul_f32 v[68:69], v[68:69], v[82:83] op_sel_hi:[1,0]
	v_pk_mul_f32 v[66:67], v[66:67], v[82:83] op_sel_hi:[1,0]
	v_max_f32_e32 v78, 0, v78
	v_max_f32_e32 v74, 0, v74
	v_max_f32_e32 v79, 0, v79
	v_max_f32_e32 v75, 0, v75
	v_max_f32_e32 v80, 0, v80
	v_max_f32_e32 v76, 0, v76
	v_max_f32_e32 v81, 0, v81
	v_max_f32_e32 v77, 0, v77
	v_max_f32_e32 v70, 0, v70
	v_max_f32_e32 v66, 0, v66
	v_max_f32_e32 v71, 0, v71
	v_max_f32_e32 v67, 0, v67
	v_max_f32_e32 v72, 0, v72
	v_max_f32_e32 v68, 0, v68
	v_max_f32_e32 v73, 0, v73
	v_max_f32_e32 v69, 0, v69
	v_pk_mul_f32 v[78:79], v[78:79], v[78:79]
	v_pk_mul_f32 v[74:75], v[74:75], v[74:75]
	v_pk_mul_f32 v[80:81], v[80:81], v[80:81]
	v_pk_mul_f32 v[76:77], v[76:77], v[76:77]
	v_pk_mul_f32 v[70:71], v[70:71], v[70:71]
	v_pk_mul_f32 v[82:83], v[66:67], v[66:67]
	v_pk_mul_f32 v[72:73], v[72:73], v[72:73]
	v_pk_mul_f32 v[90:91], v[68:69], v[68:69]
	v_cvt_pk_bf16_f32 v66, v78, v79
	v_cvt_pk_bf16_f32 v67, v80, v81
	v_cvt_pk_bf16_f32 v68, v74, v75
	v_cvt_pk_bf16_f32 v69, v76, v77
	v_cvt_pk_bf16_f32 v70, v70, v71
	v_cvt_pk_bf16_f32 v71, v72, v73
	v_cvt_pk_bf16_f32 v72, v82, v83
	v_cvt_pk_bf16_f32 v73, v90, v91
	global_store_dwordx4 v[86:87], v[66:69], off
	global_store_dwordx4 v[86:87], v[70:73], off offset:256
	s_nop 0
	v_add_u32_e32 v68, 0x90, v148
;   DI void operator()(const f32x4 (&acc)[2][2][4][2], const pg8::Unit& u, int wr, int wc, int fr, int fq) const {
;     ...
;       for (int m = 0; m < 4; ++m) {
;         const int row = u.pm * 256 + ai * 128 + wr * 64 + m * 16 + fr;
;         const int grow = rowbase + row;
;         float rs = 1.f;
;         if (MODE == EP_IN) rs = ((const float*)(ws + OFF_RS0))[grow];
;         if (MODE == EP_UP) rs = ((const float*)(ws + OFF_RS2))[grow];
;         if (MODE == EP_Q || MODE == EP_KV) {
;           const f32x4* sp = (const f32x4*)(ws + OFF_SSQA) + (size_t)grow * 4 + (MODE == EP_KV ? 2 : 0);
;           const f32x4 s0 = sp[0], s1 = sp[1];
;           const float ss = (s0[0] + s0[1]) + (s0[2] + s0[3]) + (s1[0] + s1[1]) + (s1[2] + s1[3]);
;           rs = __builtin_amdgcn_rsqf(ss * (1.0f / 512) + EPS);
;           if (MODE == EP_Q) rs *= QSCALE;
;         }
;         float ssq = 0.f;
; #pragma unroll
;         for (int bj = 0; bj < 2; ++bj) {
;           f32x4 v0 = acc[ai][bj][m][0] * rs, v1 = acc[ai][bj][m][1] * rs;
;           if (MODE == EP_IN || MODE == EP_MIX || MODE == EP_DOWN) {
; #pragma unroll
;             for (int j = 0; j < 4; ++j) ssq += v0[j] * v0[j] + v1[j] * v1[j];
;           }
;           if (MODE == EP_UP) {
; #pragma unroll
;             for (int j = 0; j < 4; ++j) { float a = fmaxf(v0[j], 0.f), b = fmaxf(v1[j], 0.f); v0[j] = a * a; v1[j] = b * b; }
;           }
;           bf16_t* dst;
;           const int ct = bj * 128 + cl;
;           if (MODE == EP_IN) {
;             if (pn < 4) dst = (bf16_t*)(ws + OFF_PROJA) + (size_t)grow * 1024 + pn * 256 + ct;
;             else if (pn < 16) dst = (bf16_t*)(ws + OFF_PROJG) + (size_t)grow * 3072 + (pn - 4) * 256 + ct;
;             else dst = (bf16_t*)(ws + OFF_PROJS) + (size_t)grow * 256 + ct;
;           } else if (MODE == EP_Q) {
;             if (pn < 4) dst = (bf16_t*)(dout + DO_Q) + (size_t)grow * 1536 + (pn * 2 + bj) * 192 + cl;
;             else {
;               const int mm = (pn - 4) * 256 + ct, h = mm >> 6, r = mm & 63;
;               dst = (bf16_t*)(dout + DO_Q) + (size_t)grow * 1536 + h * 192 + 128 + r;
;               const int pos = grow < TP ? (grow & 4095) : grow - TP;
;               const f32x4* tb = (const f32x4*)((const f32x2*)(ws + OFF_ROPE) + pos * 32 + (r >> 1));
;               const f32x4 t0 = tb[0], t1 = tb[1];
;               f32x4 o0, o1;
	v_lshlrev_b64 v[70:71], 14, v[84:85]
	v_lshl_add_u64 v[70:71], s[6:7], 0, v[70:71]
	v_lshl_add_u64 v[70:71], v[70:71], 0, s[18:19]
	v_ashrrev_i32_e32 v69, 31, v68
	v_lshl_add_u64 v[70:71], v[70:71], 0, v[138:139]
	v_lshl_add_u64 v[72:73], v[68:69], 2, s[4:5]
	v_mov_b32_e32 v66, v243
	v_pk_mul_f32 v[64:65], v[64:65], v[66:67] op_sel_hi:[1,0]
	v_pk_mul_f32 v[62:63], v[62:63], v[66:67] op_sel_hi:[1,0]
	v_pk_mul_f32 v[60:61], v[60:61], v[66:67] op_sel_hi:[1,0]
	v_pk_mul_f32 v[58:59], v[58:59], v[66:67] op_sel_hi:[1,0]
	v_pk_mul_f32 v[56:57], v[56:57], v[66:67] op_sel_hi:[1,0]
	v_pk_mul_f32 v[54:55], v[54:55], v[66:67] op_sel_hi:[1,0]
	v_pk_mul_f32 v[52:53], v[52:53], v[66:67] op_sel_hi:[1,0]
	v_pk_mul_f32 v[50:51], v[50:51], v[66:67] op_sel_hi:[1,0]
	v_max_f32_e32 v62, 0, v62
	v_max_f32_e32 v58, 0, v58
	v_max_f32_e32 v63, 0, v63
	v_max_f32_e32 v59, 0, v59
	v_max_f32_e32 v64, 0, v64
	v_max_f32_e32 v60, 0, v60
	v_max_f32_e32 v65, 0, v65
	v_max_f32_e32 v61, 0, v61
	v_max_f32_e32 v54, 0, v54
	v_max_f32_e32 v50, 0, v50
	v_max_f32_e32 v55, 0, v55
	v_max_f32_e32 v51, 0, v51
	v_max_f32_e32 v56, 0, v56
	v_max_f32_e32 v52, 0, v52
	v_max_f32_e32 v57, 0, v57
	v_max_f32_e32 v53, 0, v53
	v_pk_mul_f32 v[62:63], v[62:63], v[62:63]
	v_pk_mul_f32 v[58:59], v[58:59], v[58:59]
	v_pk_mul_f32 v[64:65], v[64:65], v[64:65]
	v_pk_mul_f32 v[60:61], v[60:61], v[60:61]
	v_pk_mul_f32 v[54:55], v[54:55], v[54:55]
	v_pk_mul_f32 v[66:67], v[50:51], v[50:51]
	v_pk_mul_f32 v[56:57], v[56:57], v[56:57]
	v_pk_mul_f32 v[74:75], v[52:53], v[52:53]
	v_cvt_pk_bf16_f32 v50, v62, v63
	v_cvt_pk_bf16_f32 v51, v64, v65
	v_cvt_pk_bf16_f32 v52, v58, v59
	v_cvt_pk_bf16_f32 v53, v60, v61
	v_cvt_pk_bf16_f32 v54, v54, v55
	v_cvt_pk_bf16_f32 v55, v56, v57
	v_cvt_pk_bf16_f32 v56, v66, v67
	v_cvt_pk_bf16_f32 v57, v74, v75
	global_store_dwordx4 v[70:71], v[50:53], off
	global_store_dwordx4 v[70:71], v[54:57], off offset:256
	s_nop 0
	v_add_u32_e32 v52, 0xa0, v148
	v_lshlrev_b64 v[54:55], 14, v[68:69]
	v_lshl_add_u64 v[54:55], s[6:7], 0, v[54:55]
	v_lshl_add_u64 v[54:55], v[54:55], 0, s[18:19]
	v_ashrrev_i32_e32 v53, 31, v52
	v_lshl_add_u64 v[54:55], v[54:55], 0, v[138:139]
	v_lshl_add_u64 v[56:57], v[52:53], 2, s[4:5]
	v_mov_b32_e32 v50, v244
	v_pk_mul_f32 v[48:49], v[48:49], v[50:51] op_sel_hi:[1,0]
	v_pk_mul_f32 v[46:47], v[46:47], v[50:51] op_sel_hi:[1,0]
	v_pk_mul_f32 v[44:45], v[44:45], v[50:51] op_sel_hi:[1,0]
	v_pk_mul_f32 v[42:43], v[42:43], v[50:51] op_sel_hi:[1,0]
	v_pk_mul_f32 v[40:41], v[40:41], v[50:51] op_sel_hi:[1,0]
	v_pk_mul_f32 v[38:39], v[38:39], v[50:51] op_sel_hi:[1,0]
	v_pk_mul_f32 v[36:37], v[36:37], v[50:51] op_sel_hi:[1,0]
	v_pk_mul_f32 v[34:35], v[34:35], v[50:51] op_sel_hi:[1,0]
	v_max_f32_e32 v46, 0, v46
	v_max_f32_e32 v42, 0, v42
	v_max_f32_e32 v47, 0, v47
	v_max_f32_e32 v43, 0, v43
	v_max_f32_e32 v48, 0, v48
	v_max_f32_e32 v44, 0, v44
	v_max_f32_e32 v49, 0, v49
	v_max_f32_e32 v45, 0, v45
	v_max_f32_e32 v38, 0, v38
	v_max_f32_e32 v34, 0, v34
	v_max_f32_e32 v39, 0, v39
	v_max_f32_e32 v35, 0, v35
	v_max_f32_e32 v40, 0, v40
	v_max_f32_e32 v36, 0, v36
	v_max_f32_e32 v41, 0, v41
	v_max_f32_e32 v37, 0, v37
	v_pk_mul_f32 v[46:47], v[46:47], v[46:47]
	v_pk_mul_f32 v[42:43], v[42:43], v[42:43]
	v_pk_mul_f32 v[48:49], v[48:49], v[48:49]
	v_pk_mul_f32 v[44:45], v[44:45], v[44:45]
	v_pk_mul_f32 v[38:39], v[38:39], v[38:39]
	v_pk_mul_f32 v[50:51], v[34:35], v[34:35]
	v_pk_mul_f32 v[40:41], v[40:41], v[40:41]
	v_pk_mul_f32 v[58:59], v[36:37], v[36:37]
	v_cvt_pk_bf16_f32 v34, v46, v47
	v_cvt_pk_bf16_f32 v35, v48, v49
	v_cvt_pk_bf16_f32 v36, v42, v43
	v_cvt_pk_bf16_f32 v37, v44, v45
	v_cvt_pk_bf16_f32 v38, v38, v39
	v_cvt_pk_bf16_f32 v39, v40, v41
	v_cvt_pk_bf16_f32 v40, v50, v51
	v_cvt_pk_bf16_f32 v41, v58, v59
	global_store_dwordx4 v[54:55], v[34:37], off
	global_store_dwordx4 v[54:55], v[38:41], off offset:256
;   DI void operator()(const f32x4 (&acc)[2][2][4][2], const pg8::Unit& u, int wr, int wc, int fr, int fq) const {
;     ...
;       for (int m = 0; m < 4; ++m) {
;         const int row = u.pm * 256 + ai * 128 + wr * 64 + m * 16 + fr;
;         const int grow = rowbase + row;
;         float rs = 1.f;
;         if (MODE == EP_IN) rs = ((const float*)(ws + OFF_RS0))[grow];
;         if (MODE == EP_UP) rs = ((const float*)(ws + OFF_RS2))[grow];
;         if (MODE == EP_Q || MODE == EP_KV) {
;           const f32x4* sp = (const f32x4*)(ws + OFF_SSQA) + (size_t)grow * 4 + (MODE == EP_KV ? 2 : 0);
;           const f32x4 s0 = sp[0], s1 = sp[1];
;           const float ss = (s0[0] + s0[1]) + (s0[2] + s0[3]) + (s1[0] + s1[1]) + (s1[2] + s1[3]);
;           rs = __builtin_amdgcn_rsqf(ss * (1.0f / 512) + EPS);
;           if (MODE == EP_Q) rs *= QSCALE;
;         }
;         float ssq = 0.f;
; #pragma unroll
;         for (int bj = 0; bj < 2; ++bj) {
;           f32x4 v0 = acc[ai][bj][m][0] * rs, v1 = acc[ai][bj][m][1] * rs;
;           if (MODE == EP_IN || MODE == EP_MIX || MODE == EP_DOWN) {
; #pragma unroll
;             for (int j = 0; j < 4; ++j) ssq += v0[j] * v0[j] + v1[j] * v1[j];
;           }
;           if (MODE == EP_UP) {
; #pragma unroll
;             for (int j = 0; j < 4; ++j) { float a = fmaxf(v0[j], 0.f), b = fmaxf(v1[j], 0.f); v0[j] = a * a; v1[j] = b * b; }
;           }
;           bf16_t* dst;
;           const int ct = bj * 128 + cl;
;           if (MODE == EP_IN) {
;             if (pn < 4) dst = (bf16_t*)(ws + OFF_PROJA) + (size_t)grow * 1024 + pn * 256 + ct;
;             else if (pn < 16) dst = (bf16_t*)(ws + OFF_PROJG) + (size_t)grow * 3072 + (pn - 4) * 256 + ct;
;             else dst = (bf16_t*)(ws + OFF_PROJS) + (size_t)grow * 256 + ct;
;           } else if (MODE == EP_Q) {
;             if (pn < 4) dst = (bf16_t*)(dout + DO_Q) + (size_t)grow * 1536 + (pn * 2 + bj) * 192 + cl;
;             else {
;               const int mm = (pn - 4) * 256 + ct, h = mm >> 6, r = mm & 63;
;               dst = (bf16_t*)(dout + DO_Q) + (size_t)grow * 1536 + h * 192 + 128 + r;
;               const int pos = grow < TP ? (grow & 4095) : grow - TP;
;               const f32x4* tb = (const f32x4*)((const f32x2*)(ws + OFF_ROPE) + pos * 32 + (r >> 1));
;               const f32x4 t0 = tb[0], t1 = tb[1];
;               f32x4 o0, o1;
	s_nop 0
	v_add_u32_e32 v36, 0xb0, v148
	v_lshlrev_b64 v[38:39], 14, v[52:53]
	v_lshl_add_u64 v[38:39], s[6:7], 0, v[38:39]
	v_lshl_add_u64 v[38:39], v[38:39], 0, s[18:19]
	v_ashrrev_i32_e32 v37, 31, v36
	v_lshl_add_u64 v[38:39], v[38:39], 0, v[138:139]
	v_lshl_add_u64 v[40:41], v[36:37], 2, s[4:5]
	v_mov_b32_e32 v34, v245
	v_pk_mul_f32 v[32:33], v[32:33], v[34:35] op_sel_hi:[1,0]
	v_pk_mul_f32 v[30:31], v[30:31], v[34:35] op_sel_hi:[1,0]
	v_pk_mul_f32 v[28:29], v[28:29], v[34:35] op_sel_hi:[1,0]
	v_pk_mul_f32 v[26:27], v[26:27], v[34:35] op_sel_hi:[1,0]
	v_pk_mul_f32 v[24:25], v[24:25], v[34:35] op_sel_hi:[1,0]
	v_pk_mul_f32 v[22:23], v[22:23], v[34:35] op_sel_hi:[1,0]
	v_pk_mul_f32 v[20:21], v[20:21], v[34:35] op_sel_hi:[1,0]
	v_pk_mul_f32 v[18:19], v[18:19], v[34:35] op_sel_hi:[1,0]
	v_max_f32_e32 v30, 0, v30
	v_max_f32_e32 v26, 0, v26
	v_max_f32_e32 v31, 0, v31
	v_max_f32_e32 v27, 0, v27
	v_max_f32_e32 v32, 0, v32
	v_max_f32_e32 v28, 0, v28
	v_max_f32_e32 v33, 0, v33
	v_max_f32_e32 v29, 0, v29
	v_max_f32_e32 v22, 0, v22
	v_max_f32_e32 v18, 0, v18
	v_max_f32_e32 v23, 0, v23
	v_max_f32_e32 v19, 0, v19
	v_max_f32_e32 v24, 0, v24
	v_max_f32_e32 v20, 0, v20
	v_max_f32_e32 v25, 0, v25
	v_max_f32_e32 v21, 0, v21
	v_pk_mul_f32 v[30:31], v[30:31], v[30:31]
	v_pk_mul_f32 v[26:27], v[26:27], v[26:27]
	v_pk_mul_f32 v[32:33], v[32:33], v[32:33]
	v_pk_mul_f32 v[28:29], v[28:29], v[28:29]
	v_pk_mul_f32 v[22:23], v[22:23], v[22:23]
	v_pk_mul_f32 v[34:35], v[18:19], v[18:19]
	v_pk_mul_f32 v[24:25], v[24:25], v[24:25]
	v_pk_mul_f32 v[42:43], v[20:21], v[20:21]
	v_cvt_pk_bf16_f32 v18, v30, v31
	v_cvt_pk_bf16_f32 v19, v32, v33
	v_cvt_pk_bf16_f32 v20, v26, v27
	v_cvt_pk_bf16_f32 v21, v28, v29
	v_cvt_pk_bf16_f32 v22, v22, v23
	v_cvt_pk_bf16_f32 v23, v24, v25
	v_cvt_pk_bf16_f32 v24, v34, v35
	v_cvt_pk_bf16_f32 v25, v42, v43
	global_store_dwordx4 v[38:39], v[18:21], off
	global_store_dwordx4 v[38:39], v[22:25], off offset:256
	s_nop 0
	v_lshlrev_b64 v[20:21], 14, v[36:37]
	v_lshl_add_u64 v[20:21], s[6:7], 0, v[20:21]
	v_lshl_add_u64 v[20:21], v[20:21], 0, s[18:19]
	v_lshl_add_u64 v[20:21], v[20:21], 0, v[138:139]
	v_mov_b32_e32 v18, v246
	v_pk_mul_f32 v[16:17], v[16:17], v[18:19] op_sel_hi:[1,0]
	v_pk_mul_f32 v[14:15], v[14:15], v[18:19] op_sel_hi:[1,0]
	v_pk_mul_f32 v[12:13], v[12:13], v[18:19] op_sel_hi:[1,0]
	v_pk_mul_f32 v[10:11], v[10:11], v[18:19] op_sel_hi:[1,0]
	v_pk_mul_f32 v[8:9], v[8:9], v[18:19] op_sel_hi:[1,0]
	v_pk_mul_f32 v[6:7], v[6:7], v[18:19] op_sel_hi:[1,0]
	v_pk_mul_f32 v[4:5], v[4:5], v[18:19] op_sel_hi:[1,0]
	v_pk_mul_f32 v[2:3], v[2:3], v[18:19] op_sel_hi:[1,0]
	v_max_f32_e32 v14, 0, v14
	v_max_f32_e32 v10, 0, v10
	v_max_f32_e32 v15, 0, v15
	v_max_f32_e32 v11, 0, v11
	v_max_f32_e32 v16, 0, v16
	v_max_f32_e32 v12, 0, v12
	v_max_f32_e32 v17, 0, v17
	v_max_f32_e32 v13, 0, v13
	v_max_f32_e32 v6, 0, v6
	v_max_f32_e32 v2, 0, v2
	v_max_f32_e32 v7, 0, v7
	v_max_f32_e32 v3, 0, v3
	v_max_f32_e32 v8, 0, v8
	v_max_f32_e32 v4, 0, v4
	v_max_f32_e32 v9, 0, v9
	v_max_f32_e32 v5, 0, v5
	v_pk_mul_f32 v[14:15], v[14:15], v[14:15]
	v_pk_mul_f32 v[10:11], v[10:11], v[10:11]
	v_pk_mul_f32 v[16:17], v[16:17], v[16:17]
	v_pk_mul_f32 v[12:13], v[12:13], v[12:13]
	v_pk_mul_f32 v[6:7], v[6:7], v[6:7]
	v_pk_mul_f32 v[18:19], v[2:3], v[2:3]
	v_pk_mul_f32 v[8:9], v[8:9], v[8:9]
	v_pk_mul_f32 v[22:23], v[4:5], v[4:5]
	v_cvt_pk_bf16_f32 v2, v14, v15
	v_cvt_pk_bf16_f32 v3, v16, v17
	v_cvt_pk_bf16_f32 v4, v10, v11
	v_cvt_pk_bf16_f32 v5, v12, v13
	v_cvt_pk_bf16_f32 v6, v6, v7
	v_cvt_pk_bf16_f32 v7, v8, v9
	v_cvt_pk_bf16_f32 v8, v18, v19
	v_cvt_pk_bf16_f32 v9, v22, v23
	global_store_dwordx4 v[20:21], v[2:5], off
	global_store_dwordx4 v[20:21], v[6:9], off offset:256
	s_cbranch_vccz .LBB0_914
	s_waitcnt vmcnt(0)
	s_cmpk_gt_u32 s24, 0xff
	s_cbranch_scc1 .LBB0_925
	s_barrier

; #define PG8_STAGE(bufoff, gbase, voff) do { _Pragma("unroll") for (int _i = 0; _i < 2; ++_i) \
;     __builtin_amdgcn_global_load_lds((const unsigned*)((const char*)(gbase) + (voff)[_i]), (LAS unsigned*)(lds + (bufoff) + ldsw + _i * 8192), 16, 0, 0); } while (0)
; #define PG8_LDA(dst, b, h) do { _Pragma("unroll") for (int m = 0; m < 4; ++m) _Pragma("unroll") for (int k = 0; k < 2; ++k) dst[m][k] = *(const LAS bf16x8*)(lds + PG8_SA(b, h) + aoff + m * 2048 + k * 1024); } while (0)
; #define PG8_LDB(dst, b, h) do { _Pragma("unroll") for (int n = 0; n < 2; ++n) _Pragma("unroll") for (int k = 0; k < 2; ++k) dst[n][k] = *(const LAS bf16x8*)(lds + PG8_SB(b, h) + boff + n * 2048 + k * 1024); } while (0)
; #define PG8_MMA(ai, bj, At, Bt) do { __builtin_amdgcn_s_setprio(1); _Pragma("unroll") for (int m = 0; m < 4; ++m) _Pragma("unroll") for (int n = 0; n < 2; ++n) _Pragma("unroll") for (int k = 0; k < 2; ++k) \
;     acc[ai][bj][m][n] = __builtin_amdgcn_mfma_f32_16x16x32_bf16(Bt[n][k], At[m][k], acc[ai][bj][m][n], 0, 0, 0); __builtin_amdgcn_s_setprio(0); } while (0)
; #define PG8_WAIT_V(n) asm volatile("s_waitcnt vmcnt(" #n ")" ::: "memory")
; #define PG8_WAIT_L(n) asm volatile("s_waitcnt lgkmcnt(" #n ")" ::: "memory")
; #define PG8_BAR __builtin_amdgcn_s_barrier()
; #define PG8_SCHED __builtin_amdgcn_sched_barrier(0)
; template <class Epi>
; DI void gemm_phase(LAS unsigned char* lds, const Gemm g, const StaticOrder& S, const Epi& E) {
;     ...
;     for (int t = 0; t < nt; t += 2) {
;       const bool last = (t == nt - 2);
;       const char* a1 = cA + PG8_AK(t + 1);
;       const char* a2 = last ? nA : cA + PG8_AK(t + 2); const char* b2 = last ? nB : cB + (size_t)(t + 2) * kstep;
;       const char* a3 = a2 + kstep; const char* b3 = b2 + kstep;
;       PG8_LDB(B0, 0, 0); PG8_SCHED; PG8_LDA(At, 0, 0); PG8_STAGE(PG8_SA(1, 1), a1 + hstepA, voffA);
;       PG8_WAIT_L(8); PG8_BAR; PG8_WAIT_L(0); PG8_MMA(0, 0, At, B0); PG8_BAR; PG8_SCHED;
;       PG8_LDB(B1, 0, 1); PG8_STAGE(PG8_SB(0, 0), b2, voffB);
;       PG8_BAR; PG8_WAIT_L(0); PG8_MMA(0, 1, At, B1); PG8_BAR;
;       PG8_LDA(At, 0, 1); PG8_STAGE(PG8_SA(0, 0), a2, voffA);
;       PG8_BAR; PG8_WAIT_L(0); PG8_MMA(1, 0, At, B0); PG8_BAR; PG8_SCHED;
;       PG8_STAGE(PG8_SB(0, 1), b2 + hstepB, voffB);
;       PG8_WAIT_V(6); PG8_BAR; PG8_MMA(1, 1, At, B1); PG8_BAR;
.LBB0_962:
	ds_read_b128 v[156:159], v151
	ds_read_b128 v[160:163], v151 offset:1024
	ds_read_b128 v[164:167], v151 offset:2048
	ds_read_b128 v[168:171], v151 offset:3072
	s_add_u32 s22, s20, 0xffe00080
	s_addc_u32 s23, s21, -1
	s_cmpk_eq_i32 s48, 0x7c
	s_cselect_b32 s25, s13, s23
	s_cselect_b32 s24, s19, s22
	s_cselect_b32 s23, s11, s47
	s_cselect_b32 s22, s45, s46
	v_lshl_add_u64 v[148:149], s[20:21], 0, v[140:141]
	s_add_i32 m0, s33, 0xc000
	ds_read_b128 v[172:175], v152
	ds_read_b128 v[176:179], v152 offset:1024
	ds_read_b128 v[180:183], v152 offset:2048
	ds_read_b128 v[184:187], v152 offset:3072
	ds_read_b128 v[188:191], v152 offset:4096
	ds_read_b128 v[192:195], v152 offset:5120
	ds_read_b128 v[196:199], v152 offset:6144
	ds_read_b128 v[200:203], v152 offset:7168
	global_load_lds_dwordx4 v[148:149], off
	v_lshl_add_u64 v[148:149], s[20:21], 0, v[142:143]
	s_add_i32 m0, s33, 0xe000
	s_nop 0
	global_load_lds_dwordx4 v[148:149], off
	s_waitcnt lgkmcnt(8)
	s_barrier
	s_waitcnt lgkmcnt(0)
	s_waitcnt lgkmcnt(0)
	v_mfma_f32_16x16x32_bf16 v[126:129], v[156:159], v[172:175], v[126:129]
	v_mfma_f32_16x16x32_bf16 v[122:125], v[164:167], v[172:175], v[122:125]
	v_mfma_f32_16x16x32_bf16 v[110:113], v[156:159], v[180:183], v[110:113]
	v_mfma_f32_16x16x32_bf16 v[106:109], v[164:167], v[180:183], v[106:109]
	v_mfma_f32_16x16x32_bf16 v[94:97], v[156:159], v[188:191], v[94:97]
	v_mfma_f32_16x16x32_bf16 v[90:93], v[164:167], v[188:191], v[90:93]
	v_mfma_f32_16x16x32_bf16 v[78:81], v[156:159], v[196:199], v[78:81]
	v_mfma_f32_16x16x32_bf16 v[74:77], v[164:167], v[196:199], v[74:77]
	v_mfma_f32_16x16x32_bf16 v[126:129], v[160:163], v[176:179], v[126:129]
	v_mfma_f32_16x16x32_bf16 v[122:125], v[168:171], v[176:179], v[122:125]
	v_mfma_f32_16x16x32_bf16 v[110:113], v[160:163], v[184:187], v[110:113]
	v_mfma_f32_16x16x32_bf16 v[106:109], v[168:171], v[184:187], v[106:109]
	v_mfma_f32_16x16x32_bf16 v[94:97], v[160:163], v[192:195], v[94:97]
	v_mfma_f32_16x16x32_bf16 v[90:93], v[168:171], v[192:195], v[90:93]
	v_mfma_f32_16x16x32_bf16 v[78:81], v[160:163], v[200:203], v[78:81]
	v_mfma_f32_16x16x32_bf16 v[74:77], v[168:171], v[200:203], v[74:77]
	s_barrier
	s_add_i32 s49, s42, s31
	v_lshl_add_u64 v[148:149], s[22:23], 0, v[132:133]
	s_mov_b32 m0, s49
	ds_read_b128 v[204:207], v153
	ds_read_b128 v[208:211], v153 offset:1024
	ds_read_b128 v[212:215], v153 offset:2048
	ds_read_b128 v[216:219], v153 offset:3072
	global_load_lds_dwordx4 v[148:149], off
	v_lshl_add_u64 v[220:221], s[22:23], 0, v[136:137]
	s_add_i32 m0, s49, 0x2000
	s_nop 0
	global_load_lds_dwordx4 v[220:221], off
	s_barrier
	s_waitcnt lgkmcnt(0)
	s_waitcnt lgkmcnt(0)
	v_mfma_f32_16x16x32_bf16 v[118:121], v[204:207], v[172:175], v[118:121]
	v_mfma_f32_16x16x32_bf16 v[114:117], v[212:215], v[172:175], v[114:117]
	v_mfma_f32_16x16x32_bf16 v[102:105], v[204:207], v[180:183], v[102:105]
	v_mfma_f32_16x16x32_bf16 v[98:101], v[212:215], v[180:183], v[98:101]
	v_mfma_f32_16x16x32_bf16 v[86:89], v[204:207], v[188:191], v[86:89]
	v_mfma_f32_16x16x32_bf16 v[82:85], v[212:215], v[188:191], v[82:85]
	v_mfma_f32_16x16x32_bf16 v[70:73], v[204:207], v[196:199], v[70:73]
	v_mfma_f32_16x16x32_bf16 v[66:69], v[212:215], v[196:199], v[66:69]
	v_mfma_f32_16x16x32_bf16 v[118:121], v[208:211], v[176:179], v[118:121]
	v_mfma_f32_16x16x32_bf16 v[114:117], v[216:219], v[176:179], v[114:117]
	v_mfma_f32_16x16x32_bf16 v[102:105], v[208:211], v[184:187], v[102:105]
	v_mfma_f32_16x16x32_bf16 v[98:101], v[216:219], v[184:187], v[98:101]
	v_mfma_f32_16x16x32_bf16 v[86:89], v[208:211], v[192:195], v[86:89]
	v_mfma_f32_16x16x32_bf16 v[82:85], v[216:219], v[192:195], v[82:85]
	v_mfma_f32_16x16x32_bf16 v[70:73], v[208:211], v[200:203], v[70:73]
	v_mfma_f32_16x16x32_bf16 v[66:69], v[216:219], v[200:203], v[66:69]
	s_mov_b32 m0, s33
	v_lshl_add_u64 v[222:223], s[24:25], 0, v[130:131]
	s_barrier
	ds_read_b128 v[172:175], v152 offset:16384
	ds_read_b128 v[176:179], v152 offset:17408
	ds_read_b128 v[180:183], v152 offset:18432
	ds_read_b128 v[184:187], v152 offset:19456
	ds_read_b128 v[188:191], v152 offset:20480
	ds_read_b128 v[192:195], v152 offset:21504
	ds_read_b128 v[196:199], v152 offset:22528
	ds_read_b128 v[200:203], v152 offset:23552
	global_load_lds_dwordx4 v[222:223], off
	v_lshl_add_u64 v[224:225], s[24:25], 0, v[134:135]
	s_mov_b32 m0, s34
	s_nop 0
	global_load_lds_dwordx4 v[224:225], off
	s_barrier
	s_waitcnt lgkmcnt(0)
	s_waitcnt lgkmcnt(0)
	v_mfma_f32_16x16x32_bf16 v[62:65], v[156:159], v[172:175], v[62:65]
	v_mfma_f32_16x16x32_bf16 v[58:61], v[164:167], v[172:175], v[58:61]
	v_mfma_f32_16x16x32_bf16 v[46:49], v[156:159], v[180:183], v[46:49]
	v_mfma_f32_16x16x32_bf16 v[42:45], v[164:167], v[180:183], v[42:45]
	v_mfma_f32_16x16x32_bf16 v[30:33], v[156:159], v[188:191], v[30:33]
	v_mfma_f32_16x16x32_bf16 v[26:29], v[164:167], v[188:191], v[26:29]
	v_mfma_f32_16x16x32_bf16 v[14:17], v[156:159], v[196:199], v[14:17]
	v_mfma_f32_16x16x32_bf16 v[10:13], v[164:167], v[196:199], v[10:13]
	v_mfma_f32_16x16x32_bf16 v[62:65], v[160:163], v[176:179], v[62:65]
	v_mfma_f32_16x16x32_bf16 v[58:61], v[168:171], v[176:179], v[58:61]
	v_mfma_f32_16x16x32_bf16 v[46:49], v[160:163], v[184:187], v[46:49]
	v_mfma_f32_16x16x32_bf16 v[42:45], v[168:171], v[184:187], v[42:45]
	v_mfma_f32_16x16x32_bf16 v[30:33], v[160:163], v[192:195], v[30:33]
	v_mfma_f32_16x16x32_bf16 v[26:29], v[168:171], v[192:195], v[26:29]
	v_mfma_f32_16x16x32_bf16 v[14:17], v[160:163], v[200:203], v[14:17]
	v_mfma_f32_16x16x32_bf16 v[10:13], v[168:171], v[200:203], v[10:13]
	s_barrier
; #define PG8_STAGE(bufoff, gbase, voff) do { _Pragma("unroll") for (int _i = 0; _i < 2; ++_i) \
;     __builtin_amdgcn_global_load_lds((const unsigned*)((const char*)(gbase) + (voff)[_i]), (LAS unsigned*)(lds + (bufoff) + ldsw + _i * 8192), 16, 0, 0); } while (0)
; #define PG8_LDA(dst, b, h) do { _Pragma("unroll") for (int m = 0; m < 4; ++m) _Pragma("unroll") for (int k = 0; k < 2; ++k) dst[m][k] = *(const LAS bf16x8*)(lds + PG8_SA(b, h) + aoff + m * 2048 + k * 1024); } while (0)
; #define PG8_LDB(dst, b, h) do { _Pragma("unroll") for (int n = 0; n < 2; ++n) _Pragma("unroll") for (int k = 0; k < 2; ++k) dst[n][k] = *(const LAS bf16x8*)(lds + PG8_SB(b, h) + boff + n * 2048 + k * 1024); } while (0)
; #define PG8_MMA(ai, bj, At, Bt) do { __builtin_amdgcn_s_setprio(1); _Pragma("unroll") for (int m = 0; m < 4; ++m) _Pragma("unroll") for (int n = 0; n < 2; ++n) _Pragma("unroll") for (int k = 0; k < 2; ++k) \
;     acc[ai][bj][m][n] = __builtin_amdgcn_mfma_f32_16x16x32_bf16(Bt[n][k], At[m][k], acc[ai][bj][m][n], 0, 0, 0); __builtin_amdgcn_s_setprio(0); } while (0)
; #define PG8_WAIT_V(n) asm volatile("s_waitcnt vmcnt(" #n ")" ::: "memory")
; #define PG8_WAIT_L(n) asm volatile("s_waitcnt lgkmcnt(" #n ")" ::: "memory")
; #define PG8_BAR __builtin_amdgcn_s_barrier()
; #define PG8_SCHED __builtin_amdgcn_sched_barrier(0)
; template <class Epi>
; DI void gemm_phase(LAS unsigned char* lds, const Gemm g, const StaticOrder& S, const Epi& E) {
;     ...
;       PG8_STAGE(PG8_SB(0, 1), b2 + hstepB, voffB);
;       PG8_WAIT_V(6); PG8_BAR; PG8_MMA(1, 1, At, B1); PG8_BAR;
;       PG8_LDB(B0, 1, 0); PG8_SCHED; PG8_LDA(At, 1, 0); PG8_STAGE(PG8_SA(0, 1), a2 + hstepA, voffA);
;       PG8_WAIT_L(8); PG8_BAR; PG8_WAIT_L(0); PG8_MMA(0, 0, At, B0); PG8_BAR; PG8_SCHED;
;       PG8_LDB(B1, 1, 1); PG8_STAGE(PG8_SB(1, 0), b3, voffB);
;       PG8_BAR; PG8_WAIT_L(0); PG8_MMA(0, 1, At, B1); PG8_BAR;
;       PG8_LDA(At, 1, 1); PG8_STAGE(PG8_SA(1, 0), a3, voffA);
;       PG8_BAR; PG8_WAIT_L(0); PG8_MMA(1, 0, At, B0); PG8_BAR; PG8_SCHED;
	s_add_u32 s50, s22, 0x200000
	s_addc_u32 s51, s23, 0
	s_add_i32 s49, s43, s31
	v_lshl_add_u64 v[156:157], s[50:51], 0, v[132:133]
	s_mov_b32 m0, s49
	s_nop 0
	global_load_lds_dwordx4 v[156:157], off
	v_lshl_add_u64 v[156:157], s[50:51], 0, v[136:137]
	s_add_i32 m0, s49, 0x2000
	s_nop 0
	global_load_lds_dwordx4 v[156:157], off
	s_waitcnt vmcnt(6)
	s_barrier
	v_mfma_f32_16x16x32_bf16 v[54:57], v[204:207], v[172:175], v[54:57]
	v_mfma_f32_16x16x32_bf16 v[50:53], v[212:215], v[172:175], v[50:53]
	v_mfma_f32_16x16x32_bf16 v[38:41], v[204:207], v[180:183], v[38:41]
	v_mfma_f32_16x16x32_bf16 v[34:37], v[212:215], v[180:183], v[34:37]
	v_mfma_f32_16x16x32_bf16 v[22:25], v[204:207], v[188:191], v[22:25]
	v_mfma_f32_16x16x32_bf16 v[18:21], v[212:215], v[188:191], v[18:21]
	v_mfma_f32_16x16x32_bf16 v[6:9], v[204:207], v[196:199], v[6:9]
	v_mfma_f32_16x16x32_bf16 v[2:5], v[212:215], v[196:199], v[2:5]
	v_mfma_f32_16x16x32_bf16 v[54:57], v[208:211], v[176:179], v[54:57]
	v_mfma_f32_16x16x32_bf16 v[50:53], v[216:219], v[176:179], v[50:53]
	v_mfma_f32_16x16x32_bf16 v[38:41], v[208:211], v[184:187], v[38:41]
	v_mfma_f32_16x16x32_bf16 v[34:37], v[216:219], v[184:187], v[34:37]
	v_mfma_f32_16x16x32_bf16 v[22:25], v[208:211], v[192:195], v[22:25]
	v_mfma_f32_16x16x32_bf16 v[18:21], v[216:219], v[192:195], v[18:21]
	v_mfma_f32_16x16x32_bf16 v[6:9], v[208:211], v[200:203], v[6:9]
	v_mfma_f32_16x16x32_bf16 v[2:5], v[216:219], v[200:203], v[2:5]
	s_add_i32 s49, 0, 0x18000
	v_add_u32_e32 v155, s49, v150
	s_barrier
	ds_read_b128 v[156:159], v155
	ds_read_b128 v[160:163], v155 offset:1024
	ds_read_b128 v[164:167], v155 offset:2048
	ds_read_b128 v[168:171], v155 offset:3072
	s_add_u32 s24, s24, 0x200000
	s_addc_u32 s25, s25, 0
	s_mov_b32 m0, s35
	v_lshl_add_u64 v[204:205], s[24:25], 0, v[130:131]
	ds_read_b128 v[172:175], v152 offset:32768
	ds_read_b128 v[176:179], v152 offset:33792
	ds_read_b128 v[180:183], v152 offset:34816
	ds_read_b128 v[184:187], v152 offset:35840
	ds_read_b128 v[188:191], v152 offset:36864
	ds_read_b128 v[192:195], v152 offset:37888
	ds_read_b128 v[196:199], v152 offset:38912
	ds_read_b128 v[200:203], v152 offset:39936
	global_load_lds_dwordx4 v[204:205], off
	v_lshl_add_u64 v[204:205], s[24:25], 0, v[134:135]
	s_mov_b32 m0, s36
	s_nop 0
	global_load_lds_dwordx4 v[204:205], off
	s_waitcnt lgkmcnt(8)
	s_barrier
	s_waitcnt lgkmcnt(0)
	s_waitcnt lgkmcnt(0)
	v_mfma_f32_16x16x32_bf16 v[126:129], v[156:159], v[172:175], v[126:129]
	v_mfma_f32_16x16x32_bf16 v[122:125], v[164:167], v[172:175], v[122:125]
	v_mfma_f32_16x16x32_bf16 v[110:113], v[156:159], v[180:183], v[110:113]
	v_mfma_f32_16x16x32_bf16 v[106:109], v[164:167], v[180:183], v[106:109]
	v_mfma_f32_16x16x32_bf16 v[94:97], v[156:159], v[188:191], v[94:97]
	v_mfma_f32_16x16x32_bf16 v[90:93], v[164:167], v[188:191], v[90:93]
	v_mfma_f32_16x16x32_bf16 v[78:81], v[156:159], v[196:199], v[78:81]
	v_mfma_f32_16x16x32_bf16 v[74:77], v[164:167], v[196:199], v[74:77]
	v_mfma_f32_16x16x32_bf16 v[126:129], v[160:163], v[176:179], v[126:129]
	v_mfma_f32_16x16x32_bf16 v[122:125], v[168:171], v[176:179], v[122:125]
	v_mfma_f32_16x16x32_bf16 v[110:113], v[160:163], v[184:187], v[110:113]
	v_mfma_f32_16x16x32_bf16 v[106:109], v[168:171], v[184:187], v[106:109]
	v_mfma_f32_16x16x32_bf16 v[94:97], v[160:163], v[192:195], v[94:97]
	v_mfma_f32_16x16x32_bf16 v[90:93], v[168:171], v[192:195], v[90:93]
	v_mfma_f32_16x16x32_bf16 v[78:81], v[160:163], v[200:203], v[78:81]
	v_mfma_f32_16x16x32_bf16 v[74:77], v[168:171], v[200:203], v[74:77]
	s_barrier
	s_add_i32 s24, 0, 0x1c000
	s_add_i32 s25, s49, s31
	v_add_u32_e32 v155, s24, v150
	v_lshl_add_u64 v[148:149], v[148:149], 0, s[6:7]
	s_mov_b32 m0, s25
	ds_read_b128 v[204:207], v155
	ds_read_b128 v[208:211], v155 offset:1024
	ds_read_b128 v[212:215], v155 offset:2048
	ds_read_b128 v[216:219], v155 offset:3072
	global_load_lds_dwordx4 v[148:149], off
	v_lshl_add_u64 v[148:149], v[220:221], 0, s[6:7]
	s_add_i32 m0, s25, 0x2000
	s_nop 0
	global_load_lds_dwordx4 v[148:149], off
	s_barrier
	s_waitcnt lgkmcnt(0)
	s_waitcnt lgkmcnt(0)
	v_mfma_f32_16x16x32_bf16 v[118:121], v[204:207], v[172:175], v[118:121]
	v_mfma_f32_16x16x32_bf16 v[114:117], v[212:215], v[172:175], v[114:117]
	v_mfma_f32_16x16x32_bf16 v[102:105], v[204:207], v[180:183], v[102:105]
	v_mfma_f32_16x16x32_bf16 v[98:101], v[212:215], v[180:183], v[98:101]
	v_mfma_f32_16x16x32_bf16 v[86:89], v[204:207], v[188:191], v[86:89]
	v_mfma_f32_16x16x32_bf16 v[82:85], v[212:215], v[188:191], v[82:85]
	v_mfma_f32_16x16x32_bf16 v[70:73], v[204:207], v[196:199], v[70:73]
	v_mfma_f32_16x16x32_bf16 v[66:69], v[212:215], v[196:199], v[66:69]
	v_mfma_f32_16x16x32_bf16 v[118:121], v[208:211], v[176:179], v[118:121]
	v_mfma_f32_16x16x32_bf16 v[114:117], v[216:219], v[176:179], v[114:117]
	v_mfma_f32_16x16x32_bf16 v[102:105], v[208:211], v[184:187], v[102:105]
	v_mfma_f32_16x16x32_bf16 v[98:101], v[216:219], v[184:187], v[98:101]
	v_mfma_f32_16x16x32_bf16 v[86:89], v[208:211], v[192:195], v[86:89]
	v_mfma_f32_16x16x32_bf16 v[82:85], v[216:219], v[192:195], v[82:85]
	v_mfma_f32_16x16x32_bf16 v[70:73], v[208:211], v[200:203], v[70:73]
	v_mfma_f32_16x16x32_bf16 v[66:69], v[216:219], v[200:203], v[66:69]
	s_mov_b32 m0, s38
	v_lshl_add_u64 v[148:149], v[222:223], 0, s[6:7]
	s_barrier
	ds_read_b128 v[172:175], v152 offset:49152
	ds_read_b128 v[176:179], v152 offset:50176
	ds_read_b128 v[180:183], v152 offset:51200
	ds_read_b128 v[184:187], v152 offset:52224
	ds_read_b128 v[188:191], v152 offset:53248
	ds_read_b128 v[192:195], v152 offset:54272
	ds_read_b128 v[196:199], v152 offset:55296
	ds_read_b128 v[200:203], v152 offset:56320
	global_load_lds_dwordx4 v[148:149], off
	v_lshl_add_u64 v[148:149], v[224:225], 0, s[6:7]
	s_mov_b32 m0, s39
	s_nop 0
	global_load_lds_dwordx4 v[148:149], off
	s_barrier
; template <class Epi>
; DI void gemm_phase(LAS unsigned char* lds, const Gemm g, const StaticOrder& S, const Epi& E) {
;     ...
;       PG8_BAR; PG8_WAIT_L(0); PG8_MMA(1, 0, At, B0); PG8_BAR; PG8_SCHED;
;       PG8_STAGE(PG8_SB(1, 1), b3 + hstepB, voffB);
;       PG8_WAIT_V(6); PG8_BAR; PG8_MMA(1, 1, At, B1); PG8_BAR;
;     }
;   DI void operator()(const f32x4 (&acc)[2][2][4][2], const pg8::Unit& u, int wr, int wc, int fr, int fq) const {
;     ...
;         float ssq = 0.f;
; #pragma unroll
;         for (int bj = 0; bj < 2; ++bj) {
;           f32x4 v0 = acc[ai][bj][m][0] * rs, v1 = acc[ai][bj][m][1] * rs;
;           if (MODE == EP_IN || MODE == EP_MIX || MODE == EP_DOWN) {
; #pragma unroll
;             for (int j = 0; j < 4; ++j) ssq += v0[j] * v0[j] + v1[j] * v1[j];
;           }
;           if (MODE == EP_UP) {
; #pragma unroll
;             for (int j = 0; j < 4; ++j) { float a = fmaxf(v0[j], 0.f), b = fmaxf(v1[j], 0.f); v0[j] = a * a; v1[j] = b * b; }
;           }
;           bf16_t* dst;
;           const int ct = bj * 128 + cl;
;           if (MODE == EP_IN) {
;             if (pn < 4) dst = (bf16_t*)(ws + OFF_PROJA) + (size_t)grow * 1024 + pn * 256 + ct;
;             else if (pn < 16) dst = (bf16_t*)(ws + OFF_PROJG) + (size_t)grow * 3072 + (pn - 4) * 256 + ct;
;             else dst = (bf16_t*)(ws + OFF_PROJS) + (size_t)grow * 256 + ct;
;           } else if (MODE == EP_Q) {
;             if (pn < 4) dst = (bf16_t*)(dout + DO_Q) + (size_t)grow * 1536 + (pn * 2 + bj) * 192 + cl;
;             else {
;               const int mm = (pn - 4) * 256 + ct, h = mm >> 6, r = mm & 63;
;               dst = (bf16_t*)(dout + DO_Q) + (size_t)grow * 1536 + h * 192 + 128 + r;
;               const int pos = grow < TP ? (grow & 4095) : grow - TP;
;               const f32x4* tb = (const f32x4*)((const f32x2*)(ws + OFF_ROPE) + pos * 32 + (r >> 1));
;               const f32x4 t0 = tb[0], t1 = tb[1];
;               f32x4 o0, o1;
;               o0[0] = v0[0] * t0[0] - v0[1] * t0[1]; o0[1] = v0[1] * t0[0] + v0[0] * t0[1];
;               o0[2] = v0[2] * t0[2] - v0[3] * t0[3]; o0[3] = v0[3] * t0[2] + v0[2] * t0[3];
;               o1[0] = v1[0] * t1[0] - v1[1] * t1[1]; o1[1] = v1[1] * t1[0] + v1[0] * t1[1];
;               o1[2] = v1[2] * t1[2] - v1[3] * t1[3]; o1[3] = v1[3] * t1[2] + v1[2] * t1[3];
;               v0 = o0; v1 = o1;
;             }
	s_waitcnt lgkmcnt(0)
	s_waitcnt lgkmcnt(0)
	v_mfma_f32_16x16x32_bf16 v[62:65], v[156:159], v[172:175], v[62:65]
	v_mfma_f32_16x16x32_bf16 v[58:61], v[164:167], v[172:175], v[58:61]
	v_mfma_f32_16x16x32_bf16 v[46:49], v[156:159], v[180:183], v[46:49]
	v_mfma_f32_16x16x32_bf16 v[42:45], v[164:167], v[180:183], v[42:45]
	v_mfma_f32_16x16x32_bf16 v[30:33], v[156:159], v[188:191], v[30:33]
	v_mfma_f32_16x16x32_bf16 v[26:29], v[164:167], v[188:191], v[26:29]
	v_mfma_f32_16x16x32_bf16 v[14:17], v[156:159], v[196:199], v[14:17]
	v_mfma_f32_16x16x32_bf16 v[10:13], v[164:167], v[196:199], v[10:13]
	v_mfma_f32_16x16x32_bf16 v[62:65], v[160:163], v[176:179], v[62:65]
	v_mfma_f32_16x16x32_bf16 v[58:61], v[168:171], v[176:179], v[58:61]
	v_mfma_f32_16x16x32_bf16 v[46:49], v[160:163], v[184:187], v[46:49]
	v_mfma_f32_16x16x32_bf16 v[42:45], v[168:171], v[184:187], v[42:45]
	v_mfma_f32_16x16x32_bf16 v[30:33], v[160:163], v[192:195], v[30:33]
	v_mfma_f32_16x16x32_bf16 v[26:29], v[168:171], v[192:195], v[26:29]
	v_mfma_f32_16x16x32_bf16 v[14:17], v[160:163], v[200:203], v[14:17]
	v_mfma_f32_16x16x32_bf16 v[10:13], v[168:171], v[200:203], v[10:13]
	s_barrier
	s_add_u32 s22, s22, 0x200080
	s_addc_u32 s23, s23, 0
	s_add_i32 s24, s24, s31
	v_lshl_add_u64 v[148:149], s[22:23], 0, v[132:133]
	s_mov_b32 m0, s24
	s_nop 0
	global_load_lds_dwordx4 v[148:149], off
	v_lshl_add_u64 v[148:149], s[22:23], 0, v[136:137]
	s_add_i32 m0, s24, 0x2000
	s_nop 0
	global_load_lds_dwordx4 v[148:149], off
	s_waitcnt vmcnt(6)
	s_barrier
	v_mfma_f32_16x16x32_bf16 v[54:57], v[204:207], v[172:175], v[54:57]
	v_mfma_f32_16x16x32_bf16 v[50:53], v[212:215], v[172:175], v[50:53]
	v_mfma_f32_16x16x32_bf16 v[38:41], v[204:207], v[180:183], v[38:41]
	v_mfma_f32_16x16x32_bf16 v[34:37], v[212:215], v[180:183], v[34:37]
	v_mfma_f32_16x16x32_bf16 v[22:25], v[204:207], v[188:191], v[22:25]
	v_mfma_f32_16x16x32_bf16 v[18:21], v[212:215], v[188:191], v[18:21]
	v_mfma_f32_16x16x32_bf16 v[6:9], v[204:207], v[196:199], v[6:9]
	v_mfma_f32_16x16x32_bf16 v[2:5], v[212:215], v[196:199], v[2:5]
	v_mfma_f32_16x16x32_bf16 v[54:57], v[208:211], v[176:179], v[54:57]
	v_mfma_f32_16x16x32_bf16 v[50:53], v[216:219], v[176:179], v[50:53]
	v_mfma_f32_16x16x32_bf16 v[38:41], v[208:211], v[184:187], v[38:41]
	v_mfma_f32_16x16x32_bf16 v[34:37], v[216:219], v[184:187], v[34:37]
	v_mfma_f32_16x16x32_bf16 v[22:25], v[208:211], v[192:195], v[22:25]
	v_mfma_f32_16x16x32_bf16 v[18:21], v[216:219], v[192:195], v[18:21]
	v_mfma_f32_16x16x32_bf16 v[6:9], v[208:211], v[200:203], v[6:9]
	v_mfma_f32_16x16x32_bf16 v[2:5], v[216:219], v[200:203], v[2:5]
	s_add_i32 s48, s48, 2
	s_add_u32 s20, s20, 0x100
	s_addc_u32 s21, s21, 0
	s_add_u32 s46, s46, 0x100
	s_addc_u32 s47, s47, 0
	s_cmpk_gt_u32 s48, 0x7d
	s_barrier
	s_cbranch_scc0 .LBB0_962
	v_mul_f32_e32 v157, v122, v122
	v_mul_f32_e32 v160, v123, v123
	v_fmac_f32_e32 v157, v126, v126
	v_fmac_f32_e32 v160, v127, v127
	v_add_f32_e32 v157, v157, v160
	v_mul_f32_e32 v160, v124, v124
	v_fmac_f32_e32 v160, v128, v128
	v_add_f32_e32 v157, v160, v157
	v_mul_f32_e32 v160, v125, v125
	v_fmac_f32_e32 v160, v129, v129
	v_cvt_pk_bf16_f32 v126, v126, v127
	v_cvt_pk_bf16_f32 v127, v128, v129
	v_mul_f32_e32 v128, v114, v114
	v_add_f32_e32 v157, v160, v157
	v_fmac_f32_e32 v128, v118, v118
	v_mul_f32_e32 v129, v115, v115
	v_add_f32_e32 v128, v157, v128
	v_fmac_f32_e32 v129, v119, v119
	v_and_b32_e32 v155, 64, v154
	v_add_f32_e32 v128, v129, v128
	v_mul_f32_e32 v129, v116, v116
	v_xor_b32_e32 v149, 16, v154
	v_add_u32_e32 v155, 64, v155
	v_fmac_f32_e32 v129, v120, v120
	v_cmp_lt_i32_e32 vcc, v149, v155
	v_add_f32_e32 v128, v129, v128
	v_mul_f32_e32 v129, v117, v117
	v_cndmask_b32_e32 v149, v154, v149, vcc
	v_fmac_f32_e32 v129, v121, v121
	v_lshlrev_b32_e32 v156, 2, v149
	v_add_f32_e32 v157, v129, v128
	ds_bpermute_b32 v160, v156, v157
	v_xor_b32_e32 v149, 32, v154
	v_cmp_lt_i32_e32 vcc, v149, v155
	v_lshl_add_u32 v148, s18, 8, v1
	v_cvt_pk_bf16_f32 v128, v122, v123
	v_cndmask_b32_e32 v149, v154, v149, vcc
	v_lshlrev_b32_e32 v155, 2, v149
	v_cvt_pk_bf16_f32 v122, v118, v119
	s_waitcnt lgkmcnt(0)
	v_add_f32_e32 v118, v157, v160
	v_ashrrev_i32_e32 v149, 31, v148
	v_readlane_b32 s48, v238, 32
	ds_bpermute_b32 v119, v155, v118
	s_lshl_b32 s20, s4, 8
	v_lshlrev_b64 v[158:159], 13, v[148:149]
	v_readlane_b32 s54, v238, 38
	v_readlane_b32 s55, v238, 39
	s_ashr_i32 s21, s20, 31
	s_lshl_b32 s18, s4, 2
	v_lshl_add_u64 v[158:159], s[54:55], 0, v[158:159]
	v_lshl_add_u64 v[158:159], s[20:21], 1, v[158:159]
	s_ashr_i32 s19, s18, 31
	v_lshl_add_u64 v[158:159], v[158:159], 0, v[138:139]
	v_cvt_pk_bf16_f32 v129, v124, v125
	v_cvt_pk_bf16_f32 v123, v120, v121
	v_cvt_pk_bf16_f32 v124, v114, v115
	v_cvt_pk_bf16_f32 v125, v116, v117
	v_readlane_b32 s49, v238, 33
	v_readlane_b32 s50, v238, 34
	v_readlane_b32 s51, v238, 35
	v_readlane_b32 s52, v238, 36
	v_readlane_b32 s53, v238, 37
	global_store_dwordx4 v[158:159], v[126:129], off
	global_store_dwordx4 v[158:159], v[122:125], off offset:256
	s_and_saveexec_b64 s[22:23], s[0:1]
	s_cbranch_execz .LBB0_965
	v_lshlrev_b64 v[114:115], 7, v[148:149]
	v_lshl_add_u64 v[114:115], s[8:9], 0, v[114:115]
	v_lshl_add_u64 v[114:115], s[18:19], 2, v[114:115]
	s_lshl_b32 s4, s37, 2
	s_waitcnt lgkmcnt(0)
	v_add_f32_e32 v116, v118, v119
	v_lshl_add_u64 v[114:115], v[114:115], 0, s[4:5]
	global_store_dword v[114:115], v116, off

; #define PG8_STAGE(bufoff, gbase, voff) do { _Pragma("unroll") for (int _i = 0; _i < 2; ++_i) \
;     __builtin_amdgcn_global_load_lds((const unsigned*)((const char*)(gbase) + (voff)[_i]), (LAS unsigned*)(lds + (bufoff) + ldsw + _i * 8192), 16, 0, 0); } while (0)
; #define PG8_LDA(dst, b, h) do { _Pragma("unroll") for (int m = 0; m < 4; ++m) _Pragma("unroll") for (int k = 0; k < 2; ++k) dst[m][k] = *(const LAS bf16x8*)(lds + PG8_SA(b, h) + aoff + m * 2048 + k * 1024); } while (0)
; #define PG8_LDB(dst, b, h) do { _Pragma("unroll") for (int n = 0; n < 2; ++n) _Pragma("unroll") for (int k = 0; k < 2; ++k) dst[n][k] = *(const LAS bf16x8*)(lds + PG8_SB(b, h) + boff + n * 2048 + k * 1024); } while (0)
; #define PG8_MMA(ai, bj, At, Bt) do { __builtin_amdgcn_s_setprio(1); _Pragma("unroll") for (int m = 0; m < 4; ++m) _Pragma("unroll") for (int n = 0; n < 2; ++n) _Pragma("unroll") for (int k = 0; k < 2; ++k) \
;     acc[ai][bj][m][n] = __builtin_amdgcn_mfma_f32_16x16x32_bf16(Bt[n][k], At[m][k], acc[ai][bj][m][n], 0, 0, 0); __builtin_amdgcn_s_setprio(0); } while (0)
; #define PG8_WAIT_V(n) asm volatile("s_waitcnt vmcnt(" #n ")" ::: "memory")
; #define PG8_WAIT_L(n) asm volatile("s_waitcnt lgkmcnt(" #n ")" ::: "memory")
; #define PG8_BAR __builtin_amdgcn_s_barrier()
; #define PG8_SCHED __builtin_amdgcn_sched_barrier(0)
; template <class Epi>
; DI void gemm_phase(LAS unsigned char* lds, const Gemm g, const StaticOrder& S, const Epi& E) {
;     ...
;     for (int t = 0; t < nt; t += 2) {
;       const bool last = (t == nt - 2);
;       const char* a1 = cA + PG8_AK(t + 1);
;       const char* a2 = last ? nA : cA + PG8_AK(t + 2); const char* b2 = last ? nB : cB + (size_t)(t + 2) * kstep;
;       const char* a3 = a2 + kstep; const char* b3 = b2 + kstep;
;       PG8_LDB(B0, 0, 0); PG8_SCHED; PG8_LDA(At, 0, 0); PG8_STAGE(PG8_SA(1, 1), a1 + hstepA, voffA);
;       PG8_WAIT_L(8); PG8_BAR; PG8_WAIT_L(0); PG8_MMA(0, 0, At, B0); PG8_BAR; PG8_SCHED;
;       PG8_LDB(B1, 0, 1); PG8_STAGE(PG8_SB(0, 0), b2, voffB);
;       PG8_BAR; PG8_WAIT_L(0); PG8_MMA(0, 1, At, B1); PG8_BAR;
;       PG8_LDA(At, 0, 1); PG8_STAGE(PG8_SA(0, 0), a2, voffA);
;       PG8_BAR; PG8_WAIT_L(0); PG8_MMA(1, 0, At, B0); PG8_BAR; PG8_SCHED;
;       PG8_STAGE(PG8_SB(0, 1), b2 + hstepB, voffB);
;       PG8_WAIT_V(6); PG8_BAR; PG8_MMA(1, 1, At, B1); PG8_BAR;
.LBB0_1015:
	ds_read_b128 v[148:151], v153
	ds_read_b128 v[156:159], v153 offset:1024
	ds_read_b128 v[160:163], v153 offset:2048
	ds_read_b128 v[164:167], v153 offset:3072
	s_add_u32 s20, s18, 0xfff80080
	s_addc_u32 s21, s19, -1
	s_cmp_eq_u32 s46, 28
	s_cselect_b32 s23, s11, s21
	s_cselect_b32 s22, s42, s20
	s_cselect_b32 s21, s9, s45
	s_cselect_b32 s20, s43, s44
	v_lshl_add_u64 v[200:201], s[18:19], 0, v[140:141]
	s_add_i32 m0, s17, 0xc000
	ds_read_b128 v[168:171], v154
	ds_read_b128 v[172:175], v154 offset:1024
	ds_read_b128 v[176:179], v154 offset:2048
	ds_read_b128 v[180:183], v154 offset:3072
	ds_read_b128 v[184:187], v154 offset:4096
	ds_read_b128 v[188:191], v154 offset:5120
	ds_read_b128 v[192:195], v154 offset:6144
	ds_read_b128 v[196:199], v154 offset:7168
	global_load_lds_dwordx4 v[200:201], off
	v_lshl_add_u64 v[200:201], s[18:19], 0, v[142:143]
	s_add_i32 m0, s17, 0xe000
	s_nop 0
	global_load_lds_dwordx4 v[200:201], off
	s_waitcnt lgkmcnt(8)
	s_barrier
	s_waitcnt lgkmcnt(0)
	s_waitcnt lgkmcnt(0)
	v_mfma_f32_16x16x32_bf16 v[126:129], v[148:151], v[168:171], v[126:129]
	v_mfma_f32_16x16x32_bf16 v[122:125], v[160:163], v[168:171], v[122:125]
	v_mfma_f32_16x16x32_bf16 v[110:113], v[148:151], v[176:179], v[110:113]
	v_mfma_f32_16x16x32_bf16 v[106:109], v[160:163], v[176:179], v[106:109]
	v_mfma_f32_16x16x32_bf16 v[94:97], v[148:151], v[184:187], v[94:97]
	v_mfma_f32_16x16x32_bf16 v[90:93], v[160:163], v[184:187], v[90:93]
	v_mfma_f32_16x16x32_bf16 v[78:81], v[148:151], v[192:195], v[78:81]
	v_mfma_f32_16x16x32_bf16 v[74:77], v[160:163], v[192:195], v[74:77]
	v_mfma_f32_16x16x32_bf16 v[126:129], v[156:159], v[172:175], v[126:129]
	v_mfma_f32_16x16x32_bf16 v[122:125], v[164:167], v[172:175], v[122:125]
	v_mfma_f32_16x16x32_bf16 v[110:113], v[156:159], v[180:183], v[110:113]
	v_mfma_f32_16x16x32_bf16 v[106:109], v[164:167], v[180:183], v[106:109]
	v_mfma_f32_16x16x32_bf16 v[94:97], v[156:159], v[188:191], v[94:97]
	v_mfma_f32_16x16x32_bf16 v[90:93], v[164:167], v[188:191], v[90:93]
	v_mfma_f32_16x16x32_bf16 v[78:81], v[156:159], v[196:199], v[78:81]
	v_mfma_f32_16x16x32_bf16 v[74:77], v[164:167], v[196:199], v[74:77]
	s_barrier
	s_add_i32 s47, s39, s30
	v_lshl_add_u64 v[216:217], s[20:21], 0, v[132:133]
	s_mov_b32 m0, s47
	ds_read_b128 v[200:203], v155
	ds_read_b128 v[204:207], v155 offset:1024
	ds_read_b128 v[208:211], v155 offset:2048
	ds_read_b128 v[212:215], v155 offset:3072
	global_load_lds_dwordx4 v[216:217], off
	v_lshl_add_u64 v[218:219], s[20:21], 0, v[136:137]
	s_add_i32 m0, s47, 0x2000
	s_nop 0
	global_load_lds_dwordx4 v[218:219], off
	s_barrier
	s_waitcnt lgkmcnt(0)
	s_waitcnt lgkmcnt(0)
	v_mfma_f32_16x16x32_bf16 v[118:121], v[200:203], v[168:171], v[118:121]
	v_mfma_f32_16x16x32_bf16 v[114:117], v[208:211], v[168:171], v[114:117]
	v_mfma_f32_16x16x32_bf16 v[102:105], v[200:203], v[176:179], v[102:105]
	v_mfma_f32_16x16x32_bf16 v[98:101], v[208:211], v[176:179], v[98:101]
	v_mfma_f32_16x16x32_bf16 v[86:89], v[200:203], v[184:187], v[86:89]
	v_mfma_f32_16x16x32_bf16 v[82:85], v[208:211], v[184:187], v[82:85]
	v_mfma_f32_16x16x32_bf16 v[70:73], v[200:203], v[192:195], v[70:73]
	v_mfma_f32_16x16x32_bf16 v[66:69], v[208:211], v[192:195], v[66:69]
	v_mfma_f32_16x16x32_bf16 v[118:121], v[204:207], v[172:175], v[118:121]
	v_mfma_f32_16x16x32_bf16 v[114:117], v[212:215], v[172:175], v[114:117]
	v_mfma_f32_16x16x32_bf16 v[102:105], v[204:207], v[180:183], v[102:105]
	v_mfma_f32_16x16x32_bf16 v[98:101], v[212:215], v[180:183], v[98:101]
	v_mfma_f32_16x16x32_bf16 v[86:89], v[204:207], v[188:191], v[86:89]
	v_mfma_f32_16x16x32_bf16 v[82:85], v[212:215], v[188:191], v[82:85]
	v_mfma_f32_16x16x32_bf16 v[70:73], v[204:207], v[196:199], v[70:73]
	v_mfma_f32_16x16x32_bf16 v[66:69], v[212:215], v[196:199], v[66:69]
	s_mov_b32 m0, s17
	v_lshl_add_u64 v[220:221], s[22:23], 0, v[130:131]
	s_barrier
	ds_read_b128 v[168:171], v154 offset:16384
	ds_read_b128 v[172:175], v154 offset:17408
	ds_read_b128 v[176:179], v154 offset:18432
	ds_read_b128 v[180:183], v154 offset:19456
	ds_read_b128 v[184:187], v154 offset:20480
	ds_read_b128 v[188:191], v154 offset:21504
	ds_read_b128 v[192:195], v154 offset:22528
	ds_read_b128 v[196:199], v154 offset:23552
	global_load_lds_dwordx4 v[220:221], off
	v_lshl_add_u64 v[222:223], s[22:23], 0, v[134:135]
	s_mov_b32 m0, s31
	s_nop 0
	global_load_lds_dwordx4 v[222:223], off
	s_barrier
	s_waitcnt lgkmcnt(0)
	s_waitcnt lgkmcnt(0)
	v_mfma_f32_16x16x32_bf16 v[62:65], v[148:151], v[168:171], v[62:65]
	v_mfma_f32_16x16x32_bf16 v[58:61], v[160:163], v[168:171], v[58:61]
	v_mfma_f32_16x16x32_bf16 v[46:49], v[148:151], v[176:179], v[46:49]
	v_mfma_f32_16x16x32_bf16 v[42:45], v[160:163], v[176:179], v[42:45]
	v_mfma_f32_16x16x32_bf16 v[30:33], v[148:151], v[184:187], v[30:33]
	v_mfma_f32_16x16x32_bf16 v[26:29], v[160:163], v[184:187], v[26:29]
	v_mfma_f32_16x16x32_bf16 v[14:17], v[148:151], v[192:195], v[14:17]
	v_mfma_f32_16x16x32_bf16 v[10:13], v[160:163], v[192:195], v[10:13]
	v_mfma_f32_16x16x32_bf16 v[62:65], v[156:159], v[172:175], v[62:65]
	v_mfma_f32_16x16x32_bf16 v[58:61], v[164:167], v[172:175], v[58:61]
	v_mfma_f32_16x16x32_bf16 v[46:49], v[156:159], v[180:183], v[46:49]
	v_mfma_f32_16x16x32_bf16 v[42:45], v[164:167], v[180:183], v[42:45]
	v_mfma_f32_16x16x32_bf16 v[30:33], v[156:159], v[188:191], v[30:33]
	v_mfma_f32_16x16x32_bf16 v[26:29], v[164:167], v[188:191], v[26:29]
	v_mfma_f32_16x16x32_bf16 v[14:17], v[156:159], v[196:199], v[14:17]
	v_mfma_f32_16x16x32_bf16 v[10:13], v[164:167], v[196:199], v[10:13]
	s_barrier
; #define PG8_STAGE(bufoff, gbase, voff) do { _Pragma("unroll") for (int _i = 0; _i < 2; ++_i) \
;     __builtin_amdgcn_global_load_lds((const unsigned*)((const char*)(gbase) + (voff)[_i]), (LAS unsigned*)(lds + (bufoff) + ldsw + _i * 8192), 16, 0, 0); } while (0)
; #define PG8_LDA(dst, b, h) do { _Pragma("unroll") for (int m = 0; m < 4; ++m) _Pragma("unroll") for (int k = 0; k < 2; ++k) dst[m][k] = *(const LAS bf16x8*)(lds + PG8_SA(b, h) + aoff + m * 2048 + k * 1024); } while (0)
; #define PG8_LDB(dst, b, h) do { _Pragma("unroll") for (int n = 0; n < 2; ++n) _Pragma("unroll") for (int k = 0; k < 2; ++k) dst[n][k] = *(const LAS bf16x8*)(lds + PG8_SB(b, h) + boff + n * 2048 + k * 1024); } while (0)
; #define PG8_MMA(ai, bj, At, Bt) do { __builtin_amdgcn_s_setprio(1); _Pragma("unroll") for (int m = 0; m < 4; ++m) _Pragma("unroll") for (int n = 0; n < 2; ++n) _Pragma("unroll") for (int k = 0; k < 2; ++k) \
;     acc[ai][bj][m][n] = __builtin_amdgcn_mfma_f32_16x16x32_bf16(Bt[n][k], At[m][k], acc[ai][bj][m][n], 0, 0, 0); __builtin_amdgcn_s_setprio(0); } while (0)
; #define PG8_WAIT_V(n) asm volatile("s_waitcnt vmcnt(" #n ")" ::: "memory")
; #define PG8_WAIT_L(n) asm volatile("s_waitcnt lgkmcnt(" #n ")" ::: "memory")
; #define PG8_BAR __builtin_amdgcn_s_barrier()
; #define PG8_SCHED __builtin_amdgcn_sched_barrier(0)
; template <class Epi>
; DI void gemm_phase(LAS unsigned char* lds, const Gemm g, const StaticOrder& S, const Epi& E) {
;     ...
;       PG8_STAGE(PG8_SB(0, 1), b2 + hstepB, voffB);
;       PG8_WAIT_V(6); PG8_BAR; PG8_MMA(1, 1, At, B1); PG8_BAR;
;       PG8_LDB(B0, 1, 0); PG8_SCHED; PG8_LDA(At, 1, 0); PG8_STAGE(PG8_SA(0, 1), a2 + hstepA, voffA);
;       PG8_WAIT_L(8); PG8_BAR; PG8_WAIT_L(0); PG8_MMA(0, 0, At, B0); PG8_BAR; PG8_SCHED;
;       PG8_LDB(B1, 1, 1); PG8_STAGE(PG8_SB(1, 0), b3, voffB);
;       PG8_BAR; PG8_WAIT_L(0); PG8_MMA(0, 1, At, B1); PG8_BAR;
;       PG8_LDA(At, 1, 1); PG8_STAGE(PG8_SA(1, 0), a3, voffA);
;       PG8_BAR; PG8_WAIT_L(0); PG8_MMA(1, 0, At, B0); PG8_BAR; PG8_SCHED;
	s_add_u32 s48, s20, 0x80000
	s_addc_u32 s49, s21, 0
	s_add_i32 s47, s40, s30
	v_lshl_add_u64 v[148:149], s[48:49], 0, v[132:133]
	s_mov_b32 m0, s47
	s_nop 0
	global_load_lds_dwordx4 v[148:149], off
	v_lshl_add_u64 v[148:149], s[48:49], 0, v[136:137]
	s_add_i32 m0, s47, 0x2000
	s_nop 0
	global_load_lds_dwordx4 v[148:149], off
	s_waitcnt vmcnt(6)
	s_barrier
	v_mfma_f32_16x16x32_bf16 v[54:57], v[200:203], v[168:171], v[54:57]
	v_mfma_f32_16x16x32_bf16 v[50:53], v[208:211], v[168:171], v[50:53]
	v_mfma_f32_16x16x32_bf16 v[38:41], v[200:203], v[176:179], v[38:41]
	v_mfma_f32_16x16x32_bf16 v[34:37], v[208:211], v[176:179], v[34:37]
	v_mfma_f32_16x16x32_bf16 v[22:25], v[200:203], v[184:187], v[22:25]
	v_mfma_f32_16x16x32_bf16 v[18:21], v[208:211], v[184:187], v[18:21]
	v_mfma_f32_16x16x32_bf16 v[6:9], v[200:203], v[192:195], v[6:9]
	v_mfma_f32_16x16x32_bf16 v[2:5], v[208:211], v[192:195], v[2:5]
	v_mfma_f32_16x16x32_bf16 v[54:57], v[204:207], v[172:175], v[54:57]
	v_mfma_f32_16x16x32_bf16 v[50:53], v[212:215], v[172:175], v[50:53]
	v_mfma_f32_16x16x32_bf16 v[38:41], v[204:207], v[180:183], v[38:41]
	v_mfma_f32_16x16x32_bf16 v[34:37], v[212:215], v[180:183], v[34:37]
	v_mfma_f32_16x16x32_bf16 v[22:25], v[204:207], v[188:191], v[22:25]
	v_mfma_f32_16x16x32_bf16 v[18:21], v[212:215], v[188:191], v[18:21]
	v_mfma_f32_16x16x32_bf16 v[6:9], v[204:207], v[196:199], v[6:9]
	v_mfma_f32_16x16x32_bf16 v[2:5], v[212:215], v[196:199], v[2:5]
	s_add_i32 s47, 0, 0x18000
	v_add_u32_e32 v164, s47, v152
	s_barrier
	ds_read_b128 v[148:151], v164
	ds_read_b128 v[156:159], v164 offset:1024
	ds_read_b128 v[160:163], v164 offset:2048
	ds_read_b128 v[164:167], v164 offset:3072
	s_add_u32 s22, s22, 0x80000
	s_addc_u32 s23, s23, 0
	s_mov_b32 m0, s33
	v_lshl_add_u64 v[200:201], s[22:23], 0, v[130:131]
	ds_read_b128 v[168:171], v154 offset:32768
	ds_read_b128 v[172:175], v154 offset:33792
	ds_read_b128 v[176:179], v154 offset:34816
	ds_read_b128 v[180:183], v154 offset:35840
	ds_read_b128 v[184:187], v154 offset:36864
	ds_read_b128 v[188:191], v154 offset:37888
	ds_read_b128 v[192:195], v154 offset:38912
	ds_read_b128 v[196:199], v154 offset:39936
	global_load_lds_dwordx4 v[200:201], off
	v_lshl_add_u64 v[200:201], s[22:23], 0, v[134:135]
	s_mov_b32 m0, s34
	s_nop 0
	global_load_lds_dwordx4 v[200:201], off
	s_waitcnt lgkmcnt(8)
	s_barrier
	s_waitcnt lgkmcnt(0)
	s_waitcnt lgkmcnt(0)
	v_mfma_f32_16x16x32_bf16 v[126:129], v[148:151], v[168:171], v[126:129]
	v_mfma_f32_16x16x32_bf16 v[122:125], v[160:163], v[168:171], v[122:125]
	v_mfma_f32_16x16x32_bf16 v[110:113], v[148:151], v[176:179], v[110:113]
	v_mfma_f32_16x16x32_bf16 v[106:109], v[160:163], v[176:179], v[106:109]
	v_mfma_f32_16x16x32_bf16 v[94:97], v[148:151], v[184:187], v[94:97]
	v_mfma_f32_16x16x32_bf16 v[90:93], v[160:163], v[184:187], v[90:93]
	v_mfma_f32_16x16x32_bf16 v[78:81], v[148:151], v[192:195], v[78:81]
	v_mfma_f32_16x16x32_bf16 v[74:77], v[160:163], v[192:195], v[74:77]
	v_mfma_f32_16x16x32_bf16 v[126:129], v[156:159], v[172:175], v[126:129]
	v_mfma_f32_16x16x32_bf16 v[122:125], v[164:167], v[172:175], v[122:125]
	v_mfma_f32_16x16x32_bf16 v[110:113], v[156:159], v[180:183], v[110:113]
	v_mfma_f32_16x16x32_bf16 v[106:109], v[164:167], v[180:183], v[106:109]
	v_mfma_f32_16x16x32_bf16 v[94:97], v[156:159], v[188:191], v[94:97]
	v_mfma_f32_16x16x32_bf16 v[90:93], v[164:167], v[188:191], v[90:93]
	v_mfma_f32_16x16x32_bf16 v[78:81], v[156:159], v[196:199], v[78:81]
	v_mfma_f32_16x16x32_bf16 v[74:77], v[164:167], v[196:199], v[74:77]
	s_barrier
	s_add_i32 s22, 0, 0x1c000
	s_add_i32 s23, s47, s30
	v_add_u32_e32 v212, s22, v152
	v_lshl_add_u64 v[216:217], v[216:217], 0, s[2:3]
	s_mov_b32 m0, s23
	ds_read_b128 v[200:203], v212
	ds_read_b128 v[204:207], v212 offset:1024
	ds_read_b128 v[208:211], v212 offset:2048
	ds_read_b128 v[212:215], v212 offset:3072
	global_load_lds_dwordx4 v[216:217], off
	v_lshl_add_u64 v[216:217], v[218:219], 0, s[2:3]
	s_add_i32 m0, s23, 0x2000
	s_nop 0
	global_load_lds_dwordx4 v[216:217], off
	s_barrier
	s_waitcnt lgkmcnt(0)
	s_waitcnt lgkmcnt(0)
	v_mfma_f32_16x16x32_bf16 v[118:121], v[200:203], v[168:171], v[118:121]
	v_mfma_f32_16x16x32_bf16 v[114:117], v[208:211], v[168:171], v[114:117]
	v_mfma_f32_16x16x32_bf16 v[102:105], v[200:203], v[176:179], v[102:105]
	v_mfma_f32_16x16x32_bf16 v[98:101], v[208:211], v[176:179], v[98:101]
	v_mfma_f32_16x16x32_bf16 v[86:89], v[200:203], v[184:187], v[86:89]
	v_mfma_f32_16x16x32_bf16 v[82:85], v[208:211], v[184:187], v[82:85]
	v_mfma_f32_16x16x32_bf16 v[70:73], v[200:203], v[192:195], v[70:73]
	v_mfma_f32_16x16x32_bf16 v[66:69], v[208:211], v[192:195], v[66:69]
	v_mfma_f32_16x16x32_bf16 v[118:121], v[204:207], v[172:175], v[118:121]
	v_mfma_f32_16x16x32_bf16 v[114:117], v[212:215], v[172:175], v[114:117]
	v_mfma_f32_16x16x32_bf16 v[102:105], v[204:207], v[180:183], v[102:105]
	v_mfma_f32_16x16x32_bf16 v[98:101], v[212:215], v[180:183], v[98:101]
	v_mfma_f32_16x16x32_bf16 v[86:89], v[204:207], v[188:191], v[86:89]
	v_mfma_f32_16x16x32_bf16 v[82:85], v[212:215], v[188:191], v[82:85]
	v_mfma_f32_16x16x32_bf16 v[70:73], v[204:207], v[196:199], v[70:73]
	v_mfma_f32_16x16x32_bf16 v[66:69], v[212:215], v[196:199], v[66:69]
	s_mov_b32 m0, s36
	v_lshl_add_u64 v[216:217], v[220:221], 0, s[2:3]
	s_barrier
	ds_read_b128 v[168:171], v154 offset:49152
	ds_read_b128 v[172:175], v154 offset:50176
	ds_read_b128 v[176:179], v154 offset:51200
	ds_read_b128 v[180:183], v154 offset:52224
	ds_read_b128 v[184:187], v154 offset:53248
	ds_read_b128 v[188:191], v154 offset:54272
	ds_read_b128 v[192:195], v154 offset:55296
	ds_read_b128 v[196:199], v154 offset:56320
	global_load_lds_dwordx4 v[216:217], off
	v_lshl_add_u64 v[216:217], v[222:223], 0, s[2:3]
	s_mov_b32 m0, s37
	s_nop 0
	global_load_lds_dwordx4 v[216:217], off
	s_barrier
; template <class Epi>
; DI void gemm_phase(LAS unsigned char* lds, const Gemm g, const StaticOrder& S, const Epi& E) {
;     ...
;       PG8_BAR; PG8_WAIT_L(0); PG8_MMA(1, 0, At, B0); PG8_BAR; PG8_SCHED;
;       PG8_STAGE(PG8_SB(1, 1), b3 + hstepB, voffB);
;       PG8_WAIT_V(6); PG8_BAR; PG8_MMA(1, 1, At, B1); PG8_BAR;
;     }
;   DI void operator()(const f32x4 (&acc)[2][2][4][2], const pg8::Unit& u, int wr, int wc, int fr, int fq) const {
;     ...
;         if (MODE == EP_UP) rs = ((const float*)(ws + OFF_RS2))[grow];
;         if (MODE == EP_Q || MODE == EP_KV) {
;           const f32x4* sp = (const f32x4*)(ws + OFF_SSQA) + (size_t)grow * 4 + (MODE == EP_KV ? 2 : 0);
;           const f32x4 s0 = sp[0], s1 = sp[1];
;           const float ss = (s0[0] + s0[1]) + (s0[2] + s0[3]) + (s1[0] + s1[1]) + (s1[2] + s1[3]);
;           rs = __builtin_amdgcn_rsqf(ss * (1.0f / 512) + EPS);
;           if (MODE == EP_Q) rs *= QSCALE;
;         }
;         float ssq = 0.f;
; #pragma unroll
;         for (int bj = 0; bj < 2; ++bj) {
;           f32x4 v0 = acc[ai][bj][m][0] * rs, v1 = acc[ai][bj][m][1] * rs;
;           if (MODE == EP_IN || MODE == EP_MIX || MODE == EP_DOWN) {
; #pragma unroll
;             for (int j = 0; j < 4; ++j) ssq += v0[j] * v0[j] + v1[j] * v1[j];
;           }
;           if (MODE == EP_UP) {
; #pragma unroll
;             for (int j = 0; j < 4; ++j) { float a = fmaxf(v0[j], 0.f), b = fmaxf(v1[j], 0.f); v0[j] = a * a; v1[j] = b * b; }
;           }
;           bf16_t* dst;
;           const int ct = bj * 128 + cl;
;           if (MODE == EP_IN) {
;             if (pn < 4) dst = (bf16_t*)(ws + OFF_PROJA) + (size_t)grow * 1024 + pn * 256 + ct;
;             else if (pn < 16) dst = (bf16_t*)(ws + OFF_PROJG) + (size_t)grow * 3072 + (pn - 4) * 256 + ct;
;             else dst = (bf16_t*)(ws + OFF_PROJS) + (size_t)grow * 256 + ct;
;           } else if (MODE == EP_Q) {
;             if (pn < 4) dst = (bf16_t*)(dout + DO_Q) + (size_t)grow * 1536 + (pn * 2 + bj) * 192 + cl;
;             else {
;               const int mm = (pn - 4) * 256 + ct, h = mm >> 6, r = mm & 63;
;               dst = (bf16_t*)(dout + DO_Q) + (size_t)grow * 1536 + h * 192 + 128 + r;
;               const int pos = grow < TP ? (grow & 4095) : grow - TP;
;               const f32x4* tb = (const f32x4*)((const f32x2*)(ws + OFF_ROPE) + pos * 32 + (r >> 1));
	s_waitcnt lgkmcnt(0)
	s_waitcnt lgkmcnt(0)
	v_mfma_f32_16x16x32_bf16 v[62:65], v[148:151], v[168:171], v[62:65]
	v_mfma_f32_16x16x32_bf16 v[58:61], v[160:163], v[168:171], v[58:61]
	v_mfma_f32_16x16x32_bf16 v[46:49], v[148:151], v[176:179], v[46:49]
	v_mfma_f32_16x16x32_bf16 v[42:45], v[160:163], v[176:179], v[42:45]
	v_mfma_f32_16x16x32_bf16 v[30:33], v[148:151], v[184:187], v[30:33]
	v_mfma_f32_16x16x32_bf16 v[26:29], v[160:163], v[184:187], v[26:29]
	v_mfma_f32_16x16x32_bf16 v[14:17], v[148:151], v[192:195], v[14:17]
	v_mfma_f32_16x16x32_bf16 v[10:13], v[160:163], v[192:195], v[10:13]
	v_mfma_f32_16x16x32_bf16 v[62:65], v[156:159], v[172:175], v[62:65]
	v_mfma_f32_16x16x32_bf16 v[58:61], v[164:167], v[172:175], v[58:61]
	v_mfma_f32_16x16x32_bf16 v[46:49], v[156:159], v[180:183], v[46:49]
	v_mfma_f32_16x16x32_bf16 v[42:45], v[164:167], v[180:183], v[42:45]
	v_mfma_f32_16x16x32_bf16 v[30:33], v[156:159], v[188:191], v[30:33]
	v_mfma_f32_16x16x32_bf16 v[26:29], v[164:167], v[188:191], v[26:29]
	v_mfma_f32_16x16x32_bf16 v[14:17], v[156:159], v[196:199], v[14:17]
	v_mfma_f32_16x16x32_bf16 v[10:13], v[164:167], v[196:199], v[10:13]
	s_barrier
	s_add_u32 s20, s20, 0x80080
	s_addc_u32 s21, s21, 0
	s_add_i32 s22, s22, s30
	v_lshl_add_u64 v[148:149], s[20:21], 0, v[132:133]
	s_mov_b32 m0, s22
	s_nop 0
	global_load_lds_dwordx4 v[148:149], off
	v_lshl_add_u64 v[148:149], s[20:21], 0, v[136:137]
	s_add_i32 m0, s22, 0x2000
	s_nop 0
	global_load_lds_dwordx4 v[148:149], off
	s_waitcnt vmcnt(6)
	s_barrier
	v_mfma_f32_16x16x32_bf16 v[54:57], v[200:203], v[168:171], v[54:57]
	v_mfma_f32_16x16x32_bf16 v[50:53], v[208:211], v[168:171], v[50:53]
	v_mfma_f32_16x16x32_bf16 v[38:41], v[200:203], v[176:179], v[38:41]
	v_mfma_f32_16x16x32_bf16 v[34:37], v[208:211], v[176:179], v[34:37]
	v_mfma_f32_16x16x32_bf16 v[22:25], v[200:203], v[184:187], v[22:25]
	v_mfma_f32_16x16x32_bf16 v[18:21], v[208:211], v[184:187], v[18:21]
	v_mfma_f32_16x16x32_bf16 v[6:9], v[200:203], v[192:195], v[6:9]
	v_mfma_f32_16x16x32_bf16 v[2:5], v[208:211], v[192:195], v[2:5]
	v_mfma_f32_16x16x32_bf16 v[54:57], v[204:207], v[172:175], v[54:57]
	v_mfma_f32_16x16x32_bf16 v[50:53], v[212:215], v[172:175], v[50:53]
	v_mfma_f32_16x16x32_bf16 v[38:41], v[204:207], v[180:183], v[38:41]
	v_mfma_f32_16x16x32_bf16 v[34:37], v[212:215], v[180:183], v[34:37]
	v_mfma_f32_16x16x32_bf16 v[22:25], v[204:207], v[188:191], v[22:25]
	v_mfma_f32_16x16x32_bf16 v[18:21], v[212:215], v[188:191], v[18:21]
	v_mfma_f32_16x16x32_bf16 v[6:9], v[204:207], v[196:199], v[6:9]
	v_mfma_f32_16x16x32_bf16 v[2:5], v[212:215], v[196:199], v[2:5]
	s_add_i32 s46, s46, 2
	s_add_u32 s18, s18, 0x100
	s_addc_u32 s19, s19, 0
	s_add_u32 s44, s44, 0x100
	s_addc_u32 s45, s45, 0
	s_cmp_gt_u32 s46, 29
	s_barrier
	s_cbranch_scc0 .LBB0_1015
	v_lshl_add_u32 v148, s16, 8, v1
	v_ashrrev_i32_e32 v149, 31, v148
	v_lshl_add_u64 v[150:151], v[148:149], 2, s[4:5]
	v_add_co_u32_e32 v150, vcc, 0x10000, v150
	s_lshl_b32 s18, s41, 8
	s_nop 0
	v_addc_co_u32_e32 v151, vcc, 0, v151, vcc
	s_nop 0
	s_ashr_i32 s19, s18, 31
	v_lshlrev_b64 v[158:159], 14, v[148:149]
	s_lshl_b64 s[18:19], s[18:19], 1
	v_lshl_add_u64 v[158:159], s[6:7], 0, v[158:159]
	v_lshl_add_u64 v[158:159], v[158:159], 0, s[18:19]
	v_lshl_add_u64 v[158:159], v[158:159], 0, v[138:139]
	s_and_b64 vcc, exec, s[0:1]
	s_mov_b32 s41, s8
	s_mov_b32 s16, s10
	s_mov_b64 s[20:21], s[14:15]
	s_mov_b64 s[22:23], s[12:13]
	v_mov_b32_e32 v156, v247
	v_pk_mul_f32 v[128:129], v[128:129], v[156:157] op_sel_hi:[1,0]
	v_pk_mul_f32 v[126:127], v[126:127], v[156:157] op_sel_hi:[1,0]
	v_pk_mul_f32 v[124:125], v[124:125], v[156:157] op_sel_hi:[1,0]
	v_pk_mul_f32 v[122:123], v[122:123], v[156:157] op_sel_hi:[1,0]
	v_pk_mul_f32 v[120:121], v[120:121], v[156:157] op_sel_hi:[1,0]
	v_pk_mul_f32 v[118:119], v[118:119], v[156:157] op_sel_hi:[1,0]
	v_pk_mul_f32 v[116:117], v[116:117], v[156:157] op_sel_hi:[1,0]
	v_pk_mul_f32 v[114:115], v[114:115], v[156:157] op_sel_hi:[1,0]
	v_max_f32_e32 v126, 0, v126
	v_max_f32_e32 v122, 0, v122
	v_max_f32_e32 v127, 0, v127
	v_max_f32_e32 v123, 0, v123
	v_max_f32_e32 v128, 0, v128
	v_max_f32_e32 v124, 0, v124
	v_max_f32_e32 v129, 0, v129
	v_max_f32_e32 v125, 0, v125
	v_max_f32_e32 v118, 0, v118
	v_max_f32_e32 v114, 0, v114
	v_max_f32_e32 v119, 0, v119
	v_max_f32_e32 v115, 0, v115
	v_max_f32_e32 v120, 0, v120
	v_max_f32_e32 v116, 0, v116
	v_max_f32_e32 v121, 0, v121
	v_max_f32_e32 v117, 0, v117
	v_pk_mul_f32 v[126:127], v[126:127], v[126:127]
	v_pk_mul_f32 v[122:123], v[122:123], v[122:123]
	v_pk_mul_f32 v[128:129], v[128:129], v[128:129]
	v_pk_mul_f32 v[124:125], v[124:125], v[124:125]
	v_pk_mul_f32 v[118:119], v[118:119], v[118:119]
	v_pk_mul_f32 v[156:157], v[114:115], v[114:115]
	v_pk_mul_f32 v[120:121], v[120:121], v[120:121]
	v_pk_mul_f32 v[160:161], v[116:117], v[116:117]
	v_cvt_pk_bf16_f32 v114, v126, v127
	v_cvt_pk_bf16_f32 v115, v128, v129
	v_cvt_pk_bf16_f32 v116, v122, v123
	v_cvt_pk_bf16_f32 v117, v124, v125
	v_cvt_pk_bf16_f32 v118, v118, v119
	v_cvt_pk_bf16_f32 v119, v120, v121
	v_cvt_pk_bf16_f32 v120, v156, v157
	v_cvt_pk_bf16_f32 v121, v160, v161
	global_store_dwordx4 v[158:159], v[114:117], off
	global_store_dwordx4 v[158:159], v[118:121], off offset:256
	s_nop 0
	v_or_b32_e32 v116, 16, v148
	v_ashrrev_i32_e32 v117, 31, v116
	v_lshlrev_b64 v[116:117], 14, v[116:117]
	v_lshl_add_u64 v[116:117], s[6:7], 0, v[116:117]
	v_lshl_add_u64 v[116:117], v[116:117], 0, s[18:19]
	v_lshl_add_u64 v[116:117], v[116:117], 0, v[138:139]
	v_mov_b32_e32 v114, v240
	v_pk_mul_f32 v[112:113], v[112:113], v[114:115] op_sel_hi:[1,0]
	v_pk_mul_f32 v[110:111], v[110:111], v[114:115] op_sel_hi:[1,0]
;   DI void operator()(const f32x4 (&acc)[2][2][4][2], const pg8::Unit& u, int wr, int wc, int fr, int fq) const {
;     ...
;       for (int m = 0; m < 4; ++m) {
;         const int row = u.pm * 256 + ai * 128 + wr * 64 + m * 16 + fr;
;         const int grow = rowbase + row;
;         float rs = 1.f;
;         if (MODE == EP_IN) rs = ((const float*)(ws + OFF_RS0))[grow];
;         if (MODE == EP_UP) rs = ((const float*)(ws + OFF_RS2))[grow];
;         if (MODE == EP_Q || MODE == EP_KV) {
;           const f32x4* sp = (const f32x4*)(ws + OFF_SSQA) + (size_t)grow * 4 + (MODE == EP_KV ? 2 : 0);
;           const f32x4 s0 = sp[0], s1 = sp[1];
;           const float ss = (s0[0] + s0[1]) + (s0[2] + s0[3]) + (s1[0] + s1[1]) + (s1[2] + s1[3]);
;           rs = __builtin_amdgcn_rsqf(ss * (1.0f / 512) + EPS);
;           if (MODE == EP_Q) rs *= QSCALE;
;         }
;         float ssq = 0.f;
; #pragma unroll
;         for (int bj = 0; bj < 2; ++bj) {
;           f32x4 v0 = acc[ai][bj][m][0] * rs, v1 = acc[ai][bj][m][1] * rs;
;           if (MODE == EP_IN || MODE == EP_MIX || MODE == EP_DOWN) {
; #pragma unroll
;             for (int j = 0; j < 4; ++j) ssq += v0[j] * v0[j] + v1[j] * v1[j];
;           }
;           if (MODE == EP_UP) {
; #pragma unroll
;             for (int j = 0; j < 4; ++j) { float a = fmaxf(v0[j], 0.f), b = fmaxf(v1[j], 0.f); v0[j] = a * a; v1[j] = b * b; }
;           }
;           bf16_t* dst;
;           const int ct = bj * 128 + cl;
;           if (MODE == EP_IN) {
;             if (pn < 4) dst = (bf16_t*)(ws + OFF_PROJA) + (size_t)grow * 1024 + pn * 256 + ct;
;             else if (pn < 16) dst = (bf16_t*)(ws + OFF_PROJG) + (size_t)grow * 3072 + (pn - 4) * 256 + ct;
;             else dst = (bf16_t*)(ws + OFF_PROJS) + (size_t)grow * 256 + ct;
;           } else if (MODE == EP_Q) {
;             if (pn < 4) dst = (bf16_t*)(dout + DO_Q) + (size_t)grow * 1536 + (pn * 2 + bj) * 192 + cl;
;             else {
;               const int mm = (pn - 4) * 256 + ct, h = mm >> 6, r = mm & 63;
;               dst = (bf16_t*)(dout + DO_Q) + (size_t)grow * 1536 + h * 192 + 128 + r;
;               const int pos = grow < TP ? (grow & 4095) : grow - TP;
;               const f32x4* tb = (const f32x4*)((const f32x2*)(ws + OFF_ROPE) + pos * 32 + (r >> 1));
;               const f32x4 t0 = tb[0], t1 = tb[1];
;               f32x4 o0, o1;
	v_pk_mul_f32 v[108:109], v[108:109], v[114:115] op_sel_hi:[1,0]
	v_pk_mul_f32 v[106:107], v[106:107], v[114:115] op_sel_hi:[1,0]
	v_pk_mul_f32 v[104:105], v[104:105], v[114:115] op_sel_hi:[1,0]
	v_pk_mul_f32 v[102:103], v[102:103], v[114:115] op_sel_hi:[1,0]
	v_pk_mul_f32 v[100:101], v[100:101], v[114:115] op_sel_hi:[1,0]
	v_pk_mul_f32 v[98:99], v[98:99], v[114:115] op_sel_hi:[1,0]
	v_max_f32_e32 v110, 0, v110
	v_max_f32_e32 v106, 0, v106
	v_max_f32_e32 v111, 0, v111
	v_max_f32_e32 v107, 0, v107
	v_max_f32_e32 v112, 0, v112
	v_max_f32_e32 v108, 0, v108
	v_max_f32_e32 v113, 0, v113
	v_max_f32_e32 v109, 0, v109
	v_max_f32_e32 v102, 0, v102
	v_max_f32_e32 v98, 0, v98
	v_max_f32_e32 v103, 0, v103
	v_max_f32_e32 v99, 0, v99
	v_max_f32_e32 v104, 0, v104
	v_max_f32_e32 v100, 0, v100
	v_max_f32_e32 v105, 0, v105
	v_max_f32_e32 v101, 0, v101
	v_pk_mul_f32 v[110:111], v[110:111], v[110:111]
	v_pk_mul_f32 v[106:107], v[106:107], v[106:107]
	v_pk_mul_f32 v[112:113], v[112:113], v[112:113]
	v_pk_mul_f32 v[108:109], v[108:109], v[108:109]
	v_pk_mul_f32 v[102:103], v[102:103], v[102:103]
	v_pk_mul_f32 v[114:115], v[98:99], v[98:99]
	v_pk_mul_f32 v[104:105], v[104:105], v[104:105]
	v_pk_mul_f32 v[118:119], v[100:101], v[100:101]
	v_cvt_pk_bf16_f32 v98, v110, v111
	v_cvt_pk_bf16_f32 v99, v112, v113
	v_cvt_pk_bf16_f32 v100, v106, v107
	v_cvt_pk_bf16_f32 v101, v108, v109
	v_cvt_pk_bf16_f32 v102, v102, v103
	v_cvt_pk_bf16_f32 v103, v104, v105
	v_cvt_pk_bf16_f32 v104, v114, v115
	v_cvt_pk_bf16_f32 v105, v118, v119
	global_store_dwordx4 v[116:117], v[98:101], off
	global_store_dwordx4 v[116:117], v[102:105], off offset:256
	s_nop 0
	v_or_b32_e32 v100, 32, v148
	v_ashrrev_i32_e32 v101, 31, v100
	v_lshlrev_b64 v[100:101], 14, v[100:101]
	v_lshl_add_u64 v[100:101], s[6:7], 0, v[100:101]
	v_lshl_add_u64 v[100:101], v[100:101], 0, s[18:19]
	v_lshl_add_u64 v[100:101], v[100:101], 0, v[138:139]
	v_mov_b32_e32 v98, v241
	v_pk_mul_f32 v[96:97], v[96:97], v[98:99] op_sel_hi:[1,0]
	v_pk_mul_f32 v[94:95], v[94:95], v[98:99] op_sel_hi:[1,0]
	v_pk_mul_f32 v[92:93], v[92:93], v[98:99] op_sel_hi:[1,0]
	v_pk_mul_f32 v[90:91], v[90:91], v[98:99] op_sel_hi:[1,0]
	v_pk_mul_f32 v[88:89], v[88:89], v[98:99] op_sel_hi:[1,0]
	v_pk_mul_f32 v[86:87], v[86:87], v[98:99] op_sel_hi:[1,0]
	v_pk_mul_f32 v[84:85], v[84:85], v[98:99] op_sel_hi:[1,0]
	v_pk_mul_f32 v[82:83], v[82:83], v[98:99] op_sel_hi:[1,0]
	v_max_f32_e32 v94, 0, v94
	v_max_f32_e32 v90, 0, v90
	v_max_f32_e32 v95, 0, v95
	v_max_f32_e32 v91, 0, v91
	v_max_f32_e32 v96, 0, v96
	v_max_f32_e32 v92, 0, v92
	v_max_f32_e32 v97, 0, v97
	v_max_f32_e32 v93, 0, v93
	v_max_f32_e32 v86, 0, v86
	v_max_f32_e32 v82, 0, v82
	v_max_f32_e32 v87, 0, v87
	v_max_f32_e32 v83, 0, v83
	v_max_f32_e32 v88, 0, v88
	v_max_f32_e32 v84, 0, v84
	v_max_f32_e32 v89, 0, v89
	v_max_f32_e32 v85, 0, v85
	v_pk_mul_f32 v[94:95], v[94:95], v[94:95]
	v_pk_mul_f32 v[90:91], v[90:91], v[90:91]
	v_pk_mul_f32 v[96:97], v[96:97], v[96:97]
	v_pk_mul_f32 v[92:93], v[92:93], v[92:93]
	v_pk_mul_f32 v[86:87], v[86:87], v[86:87]
	v_pk_mul_f32 v[98:99], v[82:83], v[82:83]
	v_pk_mul_f32 v[88:89], v[88:89], v[88:89]
	v_pk_mul_f32 v[102:103], v[84:85], v[84:85]
	v_cvt_pk_bf16_f32 v82, v94, v95
	v_cvt_pk_bf16_f32 v83, v96, v97
	v_cvt_pk_bf16_f32 v84, v90, v91
	v_cvt_pk_bf16_f32 v85, v92, v93
	v_cvt_pk_bf16_f32 v86, v86, v87
	v_cvt_pk_bf16_f32 v87, v88, v89
	v_cvt_pk_bf16_f32 v88, v98, v99
	v_cvt_pk_bf16_f32 v89, v102, v103
	global_store_dwordx4 v[100:101], v[82:85], off
	global_store_dwordx4 v[100:101], v[86:89], off offset:256
	s_nop 0
	v_or_b32_e32 v84, 48, v148
	v_ashrrev_i32_e32 v85, 31, v84
	v_lshlrev_b64 v[84:85], 14, v[84:85]
	v_lshl_add_u64 v[84:85], s[6:7], 0, v[84:85]
	v_add_u32_e32 v86, 0x4080, v148
	v_lshl_add_u64 v[84:85], v[84:85], 0, s[18:19]
	v_ashrrev_i32_e32 v87, 31, v86
	v_lshl_add_u64 v[84:85], v[84:85], 0, v[138:139]
	v_lshl_add_u64 v[86:87], v[86:87], 2, s[4:5]
	v_mov_b32_e32 v82, v242
	v_pk_mul_f32 v[80:81], v[80:81], v[82:83] op_sel_hi:[1,0]
	v_pk_mul_f32 v[78:79], v[78:79], v[82:83] op_sel_hi:[1,0]
	v_pk_mul_f32 v[76:77], v[76:77], v[82:83] op_sel_hi:[1,0]
	v_pk_mul_f32 v[74:75], v[74:75], v[82:83] op_sel_hi:[1,0]
	v_pk_mul_f32 v[72:73], v[72:73], v[82:83] op_sel_hi:[1,0]
	v_pk_mul_f32 v[70:71], v[70:71], v[82:83] op_sel_hi:[1,0]
	v_pk_mul_f32 v[68:69], v[68:69], v[82:83] op_sel_hi:[1,0]
	v_pk_mul_f32 v[66:67], v[66:67], v[82:83] op_sel_hi:[1,0]
	v_max_f32_e32 v78, 0, v78
	v_max_f32_e32 v74, 0, v74
	v_max_f32_e32 v79, 0, v79
	v_max_f32_e32 v75, 0, v75
	v_max_f32_e32 v80, 0, v80
	v_max_f32_e32 v76, 0, v76
	v_max_f32_e32 v81, 0, v81
	v_max_f32_e32 v77, 0, v77
	v_max_f32_e32 v70, 0, v70
	v_max_f32_e32 v66, 0, v66
	v_max_f32_e32 v71, 0, v71
	v_max_f32_e32 v67, 0, v67
	v_max_f32_e32 v72, 0, v72
	v_max_f32_e32 v68, 0, v68
	v_max_f32_e32 v73, 0, v73
	v_max_f32_e32 v69, 0, v69
	v_pk_mul_f32 v[78:79], v[78:79], v[78:79]
	v_pk_mul_f32 v[74:75], v[74:75], v[74:75]
	v_pk_mul_f32 v[80:81], v[80:81], v[80:81]
	v_pk_mul_f32 v[76:77], v[76:77], v[76:77]
	v_pk_mul_f32 v[70:71], v[70:71], v[70:71]
	v_pk_mul_f32 v[82:83], v[66:67], v[66:67]
	v_pk_mul_f32 v[72:73], v[72:73], v[72:73]
	v_pk_mul_f32 v[88:89], v[68:69], v[68:69]
	v_cvt_pk_bf16_f32 v66, v78, v79
	v_cvt_pk_bf16_f32 v67, v80, v81
	v_cvt_pk_bf16_f32 v68, v74, v75
	v_cvt_pk_bf16_f32 v69, v76, v77
	v_cvt_pk_bf16_f32 v70, v70, v71
	v_cvt_pk_bf16_f32 v71, v72, v73
	v_cvt_pk_bf16_f32 v72, v82, v83
	v_cvt_pk_bf16_f32 v73, v88, v89
	global_store_dwordx4 v[84:85], v[66:69], off
	global_store_dwordx4 v[84:85], v[70:73], off offset:256
	s_nop 0
	v_add_u32_e32 v68, 0x80, v148
	v_ashrrev_i32_e32 v69, 31, v68
;   DI void operator()(const f32x4 (&acc)[2][2][4][2], const pg8::Unit& u, int wr, int wc, int fr, int fq) const {
;     ...
;       for (int m = 0; m < 4; ++m) {
;         const int row = u.pm * 256 + ai * 128 + wr * 64 + m * 16 + fr;
;         const int grow = rowbase + row;
;         float rs = 1.f;
;         if (MODE == EP_IN) rs = ((const float*)(ws + OFF_RS0))[grow];
;         if (MODE == EP_UP) rs = ((const float*)(ws + OFF_RS2))[grow];
;         if (MODE == EP_Q || MODE == EP_KV) {
;           const f32x4* sp = (const f32x4*)(ws + OFF_SSQA) + (size_t)grow * 4 + (MODE == EP_KV ? 2 : 0);
;           const f32x4 s0 = sp[0], s1 = sp[1];
;           const float ss = (s0[0] + s0[1]) + (s0[2] + s0[3]) + (s1[0] + s1[1]) + (s1[2] + s1[3]);
;           rs = __builtin_amdgcn_rsqf(ss * (1.0f / 512) + EPS);
;           if (MODE == EP_Q) rs *= QSCALE;
;         }
;         float ssq = 0.f;
; #pragma unroll
;         for (int bj = 0; bj < 2; ++bj) {
;           f32x4 v0 = acc[ai][bj][m][0] * rs, v1 = acc[ai][bj][m][1] * rs;
;           if (MODE == EP_IN || MODE == EP_MIX || MODE == EP_DOWN) {
; #pragma unroll
;             for (int j = 0; j < 4; ++j) ssq += v0[j] * v0[j] + v1[j] * v1[j];
;           }
;           if (MODE == EP_UP) {
; #pragma unroll
;             for (int j = 0; j < 4; ++j) { float a = fmaxf(v0[j], 0.f), b = fmaxf(v1[j], 0.f); v0[j] = a * a; v1[j] = b * b; }
;           }
;           bf16_t* dst;
;           const int ct = bj * 128 + cl;
;           if (MODE == EP_IN) {
;             if (pn < 4) dst = (bf16_t*)(ws + OFF_PROJA) + (size_t)grow * 1024 + pn * 256 + ct;
;             else if (pn < 16) dst = (bf16_t*)(ws + OFF_PROJG) + (size_t)grow * 3072 + (pn - 4) * 256 + ct;
;             else dst = (bf16_t*)(ws + OFF_PROJS) + (size_t)grow * 256 + ct;
;           } else if (MODE == EP_Q) {
;             if (pn < 4) dst = (bf16_t*)(dout + DO_Q) + (size_t)grow * 1536 + (pn * 2 + bj) * 192 + cl;
;             else {
;               const int mm = (pn - 4) * 256 + ct, h = mm >> 6, r = mm & 63;
;               dst = (bf16_t*)(dout + DO_Q) + (size_t)grow * 1536 + h * 192 + 128 + r;
;               const int pos = grow < TP ? (grow & 4095) : grow - TP;
;               const f32x4* tb = (const f32x4*)((const f32x2*)(ws + OFF_ROPE) + pos * 32 + (r >> 1));
;               const f32x4 t0 = tb[0], t1 = tb[1];
;               f32x4 o0, o1;
	v_lshlrev_b64 v[68:69], 14, v[68:69]
	v_lshl_add_u64 v[68:69], s[6:7], 0, v[68:69]
	v_add_u32_e32 v70, 0x4090, v148
	v_lshl_add_u64 v[68:69], v[68:69], 0, s[18:19]
	v_ashrrev_i32_e32 v71, 31, v70
	v_lshl_add_u64 v[68:69], v[68:69], 0, v[138:139]
	v_lshl_add_u64 v[70:71], v[70:71], 2, s[4:5]
	v_mov_b32_e32 v66, v243
	v_pk_mul_f32 v[64:65], v[64:65], v[66:67] op_sel_hi:[1,0]
	v_pk_mul_f32 v[62:63], v[62:63], v[66:67] op_sel_hi:[1,0]
	v_pk_mul_f32 v[60:61], v[60:61], v[66:67] op_sel_hi:[1,0]
	v_pk_mul_f32 v[58:59], v[58:59], v[66:67] op_sel_hi:[1,0]
	v_pk_mul_f32 v[56:57], v[56:57], v[66:67] op_sel_hi:[1,0]
	v_pk_mul_f32 v[54:55], v[54:55], v[66:67] op_sel_hi:[1,0]
	v_pk_mul_f32 v[52:53], v[52:53], v[66:67] op_sel_hi:[1,0]
	v_pk_mul_f32 v[50:51], v[50:51], v[66:67] op_sel_hi:[1,0]
	v_max_f32_e32 v62, 0, v62
	v_max_f32_e32 v58, 0, v58
	v_max_f32_e32 v63, 0, v63
	v_max_f32_e32 v59, 0, v59
	v_max_f32_e32 v64, 0, v64
	v_max_f32_e32 v60, 0, v60
	v_max_f32_e32 v65, 0, v65
	v_max_f32_e32 v61, 0, v61
	v_max_f32_e32 v54, 0, v54
	v_max_f32_e32 v50, 0, v50
	v_max_f32_e32 v55, 0, v55
	v_max_f32_e32 v51, 0, v51
	v_max_f32_e32 v56, 0, v56
	v_max_f32_e32 v52, 0, v52
	v_max_f32_e32 v57, 0, v57
	v_max_f32_e32 v53, 0, v53
	v_pk_mul_f32 v[62:63], v[62:63], v[62:63]
	v_pk_mul_f32 v[58:59], v[58:59], v[58:59]
	v_pk_mul_f32 v[64:65], v[64:65], v[64:65]
	v_pk_mul_f32 v[60:61], v[60:61], v[60:61]
	v_pk_mul_f32 v[54:55], v[54:55], v[54:55]
	v_pk_mul_f32 v[66:67], v[50:51], v[50:51]
	v_pk_mul_f32 v[56:57], v[56:57], v[56:57]
	v_pk_mul_f32 v[72:73], v[52:53], v[52:53]
	v_cvt_pk_bf16_f32 v50, v62, v63
	v_cvt_pk_bf16_f32 v51, v64, v65
	v_cvt_pk_bf16_f32 v52, v58, v59
	v_cvt_pk_bf16_f32 v53, v60, v61
	v_cvt_pk_bf16_f32 v54, v54, v55
	v_cvt_pk_bf16_f32 v55, v56, v57
	v_cvt_pk_bf16_f32 v56, v66, v67
	v_cvt_pk_bf16_f32 v57, v72, v73
	global_store_dwordx4 v[68:69], v[50:53], off
	global_store_dwordx4 v[68:69], v[54:57], off offset:256
	s_nop 0
	v_add_u32_e32 v52, 0x90, v148
	v_ashrrev_i32_e32 v53, 31, v52
	v_lshlrev_b64 v[52:53], 14, v[52:53]
	v_lshl_add_u64 v[52:53], s[6:7], 0, v[52:53]
	v_add_u32_e32 v54, 0x40a0, v148
	v_lshl_add_u64 v[52:53], v[52:53], 0, s[18:19]
	v_ashrrev_i32_e32 v55, 31, v54
	v_lshl_add_u64 v[52:53], v[52:53], 0, v[138:139]
	v_lshl_add_u64 v[54:55], v[54:55], 2, s[4:5]
	v_mov_b32_e32 v50, v244
	v_pk_mul_f32 v[48:49], v[48:49], v[50:51] op_sel_hi:[1,0]
	v_pk_mul_f32 v[46:47], v[46:47], v[50:51] op_sel_hi:[1,0]
	v_pk_mul_f32 v[44:45], v[44:45], v[50:51] op_sel_hi:[1,0]
	v_pk_mul_f32 v[42:43], v[42:43], v[50:51] op_sel_hi:[1,0]
	v_pk_mul_f32 v[40:41], v[40:41], v[50:51] op_sel_hi:[1,0]
	v_pk_mul_f32 v[38:39], v[38:39], v[50:51] op_sel_hi:[1,0]
	v_pk_mul_f32 v[36:37], v[36:37], v[50:51] op_sel_hi:[1,0]
	v_pk_mul_f32 v[34:35], v[34:35], v[50:51] op_sel_hi:[1,0]
	v_max_f32_e32 v46, 0, v46
	v_max_f32_e32 v42, 0, v42
	v_max_f32_e32 v47, 0, v47
	v_max_f32_e32 v43, 0, v43
	v_max_f32_e32 v48, 0, v48
	v_max_f32_e32 v44, 0, v44
	v_max_f32_e32 v49, 0, v49
	v_max_f32_e32 v45, 0, v45
	v_max_f32_e32 v38, 0, v38
	v_max_f32_e32 v34, 0, v34
	v_max_f32_e32 v39, 0, v39
	v_max_f32_e32 v35, 0, v35
	v_max_f32_e32 v40, 0, v40
	v_max_f32_e32 v36, 0, v36
	v_max_f32_e32 v41, 0, v41
	v_max_f32_e32 v37, 0, v37
	v_pk_mul_f32 v[46:47], v[46:47], v[46:47]
	v_pk_mul_f32 v[42:43], v[42:43], v[42:43]
	v_pk_mul_f32 v[48:49], v[48:49], v[48:49]
	v_pk_mul_f32 v[44:45], v[44:45], v[44:45]
	v_pk_mul_f32 v[38:39], v[38:39], v[38:39]
	v_pk_mul_f32 v[50:51], v[34:35], v[34:35]
	v_pk_mul_f32 v[40:41], v[40:41], v[40:41]
	v_pk_mul_f32 v[56:57], v[36:37], v[36:37]
	v_cvt_pk_bf16_f32 v34, v46, v47
	v_cvt_pk_bf16_f32 v35, v48, v49
	v_cvt_pk_bf16_f32 v36, v42, v43
	v_cvt_pk_bf16_f32 v37, v44, v45
	v_cvt_pk_bf16_f32 v38, v38, v39
	v_cvt_pk_bf16_f32 v39, v40, v41
	v_cvt_pk_bf16_f32 v40, v50, v51
	v_cvt_pk_bf16_f32 v41, v56, v57
	global_store_dwordx4 v[52:53], v[34:37], off
	global_store_dwordx4 v[52:53], v[38:41], off offset:256
;   DI void operator()(const f32x4 (&acc)[2][2][4][2], const pg8::Unit& u, int wr, int wc, int fr, int fq) const {
;     ...
;       for (int m = 0; m < 4; ++m) {
;         const int row = u.pm * 256 + ai * 128 + wr * 64 + m * 16 + fr;
;         const int grow = rowbase + row;
;         float rs = 1.f;
;         if (MODE == EP_IN) rs = ((const float*)(ws + OFF_RS0))[grow];
;         if (MODE == EP_UP) rs = ((const float*)(ws + OFF_RS2))[grow];
;         if (MODE == EP_Q || MODE == EP_KV) {
;           const f32x4* sp = (const f32x4*)(ws + OFF_SSQA) + (size_t)grow * 4 + (MODE == EP_KV ? 2 : 0);
;           const f32x4 s0 = sp[0], s1 = sp[1];
;           const float ss = (s0[0] + s0[1]) + (s0[2] + s0[3]) + (s1[0] + s1[1]) + (s1[2] + s1[3]);
;           rs = __builtin_amdgcn_rsqf(ss * (1.0f / 512) + EPS);
;           if (MODE == EP_Q) rs *= QSCALE;
;         }
;         float ssq = 0.f;
; #pragma unroll
;         for (int bj = 0; bj < 2; ++bj) {
;           f32x4 v0 = acc[ai][bj][m][0] * rs, v1 = acc[ai][bj][m][1] * rs;
;           if (MODE == EP_IN || MODE == EP_MIX || MODE == EP_DOWN) {
; #pragma unroll
;             for (int j = 0; j < 4; ++j) ssq += v0[j] * v0[j] + v1[j] * v1[j];
;           }
;           if (MODE == EP_UP) {
; #pragma unroll
;             for (int j = 0; j < 4; ++j) { float a = fmaxf(v0[j], 0.f), b = fmaxf(v1[j], 0.f); v0[j] = a * a; v1[j] = b * b; }
;           }
;           bf16_t* dst;
;           const int ct = bj * 128 + cl;
;           if (MODE == EP_IN) {
;             if (pn < 4) dst = (bf16_t*)(ws + OFF_PROJA) + (size_t)grow * 1024 + pn * 256 + ct;
;             else if (pn < 16) dst = (bf16_t*)(ws + OFF_PROJG) + (size_t)grow * 3072 + (pn - 4) * 256 + ct;
;             else dst = (bf16_t*)(ws + OFF_PROJS) + (size_t)grow * 256 + ct;
;           } else if (MODE == EP_Q) {
;             if (pn < 4) dst = (bf16_t*)(dout + DO_Q) + (size_t)grow * 1536 + (pn * 2 + bj) * 192 + cl;
;             else {
;               const int mm = (pn - 4) * 256 + ct, h = mm >> 6, r = mm & 63;
;               dst = (bf16_t*)(dout + DO_Q) + (size_t)grow * 1536 + h * 192 + 128 + r;
;               const int pos = grow < TP ? (grow & 4095) : grow - TP;
;               const f32x4* tb = (const f32x4*)((const f32x2*)(ws + OFF_ROPE) + pos * 32 + (r >> 1));
;               const f32x4 t0 = tb[0], t1 = tb[1];
;               f32x4 o0, o1;
	s_nop 0
	v_add_u32_e32 v36, 0xa0, v148
	v_ashrrev_i32_e32 v37, 31, v36
	v_lshlrev_b64 v[36:37], 14, v[36:37]
	v_lshl_add_u64 v[36:37], s[6:7], 0, v[36:37]
	v_add_u32_e32 v38, 0x40b0, v148
	v_lshl_add_u64 v[36:37], v[36:37], 0, s[18:19]
	v_ashrrev_i32_e32 v39, 31, v38
	v_lshl_add_u64 v[36:37], v[36:37], 0, v[138:139]
	v_lshl_add_u64 v[38:39], v[38:39], 2, s[4:5]
	v_mov_b32_e32 v34, v245
	v_pk_mul_f32 v[32:33], v[32:33], v[34:35] op_sel_hi:[1,0]
	v_pk_mul_f32 v[30:31], v[30:31], v[34:35] op_sel_hi:[1,0]
	v_pk_mul_f32 v[28:29], v[28:29], v[34:35] op_sel_hi:[1,0]
	v_pk_mul_f32 v[26:27], v[26:27], v[34:35] op_sel_hi:[1,0]
	v_pk_mul_f32 v[24:25], v[24:25], v[34:35] op_sel_hi:[1,0]
	v_pk_mul_f32 v[22:23], v[22:23], v[34:35] op_sel_hi:[1,0]
	v_pk_mul_f32 v[20:21], v[20:21], v[34:35] op_sel_hi:[1,0]
	v_pk_mul_f32 v[18:19], v[18:19], v[34:35] op_sel_hi:[1,0]
	v_max_f32_e32 v30, 0, v30
	v_max_f32_e32 v26, 0, v26
	v_max_f32_e32 v31, 0, v31
	v_max_f32_e32 v27, 0, v27
	v_max_f32_e32 v32, 0, v32
	v_max_f32_e32 v28, 0, v28
	v_max_f32_e32 v33, 0, v33
	v_max_f32_e32 v29, 0, v29
	v_max_f32_e32 v22, 0, v22
	v_max_f32_e32 v18, 0, v18
	v_max_f32_e32 v23, 0, v23
	v_max_f32_e32 v19, 0, v19
	v_max_f32_e32 v24, 0, v24
	v_max_f32_e32 v20, 0, v20
	v_max_f32_e32 v25, 0, v25
	v_max_f32_e32 v21, 0, v21
	v_pk_mul_f32 v[30:31], v[30:31], v[30:31]
	v_pk_mul_f32 v[26:27], v[26:27], v[26:27]
	v_pk_mul_f32 v[32:33], v[32:33], v[32:33]
	v_pk_mul_f32 v[28:29], v[28:29], v[28:29]
	v_pk_mul_f32 v[22:23], v[22:23], v[22:23]
	v_pk_mul_f32 v[34:35], v[18:19], v[18:19]
	v_pk_mul_f32 v[24:25], v[24:25], v[24:25]
	v_pk_mul_f32 v[40:41], v[20:21], v[20:21]
	v_cvt_pk_bf16_f32 v18, v30, v31
	v_cvt_pk_bf16_f32 v19, v32, v33
	v_cvt_pk_bf16_f32 v20, v26, v27
	v_cvt_pk_bf16_f32 v21, v28, v29
	v_cvt_pk_bf16_f32 v22, v22, v23
	v_cvt_pk_bf16_f32 v23, v24, v25
	v_cvt_pk_bf16_f32 v24, v34, v35
	v_cvt_pk_bf16_f32 v25, v40, v41
	global_store_dwordx4 v[36:37], v[18:21], off
	global_store_dwordx4 v[36:37], v[22:25], off offset:256
	s_nop 0
	v_add_u32_e32 v20, 0xb0, v148
	v_ashrrev_i32_e32 v21, 31, v20
	v_lshlrev_b64 v[20:21], 14, v[20:21]
	v_lshl_add_u64 v[20:21], s[6:7], 0, v[20:21]
	v_lshl_add_u64 v[20:21], v[20:21], 0, s[18:19]
	v_lshl_add_u64 v[20:21], v[20:21], 0, v[138:139]
	v_mov_b32_e32 v18, v246
	v_pk_mul_f32 v[16:17], v[16:17], v[18:19] op_sel_hi:[1,0]
	v_pk_mul_f32 v[14:15], v[14:15], v[18:19] op_sel_hi:[1,0]
	v_pk_mul_f32 v[12:13], v[12:13], v[18:19] op_sel_hi:[1,0]
	v_pk_mul_f32 v[10:11], v[10:11], v[18:19] op_sel_hi:[1,0]
	v_pk_mul_f32 v[8:9], v[8:9], v[18:19] op_sel_hi:[1,0]
	v_pk_mul_f32 v[6:7], v[6:7], v[18:19] op_sel_hi:[1,0]
	v_pk_mul_f32 v[4:5], v[4:5], v[18:19] op_sel_hi:[1,0]
	v_pk_mul_f32 v[2:3], v[2:3], v[18:19] op_sel_hi:[1,0]
	v_max_f32_e32 v14, 0, v14
	v_max_f32_e32 v10, 0, v10
	v_max_f32_e32 v15, 0, v15
	v_max_f32_e32 v11, 0, v11
	v_max_f32_e32 v16, 0, v16
	v_max_f32_e32 v12, 0, v12
	v_max_f32_e32 v17, 0, v17
	v_max_f32_e32 v13, 0, v13
	v_max_f32_e32 v6, 0, v6
	v_max_f32_e32 v2, 0, v2
	v_max_f32_e32 v7, 0, v7
	v_max_f32_e32 v3, 0, v3
	v_max_f32_e32 v8, 0, v8
	v_max_f32_e32 v4, 0, v4
	v_max_f32_e32 v9, 0, v9
	v_max_f32_e32 v5, 0, v5
	v_pk_mul_f32 v[14:15], v[14:15], v[14:15]
	v_pk_mul_f32 v[10:11], v[10:11], v[10:11]
	v_pk_mul_f32 v[16:17], v[16:17], v[16:17]
	v_pk_mul_f32 v[12:13], v[12:13], v[12:13]
	v_pk_mul_f32 v[6:7], v[6:7], v[6:7]
	v_pk_mul_f32 v[18:19], v[2:3], v[2:3]
	v_pk_mul_f32 v[8:9], v[8:9], v[8:9]
	v_pk_mul_f32 v[22:23], v[4:5], v[4:5]
	v_cvt_pk_bf16_f32 v2, v14, v15
	v_cvt_pk_bf16_f32 v3, v16, v17
	v_cvt_pk_bf16_f32 v4, v10, v11
	v_cvt_pk_bf16_f32 v5, v12, v13
	v_cvt_pk_bf16_f32 v6, v6, v7
	v_cvt_pk_bf16_f32 v7, v8, v9
	v_cvt_pk_bf16_f32 v8, v18, v19
	v_cvt_pk_bf16_f32 v9, v22, v23
	global_store_dwordx4 v[20:21], v[2:5], off
	global_store_dwordx4 v[20:21], v[6:9], off offset:256
	s_cbranch_vccz .LBB0_1008
	s_waitcnt vmcnt(0)
	s_cmpk_gt_u32 s24, 0xff
	s_cbranch_scc1 .LBB0_1019
	s_barrier

; #define PG8_STAGE(bufoff, gbase, voff) do { _Pragma("unroll") for (int _i = 0; _i < 2; ++_i) \
;     __builtin_amdgcn_global_load_lds((const unsigned*)((const char*)(gbase) + (voff)[_i]), (LAS unsigned*)(lds + (bufoff) + ldsw + _i * 8192), 16, 0, 0); } while (0)
; #define PG8_LDA(dst, b, h) do { _Pragma("unroll") for (int m = 0; m < 4; ++m) _Pragma("unroll") for (int k = 0; k < 2; ++k) dst[m][k] = *(const LAS bf16x8*)(lds + PG8_SA(b, h) + aoff + m * 2048 + k * 1024); } while (0)
; #define PG8_LDB(dst, b, h) do { _Pragma("unroll") for (int n = 0; n < 2; ++n) _Pragma("unroll") for (int k = 0; k < 2; ++k) dst[n][k] = *(const LAS bf16x8*)(lds + PG8_SB(b, h) + boff + n * 2048 + k * 1024); } while (0)
; #define PG8_MMA(ai, bj, At, Bt) do { __builtin_amdgcn_s_setprio(1); _Pragma("unroll") for (int m = 0; m < 4; ++m) _Pragma("unroll") for (int n = 0; n < 2; ++n) _Pragma("unroll") for (int k = 0; k < 2; ++k) \
;     acc[ai][bj][m][n] = __builtin_amdgcn_mfma_f32_16x16x32_bf16(Bt[n][k], At[m][k], acc[ai][bj][m][n], 0, 0, 0); __builtin_amdgcn_s_setprio(0); } while (0)
; #define PG8_WAIT_V(n) asm volatile("s_waitcnt vmcnt(" #n ")" ::: "memory")
; #define PG8_WAIT_L(n) asm volatile("s_waitcnt lgkmcnt(" #n ")" ::: "memory")
; #define PG8_BAR __builtin_amdgcn_s_barrier()
; #define PG8_SCHED __builtin_amdgcn_sched_barrier(0)
; template <class Epi>
; DI void gemm_phase(LAS unsigned char* lds, const Gemm g, const StaticOrder& S, const Epi& E) {
;     ...
;     for (int t = 0; t < nt; t += 2) {
;       const bool last = (t == nt - 2);
;       const char* a1 = cA + PG8_AK(t + 1);
;       const char* a2 = last ? nA : cA + PG8_AK(t + 2); const char* b2 = last ? nB : cB + (size_t)(t + 2) * kstep;
;       const char* a3 = a2 + kstep; const char* b3 = b2 + kstep;
;       PG8_LDB(B0, 0, 0); PG8_SCHED; PG8_LDA(At, 0, 0); PG8_STAGE(PG8_SA(1, 1), a1 + hstepA, voffA);
;       PG8_WAIT_L(8); PG8_BAR; PG8_WAIT_L(0); PG8_MMA(0, 0, At, B0); PG8_BAR; PG8_SCHED;
;       PG8_LDB(B1, 0, 1); PG8_STAGE(PG8_SB(0, 0), b2, voffB);
;       PG8_BAR; PG8_WAIT_L(0); PG8_MMA(0, 1, At, B1); PG8_BAR;
;       PG8_LDA(At, 0, 1); PG8_STAGE(PG8_SA(0, 0), a2, voffA);
;       PG8_BAR; PG8_WAIT_L(0); PG8_MMA(1, 0, At, B0); PG8_BAR; PG8_SCHED;
;       PG8_STAGE(PG8_SB(0, 1), b2 + hstepB, voffB);
;       PG8_WAIT_V(6); PG8_BAR; PG8_MMA(1, 1, At, B1); PG8_BAR;
.LBB0_1056:
	ds_read_b128 v[156:159], v151
	ds_read_b128 v[160:163], v151 offset:1024
	ds_read_b128 v[164:167], v151 offset:2048
	ds_read_b128 v[168:171], v151 offset:3072
	s_add_u32 s22, s20, 0xffe00080
	s_addc_u32 s23, s21, -1
	s_cmpk_eq_i32 s48, 0x7c
	s_cselect_b32 s25, s13, s23
	s_cselect_b32 s24, s19, s22
	s_cselect_b32 s23, s11, s47
	s_cselect_b32 s22, s45, s46
	v_lshl_add_u64 v[148:149], s[20:21], 0, v[140:141]
	s_add_i32 m0, s33, 0xc000
	ds_read_b128 v[172:175], v152
	ds_read_b128 v[176:179], v152 offset:1024
	ds_read_b128 v[180:183], v152 offset:2048
	ds_read_b128 v[184:187], v152 offset:3072
	ds_read_b128 v[188:191], v152 offset:4096
	ds_read_b128 v[192:195], v152 offset:5120
	ds_read_b128 v[196:199], v152 offset:6144
	ds_read_b128 v[200:203], v152 offset:7168
	global_load_lds_dwordx4 v[148:149], off
	v_lshl_add_u64 v[148:149], s[20:21], 0, v[142:143]
	s_add_i32 m0, s33, 0xe000
	s_nop 0
	global_load_lds_dwordx4 v[148:149], off
	s_waitcnt lgkmcnt(8)
	s_barrier
	s_waitcnt lgkmcnt(0)
	s_waitcnt lgkmcnt(0)
	v_mfma_f32_16x16x32_bf16 v[126:129], v[156:159], v[172:175], v[126:129]
	v_mfma_f32_16x16x32_bf16 v[122:125], v[164:167], v[172:175], v[122:125]
	v_mfma_f32_16x16x32_bf16 v[110:113], v[156:159], v[180:183], v[110:113]
	v_mfma_f32_16x16x32_bf16 v[106:109], v[164:167], v[180:183], v[106:109]
	v_mfma_f32_16x16x32_bf16 v[94:97], v[156:159], v[188:191], v[94:97]
	v_mfma_f32_16x16x32_bf16 v[90:93], v[164:167], v[188:191], v[90:93]
	v_mfma_f32_16x16x32_bf16 v[78:81], v[156:159], v[196:199], v[78:81]
	v_mfma_f32_16x16x32_bf16 v[74:77], v[164:167], v[196:199], v[74:77]
	v_mfma_f32_16x16x32_bf16 v[126:129], v[160:163], v[176:179], v[126:129]
	v_mfma_f32_16x16x32_bf16 v[122:125], v[168:171], v[176:179], v[122:125]
	v_mfma_f32_16x16x32_bf16 v[110:113], v[160:163], v[184:187], v[110:113]
	v_mfma_f32_16x16x32_bf16 v[106:109], v[168:171], v[184:187], v[106:109]
	v_mfma_f32_16x16x32_bf16 v[94:97], v[160:163], v[192:195], v[94:97]
	v_mfma_f32_16x16x32_bf16 v[90:93], v[168:171], v[192:195], v[90:93]
	v_mfma_f32_16x16x32_bf16 v[78:81], v[160:163], v[200:203], v[78:81]
	v_mfma_f32_16x16x32_bf16 v[74:77], v[168:171], v[200:203], v[74:77]
	s_barrier
	s_add_i32 s49, s42, s31
	v_lshl_add_u64 v[148:149], s[22:23], 0, v[132:133]
	s_mov_b32 m0, s49
	ds_read_b128 v[204:207], v153
	ds_read_b128 v[208:211], v153 offset:1024
	ds_read_b128 v[212:215], v153 offset:2048
	ds_read_b128 v[216:219], v153 offset:3072
	global_load_lds_dwordx4 v[148:149], off
	v_lshl_add_u64 v[220:221], s[22:23], 0, v[136:137]
	s_add_i32 m0, s49, 0x2000
	s_nop 0
	global_load_lds_dwordx4 v[220:221], off
	s_barrier
	s_waitcnt lgkmcnt(0)
	s_waitcnt lgkmcnt(0)
	v_mfma_f32_16x16x32_bf16 v[118:121], v[204:207], v[172:175], v[118:121]
	v_mfma_f32_16x16x32_bf16 v[114:117], v[212:215], v[172:175], v[114:117]
	v_mfma_f32_16x16x32_bf16 v[102:105], v[204:207], v[180:183], v[102:105]
	v_mfma_f32_16x16x32_bf16 v[98:101], v[212:215], v[180:183], v[98:101]
	v_mfma_f32_16x16x32_bf16 v[86:89], v[204:207], v[188:191], v[86:89]
	v_mfma_f32_16x16x32_bf16 v[82:85], v[212:215], v[188:191], v[82:85]
	v_mfma_f32_16x16x32_bf16 v[70:73], v[204:207], v[196:199], v[70:73]
	v_mfma_f32_16x16x32_bf16 v[66:69], v[212:215], v[196:199], v[66:69]
	v_mfma_f32_16x16x32_bf16 v[118:121], v[208:211], v[176:179], v[118:121]
	v_mfma_f32_16x16x32_bf16 v[114:117], v[216:219], v[176:179], v[114:117]
	v_mfma_f32_16x16x32_bf16 v[102:105], v[208:211], v[184:187], v[102:105]
	v_mfma_f32_16x16x32_bf16 v[98:101], v[216:219], v[184:187], v[98:101]
	v_mfma_f32_16x16x32_bf16 v[86:89], v[208:211], v[192:195], v[86:89]
	v_mfma_f32_16x16x32_bf16 v[82:85], v[216:219], v[192:195], v[82:85]
	v_mfma_f32_16x16x32_bf16 v[70:73], v[208:211], v[200:203], v[70:73]
	v_mfma_f32_16x16x32_bf16 v[66:69], v[216:219], v[200:203], v[66:69]
	s_mov_b32 m0, s33
	v_lshl_add_u64 v[222:223], s[24:25], 0, v[130:131]
	s_barrier
	ds_read_b128 v[172:175], v152 offset:16384
	ds_read_b128 v[176:179], v152 offset:17408
	ds_read_b128 v[180:183], v152 offset:18432
	ds_read_b128 v[184:187], v152 offset:19456
	ds_read_b128 v[188:191], v152 offset:20480
	ds_read_b128 v[192:195], v152 offset:21504
	ds_read_b128 v[196:199], v152 offset:22528
	ds_read_b128 v[200:203], v152 offset:23552
	global_load_lds_dwordx4 v[222:223], off
	v_lshl_add_u64 v[224:225], s[24:25], 0, v[134:135]
	s_mov_b32 m0, s34
	s_nop 0
	global_load_lds_dwordx4 v[224:225], off
	s_barrier
	s_waitcnt lgkmcnt(0)
	s_waitcnt lgkmcnt(0)
	v_mfma_f32_16x16x32_bf16 v[62:65], v[156:159], v[172:175], v[62:65]
	v_mfma_f32_16x16x32_bf16 v[58:61], v[164:167], v[172:175], v[58:61]
	v_mfma_f32_16x16x32_bf16 v[46:49], v[156:159], v[180:183], v[46:49]
	v_mfma_f32_16x16x32_bf16 v[42:45], v[164:167], v[180:183], v[42:45]
	v_mfma_f32_16x16x32_bf16 v[30:33], v[156:159], v[188:191], v[30:33]
	v_mfma_f32_16x16x32_bf16 v[26:29], v[164:167], v[188:191], v[26:29]
	v_mfma_f32_16x16x32_bf16 v[14:17], v[156:159], v[196:199], v[14:17]
	v_mfma_f32_16x16x32_bf16 v[10:13], v[164:167], v[196:199], v[10:13]
	v_mfma_f32_16x16x32_bf16 v[62:65], v[160:163], v[176:179], v[62:65]
	v_mfma_f32_16x16x32_bf16 v[58:61], v[168:171], v[176:179], v[58:61]
	v_mfma_f32_16x16x32_bf16 v[46:49], v[160:163], v[184:187], v[46:49]
	v_mfma_f32_16x16x32_bf16 v[42:45], v[168:171], v[184:187], v[42:45]
	v_mfma_f32_16x16x32_bf16 v[30:33], v[160:163], v[192:195], v[30:33]
	v_mfma_f32_16x16x32_bf16 v[26:29], v[168:171], v[192:195], v[26:29]
	v_mfma_f32_16x16x32_bf16 v[14:17], v[160:163], v[200:203], v[14:17]
	v_mfma_f32_16x16x32_bf16 v[10:13], v[168:171], v[200:203], v[10:13]
	s_barrier
; #define PG8_STAGE(bufoff, gbase, voff) do { _Pragma("unroll") for (int _i = 0; _i < 2; ++_i) \
;     __builtin_amdgcn_global_load_lds((const unsigned*)((const char*)(gbase) + (voff)[_i]), (LAS unsigned*)(lds + (bufoff) + ldsw + _i * 8192), 16, 0, 0); } while (0)
; #define PG8_LDA(dst, b, h) do { _Pragma("unroll") for (int m = 0; m < 4; ++m) _Pragma("unroll") for (int k = 0; k < 2; ++k) dst[m][k] = *(const LAS bf16x8*)(lds + PG8_SA(b, h) + aoff + m * 2048 + k * 1024); } while (0)
; #define PG8_LDB(dst, b, h) do { _Pragma("unroll") for (int n = 0; n < 2; ++n) _Pragma("unroll") for (int k = 0; k < 2; ++k) dst[n][k] = *(const LAS bf16x8*)(lds + PG8_SB(b, h) + boff + n * 2048 + k * 1024); } while (0)
; #define PG8_MMA(ai, bj, At, Bt) do { __builtin_amdgcn_s_setprio(1); _Pragma("unroll") for (int m = 0; m < 4; ++m) _Pragma("unroll") for (int n = 0; n < 2; ++n) _Pragma("unroll") for (int k = 0; k < 2; ++k) \
;     acc[ai][bj][m][n] = __builtin_amdgcn_mfma_f32_16x16x32_bf16(Bt[n][k], At[m][k], acc[ai][bj][m][n], 0, 0, 0); __builtin_amdgcn_s_setprio(0); } while (0)
; #define PG8_WAIT_V(n) asm volatile("s_waitcnt vmcnt(" #n ")" ::: "memory")
; #define PG8_WAIT_L(n) asm volatile("s_waitcnt lgkmcnt(" #n ")" ::: "memory")
; #define PG8_BAR __builtin_amdgcn_s_barrier()
; #define PG8_SCHED __builtin_amdgcn_sched_barrier(0)
; template <class Epi>
; DI void gemm_phase(LAS unsigned char* lds, const Gemm g, const StaticOrder& S, const Epi& E) {
;     ...
;       PG8_STAGE(PG8_SB(0, 1), b2 + hstepB, voffB);
;       PG8_WAIT_V(6); PG8_BAR; PG8_MMA(1, 1, At, B1); PG8_BAR;
;       PG8_LDB(B0, 1, 0); PG8_SCHED; PG8_LDA(At, 1, 0); PG8_STAGE(PG8_SA(0, 1), a2 + hstepA, voffA);
;       PG8_WAIT_L(8); PG8_BAR; PG8_WAIT_L(0); PG8_MMA(0, 0, At, B0); PG8_BAR; PG8_SCHED;
;       PG8_LDB(B1, 1, 1); PG8_STAGE(PG8_SB(1, 0), b3, voffB);
;       PG8_BAR; PG8_WAIT_L(0); PG8_MMA(0, 1, At, B1); PG8_BAR;
;       PG8_LDA(At, 1, 1); PG8_STAGE(PG8_SA(1, 0), a3, voffA);
;       PG8_BAR; PG8_WAIT_L(0); PG8_MMA(1, 0, At, B0); PG8_BAR; PG8_SCHED;
;       PG8_STAGE(PG8_SB(1, 1), b3 + hstepB, voffB);
;       PG8_WAIT_V(6); PG8_BAR; PG8_MMA(1, 1, At, B1); PG8_BAR;
	s_add_u32 s50, s22, 0x200000
	s_addc_u32 s51, s23, 0
	s_add_i32 s49, s43, s31
	v_lshl_add_u64 v[156:157], s[50:51], 0, v[132:133]
	s_mov_b32 m0, s49
	s_nop 0
	global_load_lds_dwordx4 v[156:157], off
	v_lshl_add_u64 v[156:157], s[50:51], 0, v[136:137]
	s_add_i32 m0, s49, 0x2000
	s_nop 0
	global_load_lds_dwordx4 v[156:157], off
	s_waitcnt vmcnt(6)
	s_barrier
	v_mfma_f32_16x16x32_bf16 v[54:57], v[204:207], v[172:175], v[54:57]
	v_mfma_f32_16x16x32_bf16 v[50:53], v[212:215], v[172:175], v[50:53]
	v_mfma_f32_16x16x32_bf16 v[38:41], v[204:207], v[180:183], v[38:41]
	v_mfma_f32_16x16x32_bf16 v[34:37], v[212:215], v[180:183], v[34:37]
	v_mfma_f32_16x16x32_bf16 v[22:25], v[204:207], v[188:191], v[22:25]
	v_mfma_f32_16x16x32_bf16 v[18:21], v[212:215], v[188:191], v[18:21]
	v_mfma_f32_16x16x32_bf16 v[6:9], v[204:207], v[196:199], v[6:9]
	v_mfma_f32_16x16x32_bf16 v[2:5], v[212:215], v[196:199], v[2:5]
	v_mfma_f32_16x16x32_bf16 v[54:57], v[208:211], v[176:179], v[54:57]
	v_mfma_f32_16x16x32_bf16 v[50:53], v[216:219], v[176:179], v[50:53]
	v_mfma_f32_16x16x32_bf16 v[38:41], v[208:211], v[184:187], v[38:41]
	v_mfma_f32_16x16x32_bf16 v[34:37], v[216:219], v[184:187], v[34:37]
	v_mfma_f32_16x16x32_bf16 v[22:25], v[208:211], v[192:195], v[22:25]
	v_mfma_f32_16x16x32_bf16 v[18:21], v[216:219], v[192:195], v[18:21]
	v_mfma_f32_16x16x32_bf16 v[6:9], v[208:211], v[200:203], v[6:9]
	v_mfma_f32_16x16x32_bf16 v[2:5], v[216:219], v[200:203], v[2:5]
	s_add_i32 s49, 0, 0x18000
	v_add_u32_e32 v155, s49, v150
	s_barrier
	ds_read_b128 v[156:159], v155
	ds_read_b128 v[160:163], v155 offset:1024
	ds_read_b128 v[164:167], v155 offset:2048
	ds_read_b128 v[168:171], v155 offset:3072
	s_add_u32 s24, s24, 0x200000
	s_addc_u32 s25, s25, 0
	s_mov_b32 m0, s35
	v_lshl_add_u64 v[204:205], s[24:25], 0, v[130:131]
	ds_read_b128 v[172:175], v152 offset:32768
	ds_read_b128 v[176:179], v152 offset:33792
	ds_read_b128 v[180:183], v152 offset:34816
	ds_read_b128 v[184:187], v152 offset:35840
	ds_read_b128 v[188:191], v152 offset:36864
	ds_read_b128 v[192:195], v152 offset:37888
	ds_read_b128 v[196:199], v152 offset:38912
	ds_read_b128 v[200:203], v152 offset:39936
	global_load_lds_dwordx4 v[204:205], off
	v_lshl_add_u64 v[204:205], s[24:25], 0, v[134:135]
	s_mov_b32 m0, s36
	s_nop 0
	global_load_lds_dwordx4 v[204:205], off
	s_waitcnt lgkmcnt(8)
	s_barrier
	s_waitcnt lgkmcnt(0)
	s_waitcnt lgkmcnt(0)
	v_mfma_f32_16x16x32_bf16 v[126:129], v[156:159], v[172:175], v[126:129]
	v_mfma_f32_16x16x32_bf16 v[122:125], v[164:167], v[172:175], v[122:125]
	v_mfma_f32_16x16x32_bf16 v[110:113], v[156:159], v[180:183], v[110:113]
	v_mfma_f32_16x16x32_bf16 v[106:109], v[164:167], v[180:183], v[106:109]
	v_mfma_f32_16x16x32_bf16 v[94:97], v[156:159], v[188:191], v[94:97]
	v_mfma_f32_16x16x32_bf16 v[90:93], v[164:167], v[188:191], v[90:93]
	v_mfma_f32_16x16x32_bf16 v[78:81], v[156:159], v[196:199], v[78:81]
	v_mfma_f32_16x16x32_bf16 v[74:77], v[164:167], v[196:199], v[74:77]
	v_mfma_f32_16x16x32_bf16 v[126:129], v[160:163], v[176:179], v[126:129]
	v_mfma_f32_16x16x32_bf16 v[122:125], v[168:171], v[176:179], v[122:125]
	v_mfma_f32_16x16x32_bf16 v[110:113], v[160:163], v[184:187], v[110:113]
	v_mfma_f32_16x16x32_bf16 v[106:109], v[168:171], v[184:187], v[106:109]
	v_mfma_f32_16x16x32_bf16 v[94:97], v[160:163], v[192:195], v[94:97]
	v_mfma_f32_16x16x32_bf16 v[90:93], v[168:171], v[192:195], v[90:93]
	v_mfma_f32_16x16x32_bf16 v[78:81], v[160:163], v[200:203], v[78:81]
	v_mfma_f32_16x16x32_bf16 v[74:77], v[168:171], v[200:203], v[74:77]
	s_barrier
	s_add_i32 s24, 0, 0x1c000
	s_add_i32 s25, s49, s31
	v_add_u32_e32 v155, s24, v150
	v_lshl_add_u64 v[148:149], v[148:149], 0, s[6:7]
	s_mov_b32 m0, s25
	ds_read_b128 v[204:207], v155
	ds_read_b128 v[208:211], v155 offset:1024
	ds_read_b128 v[212:215], v155 offset:2048
	ds_read_b128 v[216:219], v155 offset:3072
	global_load_lds_dwordx4 v[148:149], off
	v_lshl_add_u64 v[148:149], v[220:221], 0, s[6:7]
	s_add_i32 m0, s25, 0x2000
	s_nop 0
	global_load_lds_dwordx4 v[148:149], off
	s_barrier
	s_waitcnt lgkmcnt(0)
	s_waitcnt lgkmcnt(0)
	v_mfma_f32_16x16x32_bf16 v[118:121], v[204:207], v[172:175], v[118:121]
	v_mfma_f32_16x16x32_bf16 v[114:117], v[212:215], v[172:175], v[114:117]
	v_mfma_f32_16x16x32_bf16 v[102:105], v[204:207], v[180:183], v[102:105]
	v_mfma_f32_16x16x32_bf16 v[98:101], v[212:215], v[180:183], v[98:101]
	v_mfma_f32_16x16x32_bf16 v[86:89], v[204:207], v[188:191], v[86:89]
	v_mfma_f32_16x16x32_bf16 v[82:85], v[212:215], v[188:191], v[82:85]
	v_mfma_f32_16x16x32_bf16 v[70:73], v[204:207], v[196:199], v[70:73]
	v_mfma_f32_16x16x32_bf16 v[66:69], v[212:215], v[196:199], v[66:69]
	v_mfma_f32_16x16x32_bf16 v[118:121], v[208:211], v[176:179], v[118:121]
	v_mfma_f32_16x16x32_bf16 v[114:117], v[216:219], v[176:179], v[114:117]
	v_mfma_f32_16x16x32_bf16 v[102:105], v[208:211], v[184:187], v[102:105]
	v_mfma_f32_16x16x32_bf16 v[98:101], v[216:219], v[184:187], v[98:101]
	v_mfma_f32_16x16x32_bf16 v[86:89], v[208:211], v[192:195], v[86:89]
	v_mfma_f32_16x16x32_bf16 v[82:85], v[216:219], v[192:195], v[82:85]
	v_mfma_f32_16x16x32_bf16 v[70:73], v[208:211], v[200:203], v[70:73]
	v_mfma_f32_16x16x32_bf16 v[66:69], v[216:219], v[200:203], v[66:69]
	s_mov_b32 m0, s38
	v_lshl_add_u64 v[148:149], v[222:223], 0, s[6:7]
	s_barrier
	ds_read_b128 v[172:175], v152 offset:49152
	ds_read_b128 v[176:179], v152 offset:50176
	ds_read_b128 v[180:183], v152 offset:51200
	ds_read_b128 v[184:187], v152 offset:52224
	ds_read_b128 v[188:191], v152 offset:53248
	ds_read_b128 v[192:195], v152 offset:54272
	ds_read_b128 v[196:199], v152 offset:55296
	ds_read_b128 v[200:203], v152 offset:56320
	global_load_lds_dwordx4 v[148:149], off
	v_lshl_add_u64 v[148:149], v[224:225], 0, s[6:7]
	s_mov_b32 m0, s39
	s_nop 0
	global_load_lds_dwordx4 v[148:149], off
	s_barrier
; template <class Epi>
; DI void gemm_phase(LAS unsigned char* lds, const Gemm g, const StaticOrder& S, const Epi& E) {
;     ...
;       PG8_BAR; PG8_WAIT_L(0); PG8_MMA(1, 0, At, B0); PG8_BAR; PG8_SCHED;
;       PG8_STAGE(PG8_SB(1, 1), b3 + hstepB, voffB);
;       PG8_WAIT_V(6); PG8_BAR; PG8_MMA(1, 1, At, B1); PG8_BAR;
;     }
;     E(acc, cur, wr, wc, fr, fq);
;   DI void operator()(const f32x4 (&acc)[2][2][4][2], const pg8::Unit& u, int wr, int wc, int fr, int fq) const {
;     ...
;         float ssq = 0.f;
; #pragma unroll
;         for (int bj = 0; bj < 2; ++bj) {
;           f32x4 v0 = acc[ai][bj][m][0] * rs, v1 = acc[ai][bj][m][1] * rs;
;           if (MODE == EP_IN || MODE == EP_MIX || MODE == EP_DOWN) {
; #pragma unroll
;             for (int j = 0; j < 4; ++j) ssq += v0[j] * v0[j] + v1[j] * v1[j];
;           }
;           if (MODE == EP_UP) {
; #pragma unroll
;             for (int j = 0; j < 4; ++j) { float a = fmaxf(v0[j], 0.f), b = fmaxf(v1[j], 0.f); v0[j] = a * a; v1[j] = b * b; }
;           }
;           bf16_t* dst;
;           const int ct = bj * 128 + cl;
;           if (MODE == EP_IN) {
;             if (pn < 4) dst = (bf16_t*)(ws + OFF_PROJA) + (size_t)grow * 1024 + pn * 256 + ct;
;             else if (pn < 16) dst = (bf16_t*)(ws + OFF_PROJG) + (size_t)grow * 3072 + (pn - 4) * 256 + ct;
;             else dst = (bf16_t*)(ws + OFF_PROJS) + (size_t)grow * 256 + ct;
;           } else if (MODE == EP_Q) {
;             if (pn < 4) dst = (bf16_t*)(dout + DO_Q) + (size_t)grow * 1536 + (pn * 2 + bj) * 192 + cl;
;             else {
;               const int mm = (pn - 4) * 256 + ct, h = mm >> 6, r = mm & 63;
;               dst = (bf16_t*)(dout + DO_Q) + (size_t)grow * 1536 + h * 192 + 128 + r;
;               const int pos = grow < TP ? (grow & 4095) : grow - TP;
;               const f32x4* tb = (const f32x4*)((const f32x2*)(ws + OFF_ROPE) + pos * 32 + (r >> 1));
;               const f32x4 t0 = tb[0], t1 = tb[1];
;               f32x4 o0, o1;
;               o0[0] = v0[0] * t0[0] - v0[1] * t0[1]; o0[1] = v0[1] * t0[0] + v0[0] * t0[1];
;               o0[2] = v0[2] * t0[2] - v0[3] * t0[3]; o0[3] = v0[3] * t0[2] + v0[2] * t0[3];
;               o1[0] = v1[0] * t1[0] - v1[1] * t1[1]; o1[1] = v1[1] * t1[0] + v1[0] * t1[1];
;               o1[2] = v1[2] * t1[2] - v1[3] * t1[3]; o1[3] = v1[3] * t1[2] + v1[2] * t1[3];
;               v0 = o0; v1 = o1;
	s_waitcnt lgkmcnt(0)
	s_waitcnt lgkmcnt(0)
	v_mfma_f32_16x16x32_bf16 v[62:65], v[156:159], v[172:175], v[62:65]
	v_mfma_f32_16x16x32_bf16 v[58:61], v[164:167], v[172:175], v[58:61]
	v_mfma_f32_16x16x32_bf16 v[46:49], v[156:159], v[180:183], v[46:49]
	v_mfma_f32_16x16x32_bf16 v[42:45], v[164:167], v[180:183], v[42:45]
	v_mfma_f32_16x16x32_bf16 v[30:33], v[156:159], v[188:191], v[30:33]
	v_mfma_f32_16x16x32_bf16 v[26:29], v[164:167], v[188:191], v[26:29]
	v_mfma_f32_16x16x32_bf16 v[14:17], v[156:159], v[196:199], v[14:17]
	v_mfma_f32_16x16x32_bf16 v[10:13], v[164:167], v[196:199], v[10:13]
	v_mfma_f32_16x16x32_bf16 v[62:65], v[160:163], v[176:179], v[62:65]
	v_mfma_f32_16x16x32_bf16 v[58:61], v[168:171], v[176:179], v[58:61]
	v_mfma_f32_16x16x32_bf16 v[46:49], v[160:163], v[184:187], v[46:49]
	v_mfma_f32_16x16x32_bf16 v[42:45], v[168:171], v[184:187], v[42:45]
	v_mfma_f32_16x16x32_bf16 v[30:33], v[160:163], v[192:195], v[30:33]
	v_mfma_f32_16x16x32_bf16 v[26:29], v[168:171], v[192:195], v[26:29]
	v_mfma_f32_16x16x32_bf16 v[14:17], v[160:163], v[200:203], v[14:17]
	v_mfma_f32_16x16x32_bf16 v[10:13], v[168:171], v[200:203], v[10:13]
	s_barrier
	s_add_u32 s22, s22, 0x200080
	s_addc_u32 s23, s23, 0
	s_add_i32 s24, s24, s31
	v_lshl_add_u64 v[148:149], s[22:23], 0, v[132:133]
	s_mov_b32 m0, s24
	s_nop 0
	global_load_lds_dwordx4 v[148:149], off
	v_lshl_add_u64 v[148:149], s[22:23], 0, v[136:137]
	s_add_i32 m0, s24, 0x2000
	s_nop 0
	global_load_lds_dwordx4 v[148:149], off
	s_waitcnt vmcnt(6)
	s_barrier
	v_mfma_f32_16x16x32_bf16 v[54:57], v[204:207], v[172:175], v[54:57]
	v_mfma_f32_16x16x32_bf16 v[50:53], v[212:215], v[172:175], v[50:53]
	v_mfma_f32_16x16x32_bf16 v[38:41], v[204:207], v[180:183], v[38:41]
	v_mfma_f32_16x16x32_bf16 v[34:37], v[212:215], v[180:183], v[34:37]
	v_mfma_f32_16x16x32_bf16 v[22:25], v[204:207], v[188:191], v[22:25]
	v_mfma_f32_16x16x32_bf16 v[18:21], v[212:215], v[188:191], v[18:21]
	v_mfma_f32_16x16x32_bf16 v[6:9], v[204:207], v[196:199], v[6:9]
	v_mfma_f32_16x16x32_bf16 v[2:5], v[212:215], v[196:199], v[2:5]
	v_mfma_f32_16x16x32_bf16 v[54:57], v[208:211], v[176:179], v[54:57]
	v_mfma_f32_16x16x32_bf16 v[50:53], v[216:219], v[176:179], v[50:53]
	v_mfma_f32_16x16x32_bf16 v[38:41], v[208:211], v[184:187], v[38:41]
	v_mfma_f32_16x16x32_bf16 v[34:37], v[216:219], v[184:187], v[34:37]
	v_mfma_f32_16x16x32_bf16 v[22:25], v[208:211], v[192:195], v[22:25]
	v_mfma_f32_16x16x32_bf16 v[18:21], v[216:219], v[192:195], v[18:21]
	v_mfma_f32_16x16x32_bf16 v[6:9], v[208:211], v[200:203], v[6:9]
	v_mfma_f32_16x16x32_bf16 v[2:5], v[216:219], v[200:203], v[2:5]
	s_add_i32 s48, s48, 2
	s_add_u32 s20, s20, 0x100
	s_addc_u32 s21, s21, 0
	s_add_u32 s46, s46, 0x100
	s_addc_u32 s47, s47, 0
	s_cmpk_gt_u32 s48, 0x7d
	s_barrier
	s_cbranch_scc0 .LBB0_1056
	v_mul_f32_e32 v160, v122, v122
	v_mul_f32_e32 v161, v123, v123
	v_fmac_f32_e32 v160, v126, v126
	v_fmac_f32_e32 v161, v127, v127
	v_add_f32_e32 v160, v160, v161
	v_mul_f32_e32 v161, v124, v124
	v_fmac_f32_e32 v161, v128, v128
	v_add_f32_e32 v160, v161, v160
	v_mul_f32_e32 v161, v125, v125
	v_fmac_f32_e32 v161, v129, v129
	v_cvt_pk_bf16_f32 v126, v126, v127
	v_cvt_pk_bf16_f32 v127, v128, v129
	v_mul_f32_e32 v128, v114, v114
	v_add_f32_e32 v160, v161, v160
	v_fmac_f32_e32 v128, v118, v118
	v_mul_f32_e32 v129, v115, v115
	v_add_f32_e32 v128, v160, v128
	v_fmac_f32_e32 v129, v119, v119
	v_and_b32_e32 v149, 64, v154
	v_add_f32_e32 v128, v129, v128
	v_mul_f32_e32 v129, v116, v116
	v_xor_b32_e32 v148, 16, v154
	v_add_u32_e32 v149, 64, v149
	v_fmac_f32_e32 v129, v120, v120
	v_cmp_lt_i32_e32 vcc, v148, v149
	v_add_f32_e32 v128, v129, v128
	v_mul_f32_e32 v129, v117, v117
	v_cndmask_b32_e32 v148, v154, v148, vcc
	v_fmac_f32_e32 v129, v121, v121
	v_lshlrev_b32_e32 v156, 2, v148
	v_add_f32_e32 v160, v129, v128
	ds_bpermute_b32 v161, v156, v160
	v_xor_b32_e32 v148, 32, v154
	v_cmp_lt_i32_e32 vcc, v148, v149
	v_lshl_add_u32 v157, s18, 8, v1
	v_cvt_pk_bf16_f32 v128, v122, v123
	v_cndmask_b32_e32 v148, v154, v148, vcc
	v_lshlrev_b32_e32 v155, 2, v148
	v_add_u32_e32 v148, 0x4000, v157
	v_cvt_pk_bf16_f32 v122, v118, v119
	s_waitcnt lgkmcnt(0)
	v_add_f32_e32 v118, v160, v161
	v_ashrrev_i32_e32 v149, 31, v148
	v_readlane_b32 s48, v238, 32
	ds_bpermute_b32 v119, v155, v118
	s_lshl_b32 s20, s4, 8
	v_lshlrev_b64 v[158:159], 13, v[148:149]
	v_readlane_b32 s54, v238, 38
	v_readlane_b32 s55, v238, 39
	s_ashr_i32 s21, s20, 31
	s_lshl_b32 s18, s4, 2
	v_lshl_add_u64 v[158:159], s[54:55], 0, v[158:159]
	v_lshl_add_u64 v[158:159], s[20:21], 1, v[158:159]
	s_ashr_i32 s19, s18, 31
	v_lshl_add_u64 v[158:159], v[158:159], 0, v[138:139]
	v_cvt_pk_bf16_f32 v129, v124, v125
	v_cvt_pk_bf16_f32 v123, v120, v121
	v_cvt_pk_bf16_f32 v124, v114, v115
	v_cvt_pk_bf16_f32 v125, v116, v117
	v_readlane_b32 s49, v238, 33
	v_readlane_b32 s50, v238, 34
	v_readlane_b32 s51, v238, 35
	v_readlane_b32 s52, v238, 36
	v_readlane_b32 s53, v238, 37
	global_store_dwordx4 v[158:159], v[126:129], off
	global_store_dwordx4 v[158:159], v[122:125], off offset:256
	s_and_saveexec_b64 s[22:23], s[0:1]
	s_cbranch_execz .LBB0_1059
	v_lshlrev_b64 v[114:115], 7, v[148:149]
	v_lshl_add_u64 v[114:115], s[8:9], 0, v[114:115]
	v_lshl_add_u64 v[114:115], s[18:19], 2, v[114:115]
	s_lshl_b32 s4, s37, 2
	s_waitcnt lgkmcnt(0)
	v_add_f32_e32 v116, v118, v119
	v_lshl_add_u64 v[114:115], v[114:115], 0, s[4:5]
	global_store_dword v[114:115], v116, off
